# speedup vs baseline: 1.0408x; 1.0046x over previous
.LBB0_21:
	s_mul_i32 s28, s23, 0x6000
	s_add_i32 s29, s28, 0
	s_waitcnt vmcnt(6)
	v_add_u32_e32 v148, s29, v134
	v_add_u32_e32 v155, s29, v135
	s_waitcnt lgkmcnt(0)
	s_barrier
	ds_read_b128 v[158:161], v155 offset:8192
	ds_read_b128 v[136:139], v148
	ds_read_b128 v[140:143], v148 offset:1024
	ds_read_b128 v[144:147], v148 offset:2048
	ds_read_b128 v[148:151], v148 offset:3072
	ds_read_b128 v[162:165], v155 offset:9216
	ds_read_b128 v[166:169], v155 offset:10240
	ds_read_b128 v[170:173], v155 offset:11264
	s_addk_i32 s28, 0xa000
	s_cmp_gt_i32 s23, 0
	s_setprio 1
	s_waitcnt lgkmcnt(6)
	v_mfma_f32_16x16x32_bf16 v[126:129], v[158:161], v[136:139], v[126:129]
	s_cselect_b32 s28, s28, 0xc000
	v_add_u32_e32 v157, s28, v32
	v_lshl_add_u64 v[152:153], v[132:133], 0, s[8:9]
	s_waitcnt lgkmcnt(5)
	v_mfma_f32_16x16x32_bf16 v[110:113], v[158:161], v[140:143], v[110:113]
	v_lshl_add_u64 v[208:209], v[130:131], 0, s[8:9]
	s_mov_b64 s[28:29], 0xb52c080
	v_lshl_add_u64 v[206:207], v[152:153], 0, s[30:31]
	s_waitcnt lgkmcnt(4)
	v_mfma_f32_16x16x32_bf16 v[82:85], v[158:161], v[144:147], v[82:85]
	v_add_u32_e32 v205, 0x2000, v157
	s_waitcnt lgkmcnt(3)
	v_mfma_f32_16x16x32_bf16 v[50:53], v[158:161], v[148:151], v[50:53]
	v_lshl_add_u64 v[158:159], v[208:209], 0, s[28:29]
	s_waitcnt lgkmcnt(2)
	v_mfma_f32_16x16x32_bf16 v[122:125], v[162:165], v[136:139], v[122:125]
	v_readfirstlane_b32 s28, v157
	s_mov_b32 m0, s28
	s_nop 0
	global_load_lds_dwordx4 v[158:159], off
	ds_read_b128 v[158:161], v155 offset:12288
	ds_read_b128 v[174:177], v155 offset:13312
	ds_read_b128 v[178:181], v155 offset:14336
	ds_read_b128 v[182:185], v155 offset:15360
	v_mfma_f32_16x16x32_bf16 v[102:105], v[162:165], v[140:143], v[102:105]
	v_mfma_f32_16x16x32_bf16 v[70:73], v[162:165], v[144:147], v[70:73]
	v_mfma_f32_16x16x32_bf16 v[38:41], v[162:165], v[148:151], v[38:41]
	s_waitcnt lgkmcnt(5)
	v_mfma_f32_16x16x32_bf16 v[118:121], v[166:169], v[136:139], v[118:121]
	v_mfma_f32_16x16x32_bf16 v[94:97], v[166:169], v[140:143], v[94:97]
	v_add_u32_e32 v155, 0x1000, v157
	s_mov_b64 s[28:29], 0xb584080
	v_lshl_add_u64 v[162:163], v[208:209], 0, s[28:29]
	v_readfirstlane_b32 s28, v155
	s_mov_b32 m0, s28
	s_nop 0
	global_load_lds_dwordx4 v[162:163], off
	v_mfma_f32_16x16x32_bf16 v[62:65], v[166:169], v[144:147], v[62:65]
	v_mfma_f32_16x16x32_bf16 v[28:31], v[166:169], v[148:151], v[28:31]
	s_waitcnt lgkmcnt(4)
	v_mfma_f32_16x16x32_bf16 v[114:117], v[170:173], v[136:139], v[114:117]
	v_mfma_f32_16x16x32_bf16 v[86:89], v[170:173], v[140:143], v[86:89]
	v_mfma_f32_16x16x32_bf16 v[54:57], v[170:173], v[144:147], v[54:57]
	v_readfirstlane_b32 s28, v205
	s_mov_b32 m0, s28
	s_nop 0
	global_load_lds_dwordx4 v[206:207], off
	v_mfma_f32_16x16x32_bf16 v[20:23], v[170:173], v[148:151], v[20:23]
	s_waitcnt lgkmcnt(0)
	v_mfma_f32_16x16x32_bf16 v[106:109], v[158:161], v[136:139], v[106:109]
	v_mfma_f32_16x16x32_bf16 v[74:77], v[158:161], v[140:143], v[74:77]
	v_mfma_f32_16x16x32_bf16 v[42:45], v[158:161], v[144:147], v[42:45]
	v_mfma_f32_16x16x32_bf16 v[12:15], v[158:161], v[148:151], v[12:15]
	v_add_u32_e32 v155, 0x3000, v157
	s_mov_b64 s[28:29], 0x3558080
	v_lshl_add_u64 v[158:159], v[152:153], 0, s[28:29]
	v_readfirstlane_b32 s28, v155
	s_mov_b32 m0, s28
	s_nop 0
	global_load_lds_dwordx4 v[158:159], off
	v_mfma_f32_16x16x32_bf16 v[98:101], v[174:177], v[136:139], v[98:101]
	v_mfma_f32_16x16x32_bf16 v[66:69], v[174:177], v[140:143], v[66:69]
	v_mfma_f32_16x16x32_bf16 v[34:37], v[174:177], v[144:147], v[34:37]
	v_mfma_f32_16x16x32_bf16 v[8:11], v[174:177], v[148:151], v[8:11]
	v_mfma_f32_16x16x32_bf16 v[90:93], v[178:181], v[136:139], v[90:93]
	v_add_u32_e32 v155, 0x4000, v157
	s_mov_b64 s[28:29], 0x35b0080
	v_lshl_add_u64 v[158:159], v[152:153], 0, s[28:29]
	v_readfirstlane_b32 s28, v155
	s_mov_b32 m0, s28
	s_nop 0
	global_load_lds_dwordx4 v[158:159], off
	v_mfma_f32_16x16x32_bf16 v[58:61], v[178:181], v[140:143], v[58:61]
	v_mfma_f32_16x16x32_bf16 v[24:27], v[178:181], v[144:147], v[24:27]
	v_mfma_f32_16x16x32_bf16 v[4:7], v[178:181], v[148:151], v[4:7]
	v_mfma_f32_16x16x32_bf16 v[78:81], v[182:185], v[136:139], v[78:81]
	v_mfma_f32_16x16x32_bf16 v[46:49], v[182:185], v[140:143], v[46:49]
	v_add_u32_e32 v138, 0x5000, v157
	s_mov_b64 s[28:29], 0x3608080
	v_lshl_add_u64 v[136:137], v[152:153], 0, s[28:29]
	v_readfirstlane_b32 s28, v138
	s_mov_b32 m0, s28
	s_nop 0
	global_load_lds_dwordx4 v[136:137], off
	v_mfma_f32_16x16x32_bf16 v[16:19], v[182:185], v[144:147], v[16:19]
	v_mfma_f32_16x16x32_bf16 v[0:3], v[182:185], v[148:151], v[0:3]
	s_setprio 0
	s_add_i32 s28, s23, 1
	s_cmp_lg_u32 s23, 2
	s_cselect_b32 s23, s28, 0
	s_add_u32 s8, s8, 0x80
	s_addc_u32 s9, s9, 0
	s_cmpk_lg_i32 s8, 0x2b00
	s_cbranch_scc1 .LBB0_21
	s_waitcnt vmcnt(6)
	v_add_u32_e32 v32, 0, v134
	v_add_u32_e32 v152, 0, v135
	s_waitcnt lgkmcnt(0)
	s_barrier
	ds_read_b128 v[130:133], v32 offset:49152
	ds_read_b128 v[136:139], v32 offset:50176
	ds_read_b128 v[140:143], v32 offset:51200
	ds_read_b128 v[144:147], v32 offset:52224
	ds_read_b128 v[148:151], v152 offset:57344
	ds_read_b128 v[158:161], v152 offset:58368
	ds_read_b128 v[162:165], v152 offset:59392
	ds_read_b128 v[166:169], v152 offset:60416
	s_setprio 1
	s_waitcnt lgkmcnt(0)
	v_mfma_f32_16x16x32_bf16 v[126:129], v[148:151], v[130:133], v[126:129]
	v_mfma_f32_16x16x32_bf16 v[110:113], v[148:151], v[136:139], v[110:113]
	v_mfma_f32_16x16x32_bf16 v[82:85], v[148:151], v[140:143], v[82:85]
	v_mfma_f32_16x16x32_bf16 v[50:53], v[148:151], v[144:147], v[50:53]
	v_mfma_f32_16x16x32_bf16 v[122:125], v[158:161], v[130:133], v[122:125]
	ds_read_b128 v[148:151], v152 offset:61440
	ds_read_b128 v[170:173], v152 offset:62464
	ds_read_b128 v[174:177], v152 offset:63488
	ds_read_b128 v[178:181], v152 offset:64512
	v_mfma_f32_16x16x32_bf16 v[102:105], v[158:161], v[136:139], v[102:105]
	v_mfma_f32_16x16x32_bf16 v[70:73], v[158:161], v[140:143], v[70:73]
	v_mfma_f32_16x16x32_bf16 v[38:41], v[158:161], v[144:147], v[38:41]
	v_mfma_f32_16x16x32_bf16 v[118:121], v[162:165], v[130:133], v[118:121]
	v_mfma_f32_16x16x32_bf16 v[158:161], v[162:165], v[136:139], v[94:97]
	v_mfma_f32_16x16x32_bf16 v[182:185], v[162:165], v[140:143], v[62:65]
	v_mfma_f32_16x16x32_bf16 v[162:165], v[162:165], v[144:147], v[28:31]
	v_mfma_f32_16x16x32_bf16 v[114:117], v[166:169], v[130:133], v[114:117]
	v_mfma_f32_16x16x32_bf16 v[206:209], v[166:169], v[136:139], v[86:89]
	v_mfma_f32_16x16x32_bf16 v[210:213], v[166:169], v[140:143], v[54:57]
	v_mfma_f32_16x16x32_bf16 v[166:169], v[166:169], v[144:147], v[20:23]
	s_waitcnt lgkmcnt(0)
	v_mfma_f32_16x16x32_bf16 v[106:109], v[148:151], v[130:133], v[106:109]
	v_mfma_f32_16x16x32_bf16 v[74:77], v[148:151], v[136:139], v[74:77]
	v_mfma_f32_16x16x32_bf16 v[42:45], v[148:151], v[140:143], v[42:45]
	v_mfma_f32_16x16x32_bf16 v[12:15], v[148:151], v[144:147], v[12:15]
	v_mfma_f32_16x16x32_bf16 v[98:101], v[170:173], v[130:133], v[98:101]
	v_mfma_f32_16x16x32_bf16 v[66:69], v[170:173], v[136:139], v[66:69]
	v_mfma_f32_16x16x32_bf16 v[34:37], v[170:173], v[140:143], v[34:37]
	v_mfma_f32_16x16x32_bf16 v[8:11], v[170:173], v[144:147], v[8:11]
	v_mfma_f32_16x16x32_bf16 v[148:151], v[174:177], v[130:133], v[90:93]
	v_mfma_f32_16x16x32_bf16 v[170:173], v[174:177], v[136:139], v[58:61]
	v_mfma_f32_16x16x32_bf16 v[214:217], v[174:177], v[140:143], v[24:27]
	v_mfma_f32_16x16x32_bf16 v[4:7], v[174:177], v[144:147], v[4:7]
	v_mfma_f32_16x16x32_bf16 v[130:133], v[178:181], v[130:133], v[78:81]
	v_mfma_f32_16x16x32_bf16 v[134:137], v[178:181], v[136:139], v[46:49]
	v_mfma_f32_16x16x32_bf16 v[138:141], v[178:181], v[140:143], v[16:19]
	v_mfma_f32_16x16x32_bf16 v[0:3], v[178:181], v[144:147], v[0:3]
	s_setprio 0
	s_waitcnt vmcnt(0)
	s_waitcnt lgkmcnt(0)
	s_barrier
	ds_read_b128 v[142:145], v32
	ds_read_b128 v[174:177], v32 offset:1024
	ds_read_b128 v[178:181], v32 offset:2048
	ds_read_b128 v[218:221], v32 offset:3072
	ds_read_b128 v[16:19], v152 offset:8192
	ds_read_b128 v[20:23], v152 offset:9216
	ds_read_b128 v[46:49], v152 offset:10240
	ds_read_b128 v[78:81], v152 offset:11264
	s_setprio 1
	s_waitcnt lgkmcnt(0)
	v_mfma_f32_16x16x32_bf16 v[126:129], v[16:19], v[142:145], v[126:129]
	v_mfma_f32_16x16x32_bf16 v[94:97], v[16:19], v[174:177], v[110:113]
	v_mfma_f32_16x16x32_bf16 v[62:65], v[16:19], v[178:181], v[82:85]
	v_mfma_f32_16x16x32_bf16 v[28:31], v[16:19], v[218:221], v[50:53]
	v_mfma_f32_16x16x32_bf16 v[122:125], v[20:23], v[142:145], v[122:125]
	ds_read_b128 v[110:113], v152 offset:12288
	ds_read_b128 v[222:225], v152 offset:13312
	ds_read_b128 v[226:229], v152 offset:14336
	ds_read_b128 v[230:233], v152 offset:15360
	v_mfma_f32_16x16x32_bf16 v[90:93], v[20:23], v[174:177], v[102:105]
	v_mfma_f32_16x16x32_bf16 v[58:61], v[20:23], v[178:181], v[70:73]
	v_mfma_f32_16x16x32_bf16 v[24:27], v[20:23], v[218:221], v[38:41]
	v_mfma_f32_16x16x32_bf16 v[118:121], v[46:49], v[142:145], v[118:121]
	v_mfma_f32_16x16x32_bf16 v[86:89], v[46:49], v[174:177], v[158:161]
	v_mfma_f32_16x16x32_bf16 v[54:57], v[46:49], v[178:181], v[182:185]
	v_mfma_f32_16x16x32_bf16 v[20:23], v[46:49], v[218:221], v[162:165]
	v_mfma_f32_16x16x32_bf16 v[114:117], v[78:81], v[142:145], v[114:117]
	v_mfma_f32_16x16x32_bf16 v[82:85], v[78:81], v[174:177], v[206:209]
	v_mfma_f32_16x16x32_bf16 v[50:53], v[78:81], v[178:181], v[210:213]
	v_mfma_f32_16x16x32_bf16 v[16:19], v[78:81], v[218:221], v[166:169]
	s_waitcnt lgkmcnt(0)
	v_mfma_f32_16x16x32_bf16 v[158:161], v[110:113], v[142:145], v[106:109]
	v_mfma_f32_16x16x32_bf16 v[78:81], v[110:113], v[174:177], v[74:77]
	v_mfma_f32_16x16x32_bf16 v[46:49], v[110:113], v[178:181], v[42:45]
	v_mfma_f32_16x16x32_bf16 v[12:15], v[110:113], v[218:221], v[12:15]
	v_mfma_f32_16x16x32_bf16 v[162:165], v[222:225], v[142:145], v[98:101]
	v_mfma_f32_16x16x32_bf16 v[74:77], v[222:225], v[174:177], v[66:69]
	v_mfma_f32_16x16x32_bf16 v[42:45], v[222:225], v[178:181], v[34:37]
	v_mfma_f32_16x16x32_bf16 v[8:11], v[222:225], v[218:221], v[8:11]
	v_mfma_f32_16x16x32_bf16 v[102:105], v[226:229], v[142:145], v[148:151]
	v_mfma_f32_16x16x32_bf16 v[70:73], v[226:229], v[174:177], v[170:173]
	v_mfma_f32_16x16x32_bf16 v[38:41], v[226:229], v[178:181], v[214:217]
	v_mfma_f32_16x16x32_bf16 v[4:7], v[226:229], v[218:221], v[4:7]
	v_mfma_f32_16x16x32_bf16 v[98:101], v[230:233], v[142:145], v[130:133]
	v_mfma_f32_16x16x32_bf16 v[66:69], v[230:233], v[174:177], v[134:137]
	v_mfma_f32_16x16x32_bf16 v[34:37], v[230:233], v[178:181], v[138:141]
	v_mfma_f32_16x16x32_bf16 v[0:3], v[230:233], v[218:221], v[0:3]
	s_setprio 0
	v_mov_b32_e32 v32, v186
	s_waitcnt lgkmcnt(0)
	s_barrier
	s_mov_b64 s[28:29], 0x5000
	v_ashrrev_i32_e32 v106, 1, v32
	v_and_b32_e32 v106, 0xffffffc0, v106
	v_lshl_add_u32 v112, s21, 7, v106
	v_and_or_b32 v108, v32, 15, v112
	v_lshlrev_b32_e32 v106, 1, v32
	v_lshrrev_b32_e32 v32, 2, v32
	v_and_b32_e32 v106, 0x80, v106
	v_and_b32_e32 v32, 12, v32
	v_or3_b32 v32, v106, v32, s22
	v_add_u32_e32 v106, 0xffffc000, v112
	v_lshrrev_b32_e32 v106, 4, v106
	s_movk_i32 s22, 0x3fff
	v_or_b32_e32 v106, 1, v106
	v_cmp_lt_i32_e32 vcc, s22, v108
	v_lshlrev_b32_e32 v32, 2, v32
	s_movk_i32 s21, 0x5000
	v_cndmask_b32_e32 v106, 0, v106, vcc
	v_add_u32_e32 v109, s16, v106
	v_mov_b64_e32 v[106:107], s[6:7]
	v_mad_i64_i32 v[110:111], s[8:9], v109, s33, v[106:107]
	v_lshl_add_u64 v[130:131], v[110:111], 0, v[32:33]
	v_ashrrev_i32_e32 v109, 31, v108
	v_lshl_add_u64 v[138:139], v[130:131], 0, s[28:29]
	v_lshlrev_b64 v[110:111], 12, v[108:109]
	v_add_co_u32_e32 v130, vcc, s21, v130
	v_lshl_add_u64 v[110:111], s[92:93], 0, v[110:111]
	s_nop 0
	v_addc_co_u32_e32 v131, vcc, 0, v131, vcc
	v_lshl_add_u64 v[110:111], v[110:111], 0, v[32:33]
	flat_load_dwordx4 v[130:133], v[130:131]
	s_nop 0
	flat_load_dwordx4 v[134:137], v[110:111]
	s_add_i32 s17, s17, s18
	s_waitcnt vmcnt(0) lgkmcnt(0)
	v_pk_fma_f32 v[128:129], v[128:129], v[132:133], v[136:137]
	v_pk_fma_f32 v[126:127], v[126:127], v[130:131], v[134:135]
	flat_store_dwordx4 v[110:111], v[126:129]
	flat_load_dwordx4 v[126:129], v[138:139] offset:64
	s_nop 0
	flat_load_dwordx4 v[130:133], v[110:111] offset:64
	s_waitcnt vmcnt(0) lgkmcnt(0)
	v_pk_fma_f32 v[124:125], v[124:125], v[128:129], v[132:133]
	v_pk_fma_f32 v[122:123], v[122:123], v[126:127], v[130:131]
	flat_store_dwordx4 v[110:111], v[122:125] offset:64
	flat_load_dwordx4 v[122:125], v[138:139] offset:128
	s_nop 0
	flat_load_dwordx4 v[126:129], v[110:111] offset:128
	s_waitcnt vmcnt(0) lgkmcnt(0)
	v_pk_fma_f32 v[120:121], v[120:121], v[124:125], v[128:129]
	v_pk_fma_f32 v[118:119], v[118:119], v[122:123], v[126:127]
	flat_store_dwordx4 v[110:111], v[118:121] offset:128
	flat_load_dwordx4 v[118:121], v[138:139] offset:192
	s_nop 0
	flat_load_dwordx4 v[122:125], v[110:111] offset:192
	s_waitcnt vmcnt(0) lgkmcnt(0)
	v_pk_fma_f32 v[116:117], v[116:117], v[120:121], v[124:125]
	v_pk_fma_f32 v[114:115], v[114:115], v[118:119], v[122:123]
	flat_store_dwordx4 v[110:111], v[114:117] offset:192
	flat_load_dwordx4 v[114:117], v[138:139] offset:256
	s_nop 0
	flat_load_dwordx4 v[118:121], v[110:111] offset:256
	s_waitcnt vmcnt(0) lgkmcnt(0)
	v_pk_fma_f32 v[116:117], v[160:161], v[116:117], v[120:121]
	v_pk_fma_f32 v[114:115], v[158:159], v[114:115], v[118:119]
	flat_store_dwordx4 v[110:111], v[114:117] offset:256
	flat_load_dwordx4 v[114:117], v[138:139] offset:320
	s_nop 0
	flat_load_dwordx4 v[118:121], v[110:111] offset:320
	s_waitcnt vmcnt(0) lgkmcnt(0)
	v_pk_fma_f32 v[116:117], v[164:165], v[116:117], v[120:121]
	v_pk_fma_f32 v[114:115], v[162:163], v[114:115], v[118:119]
	flat_store_dwordx4 v[110:111], v[114:117] offset:320
	flat_load_dwordx4 v[114:117], v[138:139] offset:384
	s_nop 0
	flat_load_dwordx4 v[118:121], v[110:111] offset:384
	s_waitcnt vmcnt(0) lgkmcnt(0)
	v_pk_fma_f32 v[104:105], v[104:105], v[116:117], v[120:121]
	v_pk_fma_f32 v[102:103], v[102:103], v[114:115], v[118:119]
	flat_store_dwordx4 v[110:111], v[102:105] offset:384
	flat_load_dwordx4 v[102:105], v[138:139] offset:448
	s_nop 0
	flat_load_dwordx4 v[114:117], v[110:111] offset:448
	s_waitcnt vmcnt(0) lgkmcnt(0)
	v_pk_fma_f32 v[100:101], v[100:101], v[104:105], v[116:117]
	v_pk_fma_f32 v[98:99], v[98:99], v[102:103], v[114:115]
	flat_store_dwordx4 v[110:111], v[98:101] offset:448
	s_nop 1
	v_add_u32_e32 v98, 0xffffc010, v112
	v_or_b32_e32 v100, 16, v108
	v_lshrrev_b32_e32 v98, 4, v98
	v_add_u32_e32 v98, 1, v98
	v_cmp_lt_i32_e32 vcc, s22, v100
	v_ashrrev_i32_e32 v101, 31, v100
	v_lshlrev_b64 v[100:101], 12, v[100:101]
	v_cndmask_b32_e32 v98, 0, v98, vcc
	v_add_u32_e32 v98, s16, v98
	v_mad_i64_i32 v[98:99], s[8:9], v98, s33, v[106:107]
	v_lshl_add_u64 v[102:103], v[98:99], 0, v[32:33]
	v_lshl_add_u64 v[98:99], v[102:103], 0, s[28:29]
	v_add_co_u32_e32 v102, vcc, s21, v102
	v_lshl_add_u64 v[100:101], s[92:93], 0, v[100:101]
	s_nop 0
	v_addc_co_u32_e32 v103, vcc, 0, v103, vcc
	v_lshl_add_u64 v[100:101], v[100:101], 0, v[32:33]
	flat_load_dwordx4 v[102:105], v[102:103]
	s_nop 0
	flat_load_dwordx4 v[114:117], v[100:101]
	s_waitcnt vmcnt(0) lgkmcnt(0)
	v_pk_fma_f32 v[96:97], v[96:97], v[104:105], v[116:117]
	v_pk_fma_f32 v[94:95], v[94:95], v[102:103], v[114:115]
	flat_store_dwordx4 v[100:101], v[94:97]
	flat_load_dwordx4 v[94:97], v[98:99] offset:64
	s_nop 0
	flat_load_dwordx4 v[102:105], v[100:101] offset:64
	s_waitcnt vmcnt(0) lgkmcnt(0)
	v_pk_fma_f32 v[92:93], v[92:93], v[96:97], v[104:105]
	v_pk_fma_f32 v[90:91], v[90:91], v[94:95], v[102:103]
	flat_store_dwordx4 v[100:101], v[90:93] offset:64
	flat_load_dwordx4 v[90:93], v[98:99] offset:128
	s_nop 0
	flat_load_dwordx4 v[94:97], v[100:101] offset:128
	s_waitcnt vmcnt(0) lgkmcnt(0)
	v_pk_fma_f32 v[88:89], v[88:89], v[92:93], v[96:97]
	v_pk_fma_f32 v[86:87], v[86:87], v[90:91], v[94:95]
	flat_store_dwordx4 v[100:101], v[86:89] offset:128
	flat_load_dwordx4 v[86:89], v[98:99] offset:192
	s_nop 0
	flat_load_dwordx4 v[90:93], v[100:101] offset:192
	s_waitcnt vmcnt(0) lgkmcnt(0)
	v_pk_fma_f32 v[84:85], v[84:85], v[88:89], v[92:93]
	v_pk_fma_f32 v[82:83], v[82:83], v[86:87], v[90:91]
	flat_store_dwordx4 v[100:101], v[82:85] offset:192
	flat_load_dwordx4 v[82:85], v[98:99] offset:256
	s_nop 0
	flat_load_dwordx4 v[86:89], v[100:101] offset:256
	s_waitcnt vmcnt(0) lgkmcnt(0)
	v_pk_fma_f32 v[80:81], v[80:81], v[84:85], v[88:89]
	v_pk_fma_f32 v[78:79], v[78:79], v[82:83], v[86:87]
	flat_store_dwordx4 v[100:101], v[78:81] offset:256
	flat_load_dwordx4 v[78:81], v[98:99] offset:320
	s_nop 0
	flat_load_dwordx4 v[82:85], v[100:101] offset:320
	s_waitcnt vmcnt(0) lgkmcnt(0)
	v_pk_fma_f32 v[76:77], v[76:77], v[80:81], v[84:85]
	v_pk_fma_f32 v[74:75], v[74:75], v[78:79], v[82:83]
	flat_store_dwordx4 v[100:101], v[74:77] offset:320
	flat_load_dwordx4 v[74:77], v[98:99] offset:384
	s_nop 0
	flat_load_dwordx4 v[78:81], v[100:101] offset:384
	s_waitcnt vmcnt(0) lgkmcnt(0)
	v_pk_fma_f32 v[72:73], v[72:73], v[76:77], v[80:81]
	v_pk_fma_f32 v[70:71], v[70:71], v[74:75], v[78:79]
	flat_store_dwordx4 v[100:101], v[70:73] offset:384
	flat_load_dwordx4 v[70:73], v[98:99] offset:448
	s_nop 0
	flat_load_dwordx4 v[74:77], v[100:101] offset:448
	s_waitcnt vmcnt(0) lgkmcnt(0)
	v_pk_fma_f32 v[68:69], v[68:69], v[72:73], v[76:77]
	v_pk_fma_f32 v[66:67], v[66:67], v[70:71], v[74:75]
	flat_store_dwordx4 v[100:101], v[66:69] offset:448
	s_nop 1
	v_add_u32_e32 v66, 0xffffc020, v112
	v_or_b32_e32 v68, 32, v108
	v_lshrrev_b32_e32 v66, 4, v66
	v_or_b32_e32 v66, 1, v66
	v_cmp_lt_i32_e32 vcc, s22, v68
	v_ashrrev_i32_e32 v69, 31, v68
	v_lshlrev_b64 v[68:69], 12, v[68:69]
	v_cndmask_b32_e32 v66, 0, v66, vcc
	v_add_u32_e32 v66, s16, v66
	v_mad_i64_i32 v[66:67], s[8:9], v66, s33, v[106:107]
	v_lshl_add_u64 v[70:71], v[66:67], 0, v[32:33]
	v_lshl_add_u64 v[66:67], v[70:71], 0, s[28:29]
	v_add_co_u32_e32 v70, vcc, s21, v70
	v_lshl_add_u64 v[68:69], s[92:93], 0, v[68:69]
	s_nop 0
	v_addc_co_u32_e32 v71, vcc, 0, v71, vcc
	v_lshl_add_u64 v[68:69], v[68:69], 0, v[32:33]
	flat_load_dwordx4 v[70:73], v[70:71]
	s_nop 0
	flat_load_dwordx4 v[74:77], v[68:69]
	s_waitcnt vmcnt(0) lgkmcnt(0)
	v_pk_fma_f32 v[64:65], v[64:65], v[72:73], v[76:77]
	v_pk_fma_f32 v[62:63], v[62:63], v[70:71], v[74:75]
	flat_store_dwordx4 v[68:69], v[62:65]
	flat_load_dwordx4 v[62:65], v[66:67] offset:64
	s_nop 0
	flat_load_dwordx4 v[70:73], v[68:69] offset:64
	s_waitcnt vmcnt(0) lgkmcnt(0)
	v_pk_fma_f32 v[60:61], v[60:61], v[64:65], v[72:73]
	v_pk_fma_f32 v[58:59], v[58:59], v[62:63], v[70:71]
	flat_store_dwordx4 v[68:69], v[58:61] offset:64
	flat_load_dwordx4 v[58:61], v[66:67] offset:128
	s_nop 0
	flat_load_dwordx4 v[62:65], v[68:69] offset:128
	s_waitcnt vmcnt(0) lgkmcnt(0)
	v_pk_fma_f32 v[56:57], v[56:57], v[60:61], v[64:65]
	v_pk_fma_f32 v[54:55], v[54:55], v[58:59], v[62:63]
	flat_store_dwordx4 v[68:69], v[54:57] offset:128
	flat_load_dwordx4 v[54:57], v[66:67] offset:192
	s_nop 0
	flat_load_dwordx4 v[58:61], v[68:69] offset:192
	s_waitcnt vmcnt(0) lgkmcnt(0)
	v_pk_fma_f32 v[52:53], v[52:53], v[56:57], v[60:61]
	v_pk_fma_f32 v[50:51], v[50:51], v[54:55], v[58:59]
	flat_store_dwordx4 v[68:69], v[50:53] offset:192
	flat_load_dwordx4 v[50:53], v[66:67] offset:256
	s_nop 0
	flat_load_dwordx4 v[54:57], v[68:69] offset:256
	s_waitcnt vmcnt(0) lgkmcnt(0)
	v_pk_fma_f32 v[48:49], v[48:49], v[52:53], v[56:57]
	v_pk_fma_f32 v[46:47], v[46:47], v[50:51], v[54:55]
	flat_store_dwordx4 v[68:69], v[46:49] offset:256
	flat_load_dwordx4 v[46:49], v[66:67] offset:320
	s_nop 0
	flat_load_dwordx4 v[50:53], v[68:69] offset:320
	s_waitcnt vmcnt(0) lgkmcnt(0)
	v_pk_fma_f32 v[44:45], v[44:45], v[48:49], v[52:53]
	v_pk_fma_f32 v[42:43], v[42:43], v[46:47], v[50:51]
	flat_store_dwordx4 v[68:69], v[42:45] offset:320
	flat_load_dwordx4 v[42:45], v[66:67] offset:384
	s_nop 0
	flat_load_dwordx4 v[46:49], v[68:69] offset:384
	s_waitcnt vmcnt(0) lgkmcnt(0)
	v_pk_fma_f32 v[40:41], v[40:41], v[44:45], v[48:49]
	v_pk_fma_f32 v[38:39], v[38:39], v[42:43], v[46:47]
	flat_store_dwordx4 v[68:69], v[38:41] offset:384
	flat_load_dwordx4 v[38:41], v[66:67] offset:448
	s_nop 0
	flat_load_dwordx4 v[42:45], v[68:69] offset:448
	s_waitcnt vmcnt(0) lgkmcnt(0)
	v_pk_fma_f32 v[36:37], v[36:37], v[40:41], v[44:45]
	v_pk_fma_f32 v[34:35], v[34:35], v[38:39], v[42:43]
	flat_store_dwordx4 v[68:69], v[34:37] offset:448
	v_add_u32_e32 v40, 0xffffc030, v112
	s_nop 0
	v_or_b32_e32 v34, 48, v108
	v_ashrrev_i32_e32 v35, 31, v34
	v_lshlrev_b64 v[36:37], 12, v[34:35]
	v_lshrrev_b32_e32 v35, 4, v40
	v_add_u32_e32 v35, 1, v35
	v_cmp_lt_i32_e32 vcc, s22, v34
	v_lshl_add_u64 v[38:39], s[92:93], 0, v[36:37]
	s_nop 0
	v_cndmask_b32_e32 v34, 0, v35, vcc
	v_add_u32_e32 v34, s16, v34
	v_mad_i64_i32 v[34:35], s[8:9], v34, s33, v[106:107]
	v_lshl_add_u64 v[40:41], v[34:35], 0, v[32:33]
	v_lshl_add_u64 v[34:35], v[38:39], 0, v[32:33]
	v_add_co_u32_e32 v38, vcc, s21, v40
	v_lshl_add_u64 v[36:37], v[40:41], 0, s[28:29]
	s_nop 0
	v_addc_co_u32_e32 v39, vcc, 0, v41, vcc
	flat_load_dwordx4 v[38:41], v[38:39]
	s_nop 0
	flat_load_dwordx4 v[42:45], v[34:35]
	v_readlane_b32 s8, v254, 4
	s_add_i32 s20, s20, s8
	s_add_i32 s19, s19, s8
	s_cmpk_gt_i32 s20, 0x1ff
	v_readlane_b32 s9, v254, 5
	s_waitcnt vmcnt(0) lgkmcnt(0)
	v_pk_fma_f32 v[30:31], v[30:31], v[40:41], v[44:45]
	v_pk_fma_f32 v[28:29], v[28:29], v[38:39], v[42:43]
	flat_store_dwordx4 v[34:35], v[28:31]
	flat_load_dwordx4 v[28:31], v[36:37] offset:64
	s_nop 0
	flat_load_dwordx4 v[38:41], v[34:35] offset:64
	s_waitcnt vmcnt(0) lgkmcnt(0)
	v_pk_fma_f32 v[26:27], v[26:27], v[30:31], v[40:41]
	v_pk_fma_f32 v[24:25], v[24:25], v[28:29], v[38:39]
	flat_store_dwordx4 v[34:35], v[24:27] offset:64
	flat_load_dwordx4 v[24:27], v[36:37] offset:128
	s_nop 0
	flat_load_dwordx4 v[28:31], v[34:35] offset:128
	s_waitcnt vmcnt(0) lgkmcnt(0)
	v_pk_fma_f32 v[22:23], v[22:23], v[26:27], v[30:31]
	v_pk_fma_f32 v[20:21], v[20:21], v[24:25], v[28:29]
	flat_store_dwordx4 v[34:35], v[20:23] offset:128
	flat_load_dwordx4 v[20:23], v[36:37] offset:192
	s_nop 0
	flat_load_dwordx4 v[24:27], v[34:35] offset:192
	s_waitcnt vmcnt(0) lgkmcnt(0)
	v_pk_fma_f32 v[18:19], v[18:19], v[22:23], v[26:27]
	v_pk_fma_f32 v[16:17], v[16:17], v[20:21], v[24:25]
	flat_store_dwordx4 v[34:35], v[16:19] offset:192
	flat_load_dwordx4 v[16:19], v[36:37] offset:256
	s_nop 0
	flat_load_dwordx4 v[20:23], v[34:35] offset:256
	s_waitcnt vmcnt(0) lgkmcnt(0)
	v_pk_fma_f32 v[14:15], v[14:15], v[18:19], v[22:23]
	v_pk_fma_f32 v[12:13], v[12:13], v[16:17], v[20:21]
	flat_store_dwordx4 v[34:35], v[12:15] offset:256
	flat_load_dwordx4 v[12:15], v[36:37] offset:320
	s_nop 0
	flat_load_dwordx4 v[16:19], v[34:35] offset:320
	s_waitcnt vmcnt(0) lgkmcnt(0)
	v_pk_fma_f32 v[10:11], v[10:11], v[14:15], v[18:19]
	v_pk_fma_f32 v[8:9], v[8:9], v[12:13], v[16:17]
	flat_store_dwordx4 v[34:35], v[8:11] offset:320
	flat_load_dwordx4 v[8:11], v[36:37] offset:384
	s_nop 0
	flat_load_dwordx4 v[12:15], v[34:35] offset:384
	s_waitcnt vmcnt(0) lgkmcnt(0)
	v_pk_fma_f32 v[6:7], v[6:7], v[10:11], v[14:15]
	v_pk_fma_f32 v[4:5], v[4:5], v[8:9], v[12:13]
	flat_store_dwordx4 v[34:35], v[4:7] offset:384
	flat_load_dwordx4 v[4:7], v[36:37] offset:448
	s_nop 0
	flat_load_dwordx4 v[8:11], v[34:35] offset:448
	s_waitcnt vmcnt(0) lgkmcnt(0)
	v_pk_fma_f32 v[2:3], v[2:3], v[6:7], v[10:11]
	v_pk_fma_f32 v[0:1], v[0:1], v[4:5], v[8:9]
	flat_store_dwordx4 v[34:35], v[0:3] offset:448
	s_cbranch_scc0 .LBB0_20

.LBB0_37:
	s_mul_i32 s18, s9, 0x6000
	s_add_i32 s19, s18, 0
	s_waitcnt vmcnt(6)
	v_add_u32_e32 v148, s19, v134
	v_add_u32_e32 v155, s19, v135
	s_waitcnt lgkmcnt(0)
	s_barrier
	ds_read_b128 v[158:161], v155 offset:8192
	ds_read_b128 v[136:139], v148
	ds_read_b128 v[140:143], v148 offset:1024
	ds_read_b128 v[144:147], v148 offset:2048
	ds_read_b128 v[148:151], v148 offset:3072
	ds_read_b128 v[162:165], v155 offset:9216
	ds_read_b128 v[166:169], v155 offset:10240
	ds_read_b128 v[170:173], v155 offset:11264
	s_addk_i32 s18, 0xa000
	s_cmp_gt_i32 s9, 0
	s_setprio 1
	s_waitcnt lgkmcnt(6)
	v_mfma_f32_16x16x32_bf16 v[126:129], v[158:161], v[136:139], v[126:129]
	s_cselect_b32 s18, s18, 0xc000
	v_add_u32_e32 v157, s18, v32
	v_lshl_add_u64 v[152:153], v[132:133], 0, s[10:11]
	s_waitcnt lgkmcnt(5)
	v_mfma_f32_16x16x32_bf16 v[110:113], v[158:161], v[140:143], v[110:113]
	s_mov_b64 s[18:19], 0x1f00080
	v_lshl_add_u64 v[208:209], v[130:131], 0, s[10:11]
	v_lshl_add_u64 v[206:207], v[152:153], 0, s[18:19]
	s_waitcnt lgkmcnt(4)
	v_mfma_f32_16x16x32_bf16 v[82:85], v[158:161], v[144:147], v[82:85]
	v_add_u32_e32 v205, 0x2000, v157
	s_waitcnt lgkmcnt(3)
	v_mfma_f32_16x16x32_bf16 v[50:53], v[158:161], v[148:151], v[50:53]
	v_lshl_add_u64 v[158:159], v[208:209], 0, s[20:21]
	s_waitcnt lgkmcnt(2)
	v_mfma_f32_16x16x32_bf16 v[122:125], v[162:165], v[136:139], v[122:125]
	v_readfirstlane_b32 s18, v157
	s_mov_b32 m0, s18
	s_nop 0
	global_load_lds_dwordx4 v[158:159], off
	ds_read_b128 v[158:161], v155 offset:12288
	ds_read_b128 v[174:177], v155 offset:13312
	ds_read_b128 v[178:181], v155 offset:14336
	ds_read_b128 v[182:185], v155 offset:15360
	v_mfma_f32_16x16x32_bf16 v[102:105], v[162:165], v[140:143], v[102:105]
	v_mfma_f32_16x16x32_bf16 v[70:73], v[162:165], v[144:147], v[70:73]
	v_mfma_f32_16x16x32_bf16 v[38:41], v[162:165], v[148:151], v[38:41]
	s_waitcnt lgkmcnt(5)
	v_mfma_f32_16x16x32_bf16 v[118:121], v[166:169], v[136:139], v[118:121]
	v_mfma_f32_16x16x32_bf16 v[94:97], v[166:169], v[140:143], v[94:97]
	v_add_u32_e32 v155, 0x1000, v157
	v_lshl_add_u64 v[162:163], v[208:209], 0, s[22:23]
	v_readfirstlane_b32 s18, v155
	s_mov_b32 m0, s18
	s_nop 0
	global_load_lds_dwordx4 v[162:163], off
	v_mfma_f32_16x16x32_bf16 v[62:65], v[166:169], v[144:147], v[62:65]
	v_mfma_f32_16x16x32_bf16 v[28:31], v[166:169], v[148:151], v[28:31]
	s_waitcnt lgkmcnt(4)
	v_mfma_f32_16x16x32_bf16 v[114:117], v[170:173], v[136:139], v[114:117]
	v_mfma_f32_16x16x32_bf16 v[86:89], v[170:173], v[140:143], v[86:89]
	v_mfma_f32_16x16x32_bf16 v[54:57], v[170:173], v[144:147], v[54:57]
	v_readfirstlane_b32 s18, v205
	s_mov_b32 m0, s18
	s_nop 0
	global_load_lds_dwordx4 v[206:207], off
	v_mfma_f32_16x16x32_bf16 v[20:23], v[170:173], v[148:151], v[20:23]
	s_waitcnt lgkmcnt(0)
	v_mfma_f32_16x16x32_bf16 v[106:109], v[158:161], v[136:139], v[106:109]
	v_mfma_f32_16x16x32_bf16 v[74:77], v[158:161], v[140:143], v[74:77]
	v_mfma_f32_16x16x32_bf16 v[42:45], v[158:161], v[144:147], v[42:45]
	v_mfma_f32_16x16x32_bf16 v[12:15], v[158:161], v[148:151], v[12:15]
	v_add_u32_e32 v155, 0x3000, v157
	s_mov_b64 s[18:19], 0x1f20080
	v_lshl_add_u64 v[158:159], v[152:153], 0, s[18:19]
	v_readfirstlane_b32 s18, v155
	s_mov_b32 m0, s18
	s_nop 0
	global_load_lds_dwordx4 v[158:159], off
	v_mfma_f32_16x16x32_bf16 v[98:101], v[174:177], v[136:139], v[98:101]
	v_mfma_f32_16x16x32_bf16 v[66:69], v[174:177], v[140:143], v[66:69]
	v_mfma_f32_16x16x32_bf16 v[34:37], v[174:177], v[144:147], v[34:37]
	v_mfma_f32_16x16x32_bf16 v[8:11], v[174:177], v[148:151], v[8:11]
	v_mfma_f32_16x16x32_bf16 v[90:93], v[178:181], v[136:139], v[90:93]
	v_add_u32_e32 v155, 0x4000, v157
	s_mov_b64 s[18:19], 0x1f40080
	v_lshl_add_u64 v[158:159], v[152:153], 0, s[18:19]
	v_readfirstlane_b32 s18, v155
	s_mov_b32 m0, s18
	s_nop 0
	global_load_lds_dwordx4 v[158:159], off
	v_mfma_f32_16x16x32_bf16 v[58:61], v[178:181], v[140:143], v[58:61]
	v_mfma_f32_16x16x32_bf16 v[24:27], v[178:181], v[144:147], v[24:27]
	v_mfma_f32_16x16x32_bf16 v[4:7], v[178:181], v[148:151], v[4:7]
	v_mfma_f32_16x16x32_bf16 v[78:81], v[182:185], v[136:139], v[78:81]
	v_mfma_f32_16x16x32_bf16 v[46:49], v[182:185], v[140:143], v[46:49]
	v_add_u32_e32 v138, 0x5000, v157
	s_mov_b64 s[18:19], 0x1f60080
	v_lshl_add_u64 v[136:137], v[152:153], 0, s[18:19]
	v_readfirstlane_b32 s18, v138
	s_mov_b32 m0, s18
	s_nop 0
	global_load_lds_dwordx4 v[136:137], off
	v_mfma_f32_16x16x32_bf16 v[16:19], v[182:185], v[144:147], v[16:19]
	v_mfma_f32_16x16x32_bf16 v[0:3], v[182:185], v[148:151], v[0:3]
	s_setprio 0
	s_add_i32 s18, s9, 1
	s_cmp_lg_u32 s9, 2
	s_cselect_b32 s9, s18, 0
	s_add_u32 s10, s10, 0x80
	s_addc_u32 s11, s11, 0
	s_cmpk_lg_i32 s10, 0xf00
	s_cbranch_scc1 .LBB0_37
	s_waitcnt vmcnt(6)
	v_add_u32_e32 v32, 0, v134
	v_add_u32_e32 v152, 0, v135
	s_waitcnt lgkmcnt(0)
	s_barrier
	ds_read_b128 v[130:133], v32
	ds_read_b128 v[136:139], v32 offset:1024
	ds_read_b128 v[140:143], v32 offset:2048
	ds_read_b128 v[144:147], v32 offset:3072
	ds_read_b128 v[148:151], v152 offset:8192
	ds_read_b128 v[158:161], v152 offset:9216
	ds_read_b128 v[162:165], v152 offset:10240
	ds_read_b128 v[166:169], v152 offset:11264
	s_setprio 1
	s_waitcnt lgkmcnt(0)
	v_mfma_f32_16x16x32_bf16 v[126:129], v[148:151], v[130:133], v[126:129]
	v_mfma_f32_16x16x32_bf16 v[110:113], v[148:151], v[136:139], v[110:113]
	v_mfma_f32_16x16x32_bf16 v[82:85], v[148:151], v[140:143], v[82:85]
	v_mfma_f32_16x16x32_bf16 v[50:53], v[148:151], v[144:147], v[50:53]
	v_mfma_f32_16x16x32_bf16 v[122:125], v[158:161], v[130:133], v[122:125]
	ds_read_b128 v[148:151], v152 offset:12288
	ds_read_b128 v[170:173], v152 offset:13312
	ds_read_b128 v[174:177], v152 offset:14336
	ds_read_b128 v[178:181], v152 offset:15360
	v_mfma_f32_16x16x32_bf16 v[102:105], v[158:161], v[136:139], v[102:105]
	v_mfma_f32_16x16x32_bf16 v[70:73], v[158:161], v[140:143], v[70:73]
	v_mfma_f32_16x16x32_bf16 v[38:41], v[158:161], v[144:147], v[38:41]
	v_mfma_f32_16x16x32_bf16 v[118:121], v[162:165], v[130:133], v[118:121]
	v_mfma_f32_16x16x32_bf16 v[94:97], v[162:165], v[136:139], v[94:97]
	v_mfma_f32_16x16x32_bf16 v[62:65], v[162:165], v[140:143], v[62:65]
	v_mfma_f32_16x16x32_bf16 v[28:31], v[162:165], v[144:147], v[28:31]
	v_mfma_f32_16x16x32_bf16 v[158:161], v[166:169], v[130:133], v[114:117]
	v_mfma_f32_16x16x32_bf16 v[86:89], v[166:169], v[136:139], v[86:89]
	v_mfma_f32_16x16x32_bf16 v[54:57], v[166:169], v[140:143], v[54:57]
	v_mfma_f32_16x16x32_bf16 v[20:23], v[166:169], v[144:147], v[20:23]
	s_waitcnt lgkmcnt(0)
	v_mfma_f32_16x16x32_bf16 v[162:165], v[148:151], v[130:133], v[106:109]
	v_mfma_f32_16x16x32_bf16 v[166:169], v[148:151], v[136:139], v[74:77]
	v_mfma_f32_16x16x32_bf16 v[182:185], v[148:151], v[140:143], v[42:45]
	v_mfma_f32_16x16x32_bf16 v[12:15], v[148:151], v[144:147], v[12:15]
	v_mfma_f32_16x16x32_bf16 v[148:151], v[170:173], v[130:133], v[98:101]
	v_mfma_f32_16x16x32_bf16 v[206:209], v[170:173], v[136:139], v[66:69]
	v_mfma_f32_16x16x32_bf16 v[210:213], v[170:173], v[140:143], v[34:37]
	v_mfma_f32_16x16x32_bf16 v[170:173], v[170:173], v[144:147], v[8:11]
	v_mfma_f32_16x16x32_bf16 v[214:217], v[174:177], v[130:133], v[90:93]
	v_mfma_f32_16x16x32_bf16 v[218:221], v[174:177], v[136:139], v[58:61]
	v_mfma_f32_16x16x32_bf16 v[222:225], v[174:177], v[140:143], v[24:27]
	v_mfma_f32_16x16x32_bf16 v[4:7], v[174:177], v[144:147], v[4:7]
	v_mfma_f32_16x16x32_bf16 v[130:133], v[178:181], v[130:133], v[78:81]
	v_mfma_f32_16x16x32_bf16 v[134:137], v[178:181], v[136:139], v[46:49]
	v_mfma_f32_16x16x32_bf16 v[138:141], v[178:181], v[140:143], v[16:19]
	v_mfma_f32_16x16x32_bf16 v[142:145], v[178:181], v[144:147], v[0:3]
	s_setprio 0
	s_waitcnt vmcnt(0)
	s_waitcnt lgkmcnt(0)
	s_barrier
	ds_read_b128 v[174:177], v32 offset:24576
	ds_read_b128 v[178:181], v32 offset:25600
	ds_read_b128 v[226:229], v32 offset:26624
	ds_read_b128 v[230:233], v32 offset:27648
	ds_read_b128 v[0:3], v152 offset:32768
	ds_read_b128 v[8:11], v152 offset:33792
	ds_read_b128 v[16:19], v152 offset:34816
	ds_read_b128 v[24:27], v152 offset:35840
	s_setprio 1
	s_waitcnt lgkmcnt(0)
	v_mfma_f32_16x16x32_bf16 v[126:129], v[0:3], v[174:177], v[126:129]
	v_mfma_f32_16x16x32_bf16 v[106:109], v[0:3], v[178:181], v[110:113]
	v_mfma_f32_16x16x32_bf16 v[90:93], v[0:3], v[226:229], v[82:85]
	v_mfma_f32_16x16x32_bf16 v[74:77], v[0:3], v[230:233], v[50:53]
	v_mfma_f32_16x16x32_bf16 v[114:117], v[8:11], v[174:177], v[122:125]
	ds_read_b128 v[0:3], v152 offset:36864
	ds_read_b128 v[46:49], v152 offset:37888
	s_nop 0
	ds_read_b128 v[122:125], v152 offset:38912
	ds_read_b128 v[234:237], v152 offset:39936
	v_mfma_f32_16x16x32_bf16 v[98:101], v[8:11], v[178:181], v[102:105]
	v_mfma_f32_16x16x32_bf16 v[82:85], v[8:11], v[226:229], v[70:73]
	v_mfma_f32_16x16x32_bf16 v[66:69], v[8:11], v[230:233], v[38:41]
	v_mfma_f32_16x16x32_bf16 v[238:241], v[16:19], v[174:177], v[118:121]
	v_mfma_f32_16x16x32_bf16 v[110:113], v[16:19], v[178:181], v[94:97]
	v_mfma_f32_16x16x32_bf16 v[94:97], v[16:19], v[226:229], v[62:65]
	v_mfma_f32_16x16x32_bf16 v[78:81], v[16:19], v[230:233], v[28:31]
	v_mfma_f32_16x16x32_bf16 v[158:161], v[24:27], v[174:177], v[158:161]
	v_mfma_f32_16x16x32_bf16 v[102:105], v[24:27], v[178:181], v[86:89]
	v_mfma_f32_16x16x32_bf16 v[86:89], v[24:27], v[226:229], v[54:57]
	v_mfma_f32_16x16x32_bf16 v[70:73], v[24:27], v[230:233], v[20:23]
	s_waitcnt lgkmcnt(0)
	v_mfma_f32_16x16x32_bf16 v[58:61], v[0:3], v[174:177], v[162:165]
	v_mfma_f32_16x16x32_bf16 v[42:45], v[0:3], v[178:181], v[166:169]
	v_mfma_f32_16x16x32_bf16 v[24:27], v[0:3], v[226:229], v[182:185]
	v_mfma_f32_16x16x32_bf16 v[8:11], v[0:3], v[230:233], v[12:15]
	v_mfma_f32_16x16x32_bf16 v[50:53], v[46:49], v[174:177], v[148:151]
	v_mfma_f32_16x16x32_bf16 v[34:37], v[46:49], v[178:181], v[206:209]
	v_mfma_f32_16x16x32_bf16 v[16:19], v[46:49], v[226:229], v[210:213]
	v_mfma_f32_16x16x32_bf16 v[0:3], v[46:49], v[230:233], v[170:173]
	v_mfma_f32_16x16x32_bf16 v[62:65], v[122:125], v[174:177], v[214:217]
	v_mfma_f32_16x16x32_bf16 v[46:49], v[122:125], v[178:181], v[218:221]
	v_mfma_f32_16x16x32_bf16 v[28:31], v[122:125], v[226:229], v[222:225]
	v_mfma_f32_16x16x32_bf16 v[12:15], v[122:125], v[230:233], v[4:7]
	v_mfma_f32_16x16x32_bf16 v[54:57], v[234:237], v[174:177], v[130:133]
	v_mfma_f32_16x16x32_bf16 v[38:41], v[234:237], v[178:181], v[134:137]
	v_mfma_f32_16x16x32_bf16 v[20:23], v[234:237], v[226:229], v[138:141]
	v_mfma_f32_16x16x32_bf16 v[4:7], v[234:237], v[230:233], v[142:145]
	s_setprio 0
	v_mul_f32_e32 v120, 0xbfb8aa3b, v126
	v_mul_f32_e32 v121, 0xbfb8aa3b, v127
	v_mul_f32_e32 v122, 0xbfb8aa3b, v128
	v_mul_f32_e32 v123, 0xbfb8aa3b, v129
	v_exp_f32_e32 v120, v120
	v_exp_f32_e32 v121, v121
	v_exp_f32_e32 v122, v122
	v_exp_f32_e32 v123, v123
	v_add_f32_e32 v120, 1.0, v120
	v_add_f32_e32 v121, 1.0, v121
	v_add_f32_e32 v122, 1.0, v122
	v_add_f32_e32 v123, 1.0, v123
	v_rcp_f32_e32 v120, v120
	v_rcp_f32_e32 v121, v121
	v_rcp_f32_e32 v122, v122
	v_rcp_f32_e32 v123, v123
	v_mov_b32_e32 v32, v186
	v_pk_mul_f32 v[120:121], v[126:127], v[120:121]
	s_waitcnt lgkmcnt(0)
	v_pk_mul_f32 v[122:123], v[128:129], v[122:123]
	s_barrier
	s_movk_i32 s9, 0x4400
	v_lshrrev_b32_e32 v118, 6, v32
	v_pk_mul_f32 v[120:121], v[120:121], v[238:239]
	v_pk_mul_f32 v[122:123], v[122:123], v[240:241]
	v_and_b32_e32 v119, 15, v32
	v_mul_lo_u32 v118, v118, s9
	v_cvt_pk_bf16_f32 v120, v120, v121
	v_cvt_pk_bf16_f32 v121, v122, v123
	v_lshrrev_b32_e32 v122, 1, v32
	v_add_u32_e32 v118, 0, v118
	v_mul_u32_u24_e32 v119, 0x110, v119
	v_and_b32_e32 v122, 24, v122
	v_add3_u32 v119, v118, v119, v122
	v_mul_f32_e32 v122, 0xbfb8aa3b, v114
	v_mul_f32_e32 v123, 0xbfb8aa3b, v115
	v_exp_f32_e32 v122, v122
	v_exp_f32_e32 v123, v123
	s_movk_i32 s9, 0x1600
	s_lshl_b32 s8, s8, 7
	v_add_f32_e32 v122, 1.0, v122
	v_add_f32_e32 v123, 1.0, v123
	v_rcp_f32_e32 v122, v122
	v_rcp_f32_e32 v123, v123
	s_nop 0
	v_pk_mul_f32 v[114:115], v[114:115], v[122:123]
	v_mul_f32_e32 v122, 0xbfb8aa3b, v116
	v_mul_f32_e32 v123, 0xbfb8aa3b, v117
	v_exp_f32_e32 v122, v122
	v_exp_f32_e32 v123, v123
	v_pk_mul_f32 v[114:115], v[114:115], v[158:159]
	v_add_f32_e32 v122, 1.0, v122
	v_add_f32_e32 v123, 1.0, v123
	v_rcp_f32_e32 v122, v122
	v_rcp_f32_e32 v123, v123
	v_cvt_pk_bf16_f32 v114, v114, v115
	v_pk_mul_f32 v[116:117], v[116:117], v[122:123]
	s_nop 0
	v_pk_mul_f32 v[116:117], v[116:117], v[160:161]
	s_nop 0
	v_cvt_pk_bf16_f32 v115, v116, v117
	s_waitcnt vmcnt(0)
	ds_write2_b64 v119, v[120:121], v[114:115] offset1:4
	v_mul_f32_e32 v114, 0xbfb8aa3b, v106
	v_mul_f32_e32 v115, 0xbfb8aa3b, v107
	v_exp_f32_e32 v114, v114
	v_exp_f32_e32 v115, v115
	v_add_f32_e32 v114, 1.0, v114
	v_add_f32_e32 v115, 1.0, v115
	v_rcp_f32_e32 v114, v114
	v_rcp_f32_e32 v115, v115
	s_nop 0
	v_pk_mul_f32 v[106:107], v[106:107], v[114:115]
	s_nop 0
	v_pk_mul_f32 v[106:107], v[106:107], v[110:111]
	v_mul_f32_e32 v110, 0xbfb8aa3b, v108
	v_mul_f32_e32 v111, 0xbfb8aa3b, v109
	v_exp_f32_e32 v110, v110
	v_exp_f32_e32 v111, v111
	v_cvt_pk_bf16_f32 v106, v106, v107
	v_add_f32_e32 v110, 1.0, v110
	v_add_f32_e32 v111, 1.0, v111
	v_rcp_f32_e32 v110, v110
	v_rcp_f32_e32 v111, v111
	s_nop 0
	v_pk_mul_f32 v[108:109], v[108:109], v[110:111]
	s_nop 0
	v_pk_mul_f32 v[108:109], v[108:109], v[112:113]
	s_nop 0
	v_cvt_pk_bf16_f32 v107, v108, v109
	v_mul_f32_e32 v108, 0xbfb8aa3b, v98
	v_mul_f32_e32 v109, 0xbfb8aa3b, v99
	v_exp_f32_e32 v108, v108
	v_exp_f32_e32 v109, v109
	v_add_f32_e32 v108, 1.0, v108
	v_add_f32_e32 v109, 1.0, v109
	v_rcp_f32_e32 v108, v108
	v_rcp_f32_e32 v109, v109
	s_nop 0
	v_pk_mul_f32 v[98:99], v[98:99], v[108:109]
	s_nop 0
	v_pk_mul_f32 v[98:99], v[98:99], v[102:103]
	v_mul_f32_e32 v102, 0xbfb8aa3b, v100
	v_mul_f32_e32 v103, 0xbfb8aa3b, v101
	v_exp_f32_e32 v102, v102
	v_exp_f32_e32 v103, v103
	v_add_f32_e32 v102, 1.0, v102
	v_add_f32_e32 v103, 1.0, v103
	v_rcp_f32_e32 v102, v102
	v_rcp_f32_e32 v103, v103
	s_nop 0
	v_pk_mul_f32 v[100:101], v[100:101], v[102:103]
	v_cvt_pk_bf16_f32 v102, v98, v99
	v_mul_f32_e32 v99, 0xbfb8aa3b, v90
	v_exp_f32_e32 v99, v99
	v_pk_mul_f32 v[100:101], v[100:101], v[104:105]
	v_add_u32_e32 v98, 0x1000, v119
	v_cvt_pk_bf16_f32 v103, v100, v101
	v_add_f32_e32 v99, 1.0, v99
	v_rcp_f32_e32 v100, v99
	v_mul_f32_e32 v99, 0xbfb8aa3b, v91
	v_exp_f32_e32 v99, v99
	ds_write2_b64 v98, v[106:107], v[102:103] offset0:32 offset1:36
	v_add_f32_e32 v99, 1.0, v99
	v_rcp_f32_e32 v101, v99
	s_nop 0
	v_pk_mul_f32 v[90:91], v[90:91], v[100:101]
	s_nop 0
	v_pk_mul_f32 v[90:91], v[90:91], v[94:95]
	v_mul_f32_e32 v94, 0xbfb8aa3b, v92
	v_mul_f32_e32 v95, 0xbfb8aa3b, v93
	v_exp_f32_e32 v94, v94
	v_exp_f32_e32 v95, v95
	v_cvt_pk_bf16_f32 v90, v90, v91
	v_add_f32_e32 v94, 1.0, v94
	v_add_f32_e32 v95, 1.0, v95
	v_rcp_f32_e32 v94, v94
	v_rcp_f32_e32 v95, v95
	s_nop 0
	v_pk_mul_f32 v[92:93], v[92:93], v[94:95]
	s_nop 0
	v_pk_mul_f32 v[92:93], v[92:93], v[96:97]
	s_nop 0
	v_cvt_pk_bf16_f32 v91, v92, v93
	v_mul_f32_e32 v92, 0xbfb8aa3b, v82
	v_mul_f32_e32 v93, 0xbfb8aa3b, v83
	v_exp_f32_e32 v92, v92
	v_exp_f32_e32 v93, v93
	v_add_f32_e32 v92, 1.0, v92
	v_add_f32_e32 v93, 1.0, v93
	v_rcp_f32_e32 v92, v92
	v_rcp_f32_e32 v93, v93
	s_nop 0
	v_pk_mul_f32 v[82:83], v[82:83], v[92:93]
	s_nop 0
	v_pk_mul_f32 v[82:83], v[82:83], v[86:87]
	v_mul_f32_e32 v86, 0xbfb8aa3b, v84
	v_mul_f32_e32 v87, 0xbfb8aa3b, v85
	v_exp_f32_e32 v86, v86
	v_exp_f32_e32 v87, v87
	v_add_f32_e32 v86, 1.0, v86
	v_add_f32_e32 v87, 1.0, v87
	v_rcp_f32_e32 v86, v86
	v_rcp_f32_e32 v87, v87
	s_nop 0
	v_pk_mul_f32 v[84:85], v[84:85], v[86:87]
	v_cvt_pk_bf16_f32 v86, v82, v83
	v_mul_f32_e32 v83, 0xbfb8aa3b, v74
	v_exp_f32_e32 v83, v83
	v_pk_mul_f32 v[84:85], v[84:85], v[88:89]
	v_add_u32_e32 v82, 0x2000, v119
	v_cvt_pk_bf16_f32 v87, v84, v85
	v_add_f32_e32 v83, 1.0, v83
	v_rcp_f32_e32 v84, v83
	v_mul_f32_e32 v83, 0xbfb8aa3b, v75
	v_exp_f32_e32 v83, v83
	ds_write2_b64 v82, v[90:91], v[86:87] offset0:64 offset1:68
	v_add_f32_e32 v83, 1.0, v83
	v_rcp_f32_e32 v85, v83
	s_nop 0
	v_pk_mul_f32 v[74:75], v[74:75], v[84:85]
	s_nop 0
	v_pk_mul_f32 v[74:75], v[74:75], v[78:79]
	v_mul_f32_e32 v78, 0xbfb8aa3b, v76
	v_mul_f32_e32 v79, 0xbfb8aa3b, v77
	v_exp_f32_e32 v78, v78
	v_exp_f32_e32 v79, v79
	v_cvt_pk_bf16_f32 v74, v74, v75
	v_add_f32_e32 v78, 1.0, v78
	v_add_f32_e32 v79, 1.0, v79
	v_rcp_f32_e32 v78, v78
	v_rcp_f32_e32 v79, v79
	s_nop 0
	v_pk_mul_f32 v[76:77], v[76:77], v[78:79]
	s_nop 0
	v_pk_mul_f32 v[76:77], v[76:77], v[80:81]
	s_nop 0
	v_cvt_pk_bf16_f32 v75, v76, v77
	v_mul_f32_e32 v76, 0xbfb8aa3b, v66
	v_mul_f32_e32 v77, 0xbfb8aa3b, v67
	v_exp_f32_e32 v76, v76
	v_exp_f32_e32 v77, v77
	v_add_f32_e32 v76, 1.0, v76
	v_add_f32_e32 v77, 1.0, v77
	v_rcp_f32_e32 v76, v76
	v_rcp_f32_e32 v77, v77
	s_nop 0
	v_pk_mul_f32 v[66:67], v[66:67], v[76:77]
	s_nop 0
	v_pk_mul_f32 v[66:67], v[66:67], v[70:71]
	v_mul_f32_e32 v70, 0xbfb8aa3b, v68
	v_mul_f32_e32 v71, 0xbfb8aa3b, v69
	v_exp_f32_e32 v70, v70
	v_exp_f32_e32 v71, v71
	v_add_f32_e32 v70, 1.0, v70
	v_add_f32_e32 v71, 1.0, v71
	v_rcp_f32_e32 v70, v70
	v_rcp_f32_e32 v71, v71
	s_nop 0
	v_pk_mul_f32 v[68:69], v[68:69], v[70:71]
	v_cvt_pk_bf16_f32 v70, v66, v67
	v_mul_f32_e32 v67, 0xbfb8aa3b, v58
	v_exp_f32_e32 v67, v67
	v_pk_mul_f32 v[68:69], v[68:69], v[72:73]
	v_add_u32_e32 v66, 0x3000, v119
	v_cvt_pk_bf16_f32 v71, v68, v69
	v_add_f32_e32 v67, 1.0, v67
	v_rcp_f32_e32 v68, v67
	v_mul_f32_e32 v67, 0xbfb8aa3b, v59
	v_exp_f32_e32 v67, v67
	ds_write2_b64 v66, v[74:75], v[70:71] offset0:96 offset1:100
	v_add_f32_e32 v67, 1.0, v67
	v_rcp_f32_e32 v69, v67
	s_nop 0
	v_pk_mul_f32 v[58:59], v[58:59], v[68:69]
	s_nop 0
	v_pk_mul_f32 v[58:59], v[58:59], v[62:63]
	v_mul_f32_e32 v62, 0xbfb8aa3b, v60
	v_mul_f32_e32 v63, 0xbfb8aa3b, v61
	v_exp_f32_e32 v62, v62
	v_exp_f32_e32 v63, v63
	v_cvt_pk_bf16_f32 v58, v58, v59
	v_add_f32_e32 v62, 1.0, v62
	v_add_f32_e32 v63, 1.0, v63
	v_rcp_f32_e32 v62, v62
	v_rcp_f32_e32 v63, v63
	s_nop 0
	v_pk_mul_f32 v[60:61], v[60:61], v[62:63]
	s_nop 0
	v_pk_mul_f32 v[60:61], v[60:61], v[64:65]
	s_nop 0
	v_cvt_pk_bf16_f32 v59, v60, v61
	v_mul_f32_e32 v60, 0xbfb8aa3b, v50
	v_mul_f32_e32 v61, 0xbfb8aa3b, v51
	v_exp_f32_e32 v60, v60
	v_exp_f32_e32 v61, v61
	v_add_f32_e32 v60, 1.0, v60
	v_add_f32_e32 v61, 1.0, v61
	v_rcp_f32_e32 v60, v60
	v_rcp_f32_e32 v61, v61
	s_nop 0
	v_pk_mul_f32 v[50:51], v[50:51], v[60:61]
	s_nop 0
	v_pk_mul_f32 v[50:51], v[50:51], v[54:55]
	v_mul_f32_e32 v54, 0xbfb8aa3b, v52
	v_mul_f32_e32 v55, 0xbfb8aa3b, v53
	v_exp_f32_e32 v54, v54
	v_exp_f32_e32 v55, v55
	v_cvt_pk_bf16_f32 v50, v50, v51
	v_add_f32_e32 v54, 1.0, v54
	v_add_f32_e32 v55, 1.0, v55
	v_rcp_f32_e32 v54, v54
	v_rcp_f32_e32 v55, v55
	s_nop 0
	v_pk_mul_f32 v[52:53], v[52:53], v[54:55]
	s_nop 0
	v_pk_mul_f32 v[52:53], v[52:53], v[56:57]
	s_nop 0
	v_cvt_pk_bf16_f32 v51, v52, v53
	ds_write2_b64 v119, v[58:59], v[50:51] offset0:8 offset1:12
	v_mul_f32_e32 v50, 0xbfb8aa3b, v42
	v_mul_f32_e32 v51, 0xbfb8aa3b, v43
	v_exp_f32_e32 v50, v50
	v_exp_f32_e32 v51, v51
	v_add_f32_e32 v50, 1.0, v50
	v_add_f32_e32 v51, 1.0, v51
	v_rcp_f32_e32 v50, v50
	v_rcp_f32_e32 v51, v51
	s_nop 0
	v_pk_mul_f32 v[42:43], v[42:43], v[50:51]
	s_nop 0
	v_pk_mul_f32 v[42:43], v[42:43], v[46:47]
	v_mul_f32_e32 v46, 0xbfb8aa3b, v44
	v_mul_f32_e32 v47, 0xbfb8aa3b, v45
	v_exp_f32_e32 v46, v46
	v_exp_f32_e32 v47, v47
	v_cvt_pk_bf16_f32 v42, v42, v43
	v_add_f32_e32 v46, 1.0, v46
	v_add_f32_e32 v47, 1.0, v47
	v_rcp_f32_e32 v46, v46
	v_rcp_f32_e32 v47, v47
	s_nop 0
	v_pk_mul_f32 v[44:45], v[44:45], v[46:47]
	s_nop 0
	v_pk_mul_f32 v[44:45], v[44:45], v[48:49]
	s_nop 0
	v_cvt_pk_bf16_f32 v43, v44, v45
	v_mul_f32_e32 v44, 0xbfb8aa3b, v34
	v_mul_f32_e32 v45, 0xbfb8aa3b, v35
	v_exp_f32_e32 v44, v44
	v_exp_f32_e32 v45, v45
	v_add_f32_e32 v44, 1.0, v44
	v_add_f32_e32 v45, 1.0, v45
	v_rcp_f32_e32 v44, v44
	v_rcp_f32_e32 v45, v45
	s_nop 0
	v_pk_mul_f32 v[34:35], v[34:35], v[44:45]
	s_nop 0
	v_pk_mul_f32 v[34:35], v[34:35], v[38:39]
	v_mul_f32_e32 v38, 0xbfb8aa3b, v36
	v_mul_f32_e32 v39, 0xbfb8aa3b, v37
	v_exp_f32_e32 v38, v38
	v_exp_f32_e32 v39, v39
	v_cvt_pk_bf16_f32 v34, v34, v35
	v_add_f32_e32 v38, 1.0, v38
	v_add_f32_e32 v39, 1.0, v39
	v_rcp_f32_e32 v38, v38
	v_rcp_f32_e32 v39, v39
	s_nop 0
	v_pk_mul_f32 v[36:37], v[36:37], v[38:39]
	s_nop 0
	v_pk_mul_f32 v[36:37], v[36:37], v[40:41]
	s_nop 0
	v_cvt_pk_bf16_f32 v35, v36, v37
	ds_write2_b64 v98, v[42:43], v[34:35] offset0:40 offset1:44
	v_mul_f32_e32 v34, 0xbfb8aa3b, v24
	v_mul_f32_e32 v35, 0xbfb8aa3b, v25
	v_exp_f32_e32 v34, v34
	v_exp_f32_e32 v35, v35
	v_add_f32_e32 v34, 1.0, v34
	v_add_f32_e32 v35, 1.0, v35
	v_rcp_f32_e32 v34, v34
	v_rcp_f32_e32 v35, v35
	s_nop 0
	v_pk_mul_f32 v[24:25], v[24:25], v[34:35]
	s_nop 0
	v_pk_mul_f32 v[24:25], v[24:25], v[28:29]
	v_mul_f32_e32 v28, 0xbfb8aa3b, v26
	v_mul_f32_e32 v29, 0xbfb8aa3b, v27
	v_exp_f32_e32 v28, v28
	v_exp_f32_e32 v29, v29
	v_cvt_pk_bf16_f32 v24, v24, v25
	v_add_f32_e32 v28, 1.0, v28
	v_add_f32_e32 v29, 1.0, v29
	v_rcp_f32_e32 v28, v28
	v_rcp_f32_e32 v29, v29
	s_nop 0
	v_pk_mul_f32 v[26:27], v[26:27], v[28:29]
	s_nop 0
	v_pk_mul_f32 v[26:27], v[26:27], v[30:31]
	s_nop 0
	v_cvt_pk_bf16_f32 v25, v26, v27
	v_mul_f32_e32 v26, 0xbfb8aa3b, v16
	v_mul_f32_e32 v27, 0xbfb8aa3b, v17
	v_exp_f32_e32 v26, v26
	v_exp_f32_e32 v27, v27
	v_add_f32_e32 v26, 1.0, v26
	v_add_f32_e32 v27, 1.0, v27
	v_rcp_f32_e32 v26, v26
	v_rcp_f32_e32 v27, v27
	s_nop 0
	v_pk_mul_f32 v[16:17], v[16:17], v[26:27]
	s_nop 0
	v_pk_mul_f32 v[16:17], v[16:17], v[20:21]
	v_mul_f32_e32 v20, 0xbfb8aa3b, v18
	v_mul_f32_e32 v21, 0xbfb8aa3b, v19
	v_exp_f32_e32 v20, v20
	v_exp_f32_e32 v21, v21
	v_cvt_pk_bf16_f32 v16, v16, v17
	v_add_f32_e32 v20, 1.0, v20
	v_add_f32_e32 v21, 1.0, v21
	v_rcp_f32_e32 v20, v20
	v_rcp_f32_e32 v21, v21
	s_nop 0
	v_pk_mul_f32 v[18:19], v[18:19], v[20:21]
	s_nop 0
	v_pk_mul_f32 v[18:19], v[18:19], v[22:23]
	s_nop 0
	v_cvt_pk_bf16_f32 v17, v18, v19
	ds_write2_b64 v82, v[24:25], v[16:17] offset0:72 offset1:76
	v_mul_f32_e32 v16, 0xbfb8aa3b, v8
	v_mul_f32_e32 v17, 0xbfb8aa3b, v9
	v_exp_f32_e32 v16, v16
	v_exp_f32_e32 v17, v17
	v_add_f32_e32 v16, 1.0, v16
	v_add_f32_e32 v17, 1.0, v17
	v_rcp_f32_e32 v16, v16
	v_rcp_f32_e32 v17, v17
	s_nop 0
	v_pk_mul_f32 v[8:9], v[8:9], v[16:17]
	s_nop 0
	v_pk_mul_f32 v[8:9], v[8:9], v[12:13]
	v_mul_f32_e32 v12, 0xbfb8aa3b, v10
	v_mul_f32_e32 v13, 0xbfb8aa3b, v11
	v_exp_f32_e32 v12, v12
	v_exp_f32_e32 v13, v13
	v_cvt_pk_bf16_f32 v8, v8, v9
	v_add_f32_e32 v12, 1.0, v12
	v_add_f32_e32 v13, 1.0, v13
	v_rcp_f32_e32 v12, v12
	v_rcp_f32_e32 v13, v13
	s_nop 0
	v_pk_mul_f32 v[10:11], v[10:11], v[12:13]
	s_nop 0
	v_pk_mul_f32 v[10:11], v[10:11], v[14:15]
	s_nop 0
	v_cvt_pk_bf16_f32 v9, v10, v11
	v_mul_f32_e32 v10, 0xbfb8aa3b, v0
	v_mul_f32_e32 v11, 0xbfb8aa3b, v1
	v_exp_f32_e32 v10, v10
	v_exp_f32_e32 v11, v11
	v_add_f32_e32 v10, 1.0, v10
	v_add_f32_e32 v11, 1.0, v11
	v_rcp_f32_e32 v10, v10
	v_rcp_f32_e32 v11, v11
	s_nop 0
	v_pk_mul_f32 v[0:1], v[0:1], v[10:11]
	s_nop 0
	v_pk_mul_f32 v[0:1], v[0:1], v[4:5]
	v_mul_f32_e32 v4, 0xbfb8aa3b, v2
	v_mul_f32_e32 v5, 0xbfb8aa3b, v3
	v_exp_f32_e32 v4, v4
	v_exp_f32_e32 v5, v5
	v_cvt_pk_bf16_f32 v0, v0, v1
	v_add_f32_e32 v4, 1.0, v4
	v_add_f32_e32 v5, 1.0, v5
	v_rcp_f32_e32 v4, v4
	v_rcp_f32_e32 v5, v5
	s_nop 0
	v_pk_mul_f32 v[2:3], v[2:3], v[4:5]
	s_nop 0
	v_pk_mul_f32 v[2:3], v[2:3], v[6:7]
	v_bfe_u32 v6, v32, 3, 3
	v_cvt_pk_bf16_f32 v1, v2, v3
	ds_write2_b64 v66, v[8:9], v[0:1] offset0:104 offset1:108
	v_ashrrev_i32_e32 v0, 1, v32
	v_and_b32_e32 v0, 0xffffffc0, v0
	v_lshl_add_u32 v2, s17, 7, v0
	v_mov_b64_e32 v[0:1], s[6:7]
	v_mad_i64_i32 v[0:1], s[10:11], v2, s9, v[0:1]
	v_and_or_b32 v2, v32, 64, s8
	v_ashrrev_i32_e32 v3, 31, v2
	v_lshl_add_u64 v[0:1], v[2:3], 2, v[0:1]
	v_lshlrev_b32_e32 v2, 4, v32
	v_and_b32_e32 v32, 0x70, v2
	v_lshl_add_u64 v[4:5], v[0:1], 0, v[32:33]
	v_and_b32_e32 v2, 64, v2
	v_mov_b32_e32 v3, 0
	v_lshl_add_u64 v[4:5], v[4:5], 0, v[2:3]
	v_mul_u32_u24_e32 v0, 0x110, v6
	s_waitcnt lgkmcnt(0)
	v_add3_u32 v10, v118, v32, v0
	ds_read_b128 v[0:3], v10
	v_lshrrev_b32_e32 v32, 1, v6
	v_mul_u32_u24_e32 v32, 0x2c00, v32
	v_and_b32_e32 v6, 1, v6
	v_lshl_or_b32 v32, v6, 6, v32
	v_lshl_add_u64 v[6:7], v[4:5], 0, v[32:33]
	s_mov_b32 s8, 0xb000
	s_waitcnt lgkmcnt(0)
	flat_store_dwordx4 v[6:7], v[0:3]
	ds_read_b128 v[0:3], v10 offset:2176
	v_add_co_u32_e32 v8, vcc, s8, v6
	s_mov_b32 s8, 0x16000
	s_nop 0
	v_addc_co_u32_e32 v9, vcc, 0, v7, vcc
	s_waitcnt lgkmcnt(0)
	flat_store_dwordx4 v[8:9], v[0:3]
	ds_read_b128 v[0:3], v10 offset:4352
	v_add_co_u32_e32 v8, vcc, s8, v6
	s_mov_b32 s8, 0x21000
	s_nop 0
	v_addc_co_u32_e32 v9, vcc, 0, v7, vcc
	s_waitcnt lgkmcnt(0)
	flat_store_dwordx4 v[8:9], v[0:3]
	ds_read_b128 v[0:3], v10 offset:6528
	v_add_co_u32_e32 v8, vcc, s8, v6
	s_mov_b32 s8, 0x2c000
	s_nop 0
	v_addc_co_u32_e32 v9, vcc, 0, v7, vcc
	s_waitcnt lgkmcnt(0)
	flat_store_dwordx4 v[8:9], v[0:3]
	ds_read_b128 v[0:3], v10 offset:8704
	v_add_co_u32_e32 v6, vcc, s8, v6
	v_readlane_b32 s8, v254, 4
	s_nop 0
	v_addc_co_u32_e32 v7, vcc, 0, v7, vcc
	s_waitcnt lgkmcnt(0)
	flat_store_dwordx4 v[6:7], v[0:3]
	ds_read_b128 v[0:3], v10 offset:10880
	v_add_u32_e32 v6, 0x37000, v32
	v_mov_b32_e32 v7, v33
	v_lshl_add_u64 v[6:7], v[4:5], 0, v[6:7]
	s_add_i32 s16, s16, s8
	s_waitcnt lgkmcnt(0)
	flat_store_dwordx4 v[6:7], v[0:3]
	ds_read_b128 v[0:3], v10 offset:13056
	v_add_u32_e32 v6, 0x42000, v32
	v_mov_b32_e32 v7, v33
	v_lshl_add_u64 v[6:7], v[4:5], 0, v[6:7]
	v_add_u32_e32 v32, 0x4d000, v32
	s_waitcnt lgkmcnt(0)
	flat_store_dwordx4 v[6:7], v[0:3]
	ds_read_b128 v[0:3], v10 offset:15232
	v_lshl_add_u64 v[4:5], v[4:5], 0, v[32:33]
	s_cmpk_gt_i32 s16, 0xb15
	v_readlane_b32 s9, v254, 5
	s_waitcnt lgkmcnt(0)
	flat_store_dwordx4 v[4:5], v[0:3]
	s_cbranch_scc0 .LBB0_32

.LBB0_64:
	s_mul_i32 s6, s1, 0x6000
	s_add_i32 s7, s6, 0
	s_waitcnt vmcnt(6)
	v_add_u32_e32 v148, s7, v134
	v_add_u32_e32 v155, s7, v135
	s_waitcnt lgkmcnt(0)
	s_barrier
	ds_read_b128 v[158:161], v155 offset:8192
	ds_read_b128 v[136:139], v148
	ds_read_b128 v[140:143], v148 offset:1024
	ds_read_b128 v[144:147], v148 offset:2048
	ds_read_b128 v[148:151], v148 offset:3072
	ds_read_b128 v[162:165], v155 offset:9216
	ds_read_b128 v[166:169], v155 offset:10240
	ds_read_b128 v[170:173], v155 offset:11264
	s_addk_i32 s6, 0xa000
	s_cmp_gt_i32 s1, 0
	s_setprio 1
	s_waitcnt lgkmcnt(6)
	v_mfma_f32_16x16x32_bf16 v[126:129], v[158:161], v[136:139], v[126:129]
	s_cselect_b32 s6, s6, 0xc000
	v_add_u32_e32 v157, s6, v32
	v_lshl_add_u64 v[152:153], v[132:133], 0, s[4:5]
	s_waitcnt lgkmcnt(5)
	v_mfma_f32_16x16x32_bf16 v[110:113], v[158:161], v[140:143], v[110:113]
	s_mov_b64 s[6:7], 0x1b00080
	v_lshl_add_u64 v[206:207], v[152:153], 0, s[6:7]
	v_lshl_add_u64 v[208:209], v[130:131], 0, s[4:5]
	s_waitcnt lgkmcnt(4)
	v_mfma_f32_16x16x32_bf16 v[82:85], v[158:161], v[144:147], v[82:85]
	s_mov_b64 s[6:7], 0x60ac080
	v_add_u32_e32 v205, 0x2000, v157
	s_waitcnt lgkmcnt(3)
	v_mfma_f32_16x16x32_bf16 v[50:53], v[158:161], v[148:151], v[50:53]
	v_lshl_add_u64 v[158:159], v[208:209], 0, s[6:7]
	s_waitcnt lgkmcnt(2)
	v_mfma_f32_16x16x32_bf16 v[122:125], v[162:165], v[136:139], v[122:125]
	v_readfirstlane_b32 s6, v157
	s_mov_b32 m0, s6
	s_nop 0
	global_load_lds_dwordx4 v[158:159], off
	ds_read_b128 v[158:161], v155 offset:12288
	ds_read_b128 v[174:177], v155 offset:13312
	ds_read_b128 v[178:181], v155 offset:14336
	ds_read_b128 v[182:185], v155 offset:15360
	v_mfma_f32_16x16x32_bf16 v[102:105], v[162:165], v[140:143], v[102:105]
	v_mfma_f32_16x16x32_bf16 v[70:73], v[162:165], v[144:147], v[70:73]
	v_mfma_f32_16x16x32_bf16 v[38:41], v[162:165], v[148:151], v[38:41]
	s_waitcnt lgkmcnt(5)
	v_mfma_f32_16x16x32_bf16 v[118:121], v[166:169], v[136:139], v[118:121]
	v_mfma_f32_16x16x32_bf16 v[94:97], v[166:169], v[140:143], v[94:97]
	v_add_u32_e32 v155, 0x1000, v157
	s_mov_b64 s[6:7], 0x60cc080
	v_lshl_add_u64 v[162:163], v[208:209], 0, s[6:7]
	v_readfirstlane_b32 s6, v155
	s_mov_b32 m0, s6
	s_nop 0
	global_load_lds_dwordx4 v[162:163], off
	v_mfma_f32_16x16x32_bf16 v[62:65], v[166:169], v[144:147], v[62:65]
	v_mfma_f32_16x16x32_bf16 v[28:31], v[166:169], v[148:151], v[28:31]
	s_waitcnt lgkmcnt(4)
	v_mfma_f32_16x16x32_bf16 v[114:117], v[170:173], v[136:139], v[114:117]
	v_mfma_f32_16x16x32_bf16 v[86:89], v[170:173], v[140:143], v[86:89]
	v_mfma_f32_16x16x32_bf16 v[54:57], v[170:173], v[144:147], v[54:57]
	v_readfirstlane_b32 s6, v205
	s_mov_b32 m0, s6
	s_nop 0
	global_load_lds_dwordx4 v[206:207], off
	v_mfma_f32_16x16x32_bf16 v[20:23], v[170:173], v[148:151], v[20:23]
	s_waitcnt lgkmcnt(0)
	v_mfma_f32_16x16x32_bf16 v[106:109], v[158:161], v[136:139], v[106:109]
	v_mfma_f32_16x16x32_bf16 v[74:77], v[158:161], v[140:143], v[74:77]
	v_mfma_f32_16x16x32_bf16 v[42:45], v[158:161], v[144:147], v[42:45]
	v_mfma_f32_16x16x32_bf16 v[12:15], v[158:161], v[148:151], v[12:15]
	v_add_u32_e32 v155, 0x3000, v157
	s_mov_b64 s[6:7], 0x1b20080
	v_lshl_add_u64 v[158:159], v[152:153], 0, s[6:7]
	v_readfirstlane_b32 s6, v155
	s_mov_b32 m0, s6
	s_nop 0
	global_load_lds_dwordx4 v[158:159], off
	v_mfma_f32_16x16x32_bf16 v[98:101], v[174:177], v[136:139], v[98:101]
	v_mfma_f32_16x16x32_bf16 v[66:69], v[174:177], v[140:143], v[66:69]
	v_mfma_f32_16x16x32_bf16 v[34:37], v[174:177], v[144:147], v[34:37]
	v_mfma_f32_16x16x32_bf16 v[8:11], v[174:177], v[148:151], v[8:11]
	v_mfma_f32_16x16x32_bf16 v[90:93], v[178:181], v[136:139], v[90:93]
	v_add_u32_e32 v155, 0x4000, v157
	s_mov_b64 s[6:7], 0x1b40080
	v_lshl_add_u64 v[158:159], v[152:153], 0, s[6:7]
	v_readfirstlane_b32 s6, v155
	s_mov_b32 m0, s6
	s_nop 0
	global_load_lds_dwordx4 v[158:159], off
	v_mfma_f32_16x16x32_bf16 v[58:61], v[178:181], v[140:143], v[58:61]
	v_mfma_f32_16x16x32_bf16 v[24:27], v[178:181], v[144:147], v[24:27]
	v_mfma_f32_16x16x32_bf16 v[4:7], v[178:181], v[148:151], v[4:7]
	v_mfma_f32_16x16x32_bf16 v[78:81], v[182:185], v[136:139], v[78:81]
	v_mfma_f32_16x16x32_bf16 v[46:49], v[182:185], v[140:143], v[46:49]
	v_add_u32_e32 v138, 0x5000, v157
	s_mov_b64 s[6:7], 0x1b60080
	v_lshl_add_u64 v[136:137], v[152:153], 0, s[6:7]
	v_readfirstlane_b32 s6, v138
	s_mov_b32 m0, s6
	s_nop 0
	global_load_lds_dwordx4 v[136:137], off
	v_mfma_f32_16x16x32_bf16 v[16:19], v[182:185], v[144:147], v[16:19]
	v_mfma_f32_16x16x32_bf16 v[0:3], v[182:185], v[148:151], v[0:3]
	s_setprio 0
	s_add_i32 s6, s1, 1
	s_cmp_lg_u32 s1, 2
	s_cselect_b32 s1, s6, 0
	s_add_u32 s4, s4, 64
	s_addc_u32 s5, s5, 0
	s_cmpk_lg_i32 s4, 0x780
	s_cbranch_scc1 .LBB0_64
	s_waitcnt vmcnt(6)
	v_add_u32_e32 v32, 0, v134
	v_add_u32_e32 v152, 0, v135
	s_waitcnt lgkmcnt(0)
	s_barrier
	ds_read_b128 v[130:133], v32
	ds_read_b128 v[136:139], v32 offset:1024
	ds_read_b128 v[140:143], v32 offset:2048
	ds_read_b128 v[144:147], v32 offset:3072
	ds_read_b128 v[148:151], v152 offset:8192
	ds_read_b128 v[158:161], v152 offset:9216
	ds_read_b128 v[162:165], v152 offset:10240
	ds_read_b128 v[166:169], v152 offset:11264
	s_setprio 1
	s_waitcnt lgkmcnt(0)
	v_mfma_f32_16x16x32_bf16 v[126:129], v[148:151], v[130:133], v[126:129]
	v_mfma_f32_16x16x32_bf16 v[110:113], v[148:151], v[136:139], v[110:113]
	v_mfma_f32_16x16x32_bf16 v[82:85], v[148:151], v[140:143], v[82:85]
	v_mfma_f32_16x16x32_bf16 v[50:53], v[148:151], v[144:147], v[50:53]
	v_mfma_f32_16x16x32_bf16 v[122:125], v[158:161], v[130:133], v[122:125]
	ds_read_b128 v[148:151], v152 offset:12288
	ds_read_b128 v[170:173], v152 offset:13312
	ds_read_b128 v[174:177], v152 offset:14336
	ds_read_b128 v[178:181], v152 offset:15360
	v_mfma_f32_16x16x32_bf16 v[102:105], v[158:161], v[136:139], v[102:105]
	v_mfma_f32_16x16x32_bf16 v[70:73], v[158:161], v[140:143], v[70:73]
	v_mfma_f32_16x16x32_bf16 v[38:41], v[158:161], v[144:147], v[38:41]
	v_mfma_f32_16x16x32_bf16 v[118:121], v[162:165], v[130:133], v[118:121]
	v_mfma_f32_16x16x32_bf16 v[158:161], v[162:165], v[136:139], v[94:97]
	v_mfma_f32_16x16x32_bf16 v[114:117], v[166:169], v[130:133], v[114:117]
	v_mfma_f32_16x16x32_bf16 v[182:185], v[162:165], v[140:143], v[62:65]
	v_mfma_f32_16x16x32_bf16 v[162:165], v[162:165], v[144:147], v[28:31]
	v_mfma_f32_16x16x32_bf16 v[206:209], v[166:169], v[136:139], v[86:89]
	v_mfma_f32_16x16x32_bf16 v[210:213], v[166:169], v[140:143], v[54:57]
	s_waitcnt lgkmcnt(0)
	v_mfma_f32_16x16x32_bf16 v[106:109], v[148:151], v[130:133], v[106:109]
	v_mfma_f32_16x16x32_bf16 v[74:77], v[148:151], v[136:139], v[74:77]
	v_mfma_f32_16x16x32_bf16 v[42:45], v[148:151], v[140:143], v[42:45]
	v_mfma_f32_16x16x32_bf16 v[12:15], v[148:151], v[144:147], v[12:15]
	v_mfma_f32_16x16x32_bf16 v[166:169], v[166:169], v[144:147], v[20:23]
	v_mfma_f32_16x16x32_bf16 v[98:101], v[170:173], v[130:133], v[98:101]
	v_mfma_f32_16x16x32_bf16 v[66:69], v[170:173], v[136:139], v[66:69]
	v_mfma_f32_16x16x32_bf16 v[34:37], v[170:173], v[140:143], v[34:37]
	v_mfma_f32_16x16x32_bf16 v[8:11], v[170:173], v[144:147], v[8:11]
	v_mfma_f32_16x16x32_bf16 v[148:151], v[174:177], v[130:133], v[90:93]
	v_mfma_f32_16x16x32_bf16 v[4:7], v[174:177], v[144:147], v[4:7]
	v_mfma_f32_16x16x32_bf16 v[130:133], v[178:181], v[130:133], v[78:81]
	v_mfma_f32_16x16x32_bf16 v[170:173], v[174:177], v[136:139], v[58:61]
	v_mfma_f32_16x16x32_bf16 v[214:217], v[174:177], v[140:143], v[24:27]
	v_mfma_f32_16x16x32_bf16 v[134:137], v[178:181], v[136:139], v[46:49]
	v_mfma_f32_16x16x32_bf16 v[0:3], v[178:181], v[144:147], v[0:3]
	v_mfma_f32_16x16x32_bf16 v[138:141], v[178:181], v[140:143], v[16:19]
	s_setprio 0
	s_waitcnt vmcnt(0)
	s_waitcnt lgkmcnt(0)
	s_barrier
	ds_read_b128 v[142:145], v32 offset:24576
	ds_read_b128 v[174:177], v32 offset:25600
	ds_read_b128 v[178:181], v32 offset:26624
	ds_read_b128 v[218:221], v32 offset:27648
	ds_read_b128 v[16:19], v152 offset:32768
	ds_read_b128 v[20:23], v152 offset:33792
	ds_read_b128 v[46:49], v152 offset:34816
	ds_read_b128 v[78:81], v152 offset:35840
	s_setprio 1
	s_waitcnt lgkmcnt(0)
	v_mfma_f32_16x16x32_bf16 v[126:129], v[16:19], v[142:145], v[126:129]
	v_mfma_f32_16x16x32_bf16 v[94:97], v[16:19], v[174:177], v[110:113]
	v_mfma_f32_16x16x32_bf16 v[62:65], v[16:19], v[178:181], v[82:85]
	v_mfma_f32_16x16x32_bf16 v[28:31], v[16:19], v[218:221], v[50:53]
	v_mfma_f32_16x16x32_bf16 v[122:125], v[20:23], v[142:145], v[122:125]
	ds_read_b128 v[222:225], v152 offset:36864
	ds_read_b128 v[226:229], v152 offset:37888
	ds_read_b128 v[230:233], v152 offset:38912
	ds_read_b128 v[234:237], v152 offset:39936
	v_mfma_f32_16x16x32_bf16 v[90:93], v[20:23], v[174:177], v[102:105]
	v_mfma_f32_16x16x32_bf16 v[58:61], v[20:23], v[178:181], v[70:73]
	v_mfma_f32_16x16x32_bf16 v[24:27], v[20:23], v[218:221], v[38:41]
	v_mfma_f32_16x16x32_bf16 v[118:121], v[46:49], v[142:145], v[118:121]
	v_mfma_f32_16x16x32_bf16 v[86:89], v[46:49], v[174:177], v[158:161]
	v_mfma_f32_16x16x32_bf16 v[54:57], v[46:49], v[178:181], v[182:185]
	v_mfma_f32_16x16x32_bf16 v[20:23], v[46:49], v[218:221], v[162:165]
	v_mfma_f32_16x16x32_bf16 v[114:117], v[78:81], v[142:145], v[114:117]
	v_mfma_f32_16x16x32_bf16 v[82:85], v[78:81], v[174:177], v[206:209]
	v_mfma_f32_16x16x32_bf16 v[50:53], v[78:81], v[178:181], v[210:213]
	v_mfma_f32_16x16x32_bf16 v[16:19], v[78:81], v[218:221], v[166:169]
	s_waitcnt lgkmcnt(0)
	v_mfma_f32_16x16x32_bf16 v[110:113], v[222:225], v[142:145], v[106:109]
	v_mfma_f32_16x16x32_bf16 v[78:81], v[222:225], v[174:177], v[74:77]
	v_mfma_f32_16x16x32_bf16 v[46:49], v[222:225], v[178:181], v[42:45]
	v_mfma_f32_16x16x32_bf16 v[12:15], v[222:225], v[218:221], v[12:15]
	v_mfma_f32_16x16x32_bf16 v[106:109], v[226:229], v[142:145], v[98:101]
	v_mfma_f32_16x16x32_bf16 v[74:77], v[226:229], v[174:177], v[66:69]
	v_mfma_f32_16x16x32_bf16 v[42:45], v[226:229], v[178:181], v[34:37]
	v_mfma_f32_16x16x32_bf16 v[8:11], v[226:229], v[218:221], v[8:11]
	v_mfma_f32_16x16x32_bf16 v[102:105], v[230:233], v[142:145], v[148:151]
	v_mfma_f32_16x16x32_bf16 v[70:73], v[230:233], v[174:177], v[170:173]
	v_mfma_f32_16x16x32_bf16 v[38:41], v[230:233], v[178:181], v[214:217]
	v_mfma_f32_16x16x32_bf16 v[4:7], v[230:233], v[218:221], v[4:7]
	v_mfma_f32_16x16x32_bf16 v[98:101], v[234:237], v[142:145], v[130:133]
	v_mfma_f32_16x16x32_bf16 v[66:69], v[234:237], v[174:177], v[134:137]
	v_mfma_f32_16x16x32_bf16 v[34:37], v[234:237], v[178:181], v[138:141]
	v_mfma_f32_16x16x32_bf16 v[0:3], v[234:237], v[218:221], v[0:3]
	s_setprio 0
	v_mov_b32_e32 v32, v186
	s_waitcnt lgkmcnt(0)
	s_barrier
	s_movk_i32 s4, 0x3fff
	v_ashrrev_i32_e32 v130, 1, v32
	v_and_b32_e32 v130, 0xffffffc0, v130
	v_lshl_add_u32 v130, s0, 7, v130
	v_and_or_b32 v130, v32, 15, v130
	s_movk_i32 s0, 0x4000
	v_cmp_gt_i32_e64 s[0:1], s0, v130
	v_cmp_lt_i32_e64 s[4:5], s4, v130
	s_mov_b64 s[6:7], -1
	s_and_b64 vcc, exec, s[10:11]
	s_cbranch_vccz .LBB0_67
	v_ashrrev_i32_e32 v131, 31, v130
	s_mov_b64 s[6:7], 0

; #define RAW_BARRIER() do { asm volatile("s_waitcnt lgkmcnt(0)" ::: "memory"); __builtin_amdgcn_s_barrier(); } while (0)
; #define GLDS_TILE(kt, st) do { _Pragma("unroll") for (int _i = 0; _i < NP; ++_i) GLDS_PIECE(_i, kt, st); } while (0)
;     ...
;     constexpr int NH = NI >= 4 ? NI / 2 : NI;
;     constexpr int NP = 2 + NB, IVL = (4 * NI) / NP;
;     RAW_BARRIER();
;     GLDS_TILE(0, 0);
;     GLDS_TILE(1, 1);
;     int st = 0;
;     for (int kt = 0; kt < nk - 1; ++kt) {
;         if (NI == 8) asm volatile("s_waitcnt vmcnt(6)" ::: "memory"); else if (NI == 4) asm volatile("s_waitcnt vmcnt(4)" ::: "memory"); else asm volatile("s_waitcnt vmcnt(3)" ::: "memory");
;         RAW_BARRIER();
;         const int s2 = st >= 1 ? st - 1 : 2;
;         const bool ld = kt + 2 < nk;
;         STEP_TILE(st, ld, kt + 2, s2);
;         st = st == 2 ? 0 : st + 1;
;     }
.LBB0_146:
	s_mul_i32 s6, s1, 0x6000
	s_add_i32 s7, s6, 0
	s_waitcnt vmcnt(6)
	v_add_u32_e32 v148, s7, v134
	v_add_u32_e32 v155, s7, v135
	s_waitcnt lgkmcnt(0)
	s_barrier
	ds_read_b128 v[158:161], v155 offset:8192
	ds_read_b128 v[136:139], v148
	ds_read_b128 v[140:143], v148 offset:1024
	ds_read_b128 v[144:147], v148 offset:2048
	ds_read_b128 v[148:151], v148 offset:3072
	ds_read_b128 v[162:165], v155 offset:9216
	ds_read_b128 v[166:169], v155 offset:10240
	ds_read_b128 v[170:173], v155 offset:11264
	s_addk_i32 s6, 0xa000
	s_cmp_gt_i32 s1, 0
	s_setprio 1
	s_waitcnt lgkmcnt(6)
	v_mfma_f32_16x16x32_bf16 v[126:129], v[158:161], v[136:139], v[126:129]
	s_cselect_b32 s6, s6, 0xc000
	v_add_u32_e32 v216, s6, v32
	v_lshl_add_u64 v[152:153], v[132:133], 0, s[4:5]
	s_waitcnt lgkmcnt(5)
	v_mfma_f32_16x16x32_bf16 v[110:113], v[158:161], v[140:143], v[110:113]
	v_lshl_add_u64 v[214:215], v[130:131], 0, s[4:5]
	v_lshl_add_u64 v[182:183], v[152:153], 0, s[10:11]
	v_add_u32_e32 v217, 0x2000, v216
	s_waitcnt lgkmcnt(4)
	v_mfma_f32_16x16x32_bf16 v[82:85], v[158:161], v[144:147], v[82:85]
	s_waitcnt lgkmcnt(3)
	v_mfma_f32_16x16x32_bf16 v[50:53], v[158:161], v[148:151], v[50:53]
	v_lshl_add_u64 v[158:159], v[214:215], 0, s[12:13]
	s_waitcnt lgkmcnt(2)
	v_mfma_f32_16x16x32_bf16 v[122:125], v[162:165], v[136:139], v[122:125]
	v_readfirstlane_b32 s6, v216
	s_mov_b32 m0, s6
	s_nop 0
	global_load_lds_dwordx4 v[158:159], off
	ds_read_b128 v[158:161], v155 offset:12288
	ds_read_b128 v[174:177], v155 offset:13312
	ds_read_b128 v[178:181], v155 offset:14336
	ds_read_b128 v[210:213], v155 offset:15360
	v_mfma_f32_16x16x32_bf16 v[102:105], v[162:165], v[140:143], v[102:105]
	v_mfma_f32_16x16x32_bf16 v[70:73], v[162:165], v[144:147], v[70:73]
	v_mfma_f32_16x16x32_bf16 v[38:41], v[162:165], v[148:151], v[38:41]
	s_waitcnt lgkmcnt(5)
	v_mfma_f32_16x16x32_bf16 v[118:121], v[166:169], v[136:139], v[118:121]
	v_mfma_f32_16x16x32_bf16 v[94:97], v[166:169], v[140:143], v[94:97]
	v_add_u32_e32 v155, 0x1000, v216
	v_lshl_add_u64 v[162:163], v[214:215], 0, s[14:15]
	v_readfirstlane_b32 s6, v155
	s_mov_b32 m0, s6
	s_nop 0
	global_load_lds_dwordx4 v[162:163], off
	v_mfma_f32_16x16x32_bf16 v[62:65], v[166:169], v[144:147], v[62:65]
	v_mfma_f32_16x16x32_bf16 v[28:31], v[166:169], v[148:151], v[28:31]
	s_waitcnt lgkmcnt(4)
	v_mfma_f32_16x16x32_bf16 v[114:117], v[170:173], v[136:139], v[114:117]
	v_mfma_f32_16x16x32_bf16 v[86:89], v[170:173], v[140:143], v[86:89]
	v_mfma_f32_16x16x32_bf16 v[54:57], v[170:173], v[144:147], v[54:57]
	v_readfirstlane_b32 s6, v217
	s_mov_b32 m0, s6
	s_nop 0
	global_load_lds_dwordx4 v[182:183], off
	v_mfma_f32_16x16x32_bf16 v[20:23], v[170:173], v[148:151], v[20:23]
	s_waitcnt lgkmcnt(0)
	v_mfma_f32_16x16x32_bf16 v[106:109], v[158:161], v[136:139], v[106:109]
	v_mfma_f32_16x16x32_bf16 v[74:77], v[158:161], v[140:143], v[74:77]
	v_mfma_f32_16x16x32_bf16 v[42:45], v[158:161], v[144:147], v[42:45]
	v_mfma_f32_16x16x32_bf16 v[12:15], v[158:161], v[148:151], v[12:15]
	v_add_u32_e32 v155, 0x3000, v216
	v_lshl_add_u64 v[158:159], v[152:153], 0, s[16:17]
	v_readfirstlane_b32 s6, v155
	s_mov_b32 m0, s6
	s_nop 0
	global_load_lds_dwordx4 v[158:159], off
	v_mfma_f32_16x16x32_bf16 v[98:101], v[174:177], v[136:139], v[98:101]
	v_mfma_f32_16x16x32_bf16 v[66:69], v[174:177], v[140:143], v[66:69]
	v_mfma_f32_16x16x32_bf16 v[34:37], v[174:177], v[144:147], v[34:37]
	v_mfma_f32_16x16x32_bf16 v[8:11], v[174:177], v[148:151], v[8:11]
	v_mfma_f32_16x16x32_bf16 v[90:93], v[178:181], v[136:139], v[90:93]
	v_add_u32_e32 v155, 0x4000, v216
	v_lshl_add_u64 v[158:159], v[152:153], 0, s[76:77]
	v_readfirstlane_b32 s6, v155
	s_mov_b32 m0, s6
	s_nop 0
	global_load_lds_dwordx4 v[158:159], off
	v_mfma_f32_16x16x32_bf16 v[58:61], v[178:181], v[140:143], v[58:61]
	v_mfma_f32_16x16x32_bf16 v[24:27], v[178:181], v[144:147], v[24:27]
	v_mfma_f32_16x16x32_bf16 v[4:7], v[178:181], v[148:151], v[4:7]
	v_mfma_f32_16x16x32_bf16 v[78:81], v[210:213], v[136:139], v[78:81]
	v_mfma_f32_16x16x32_bf16 v[46:49], v[210:213], v[140:143], v[46:49]
	v_add_u32_e32 v138, 0x5000, v216
	v_lshl_add_u64 v[136:137], v[152:153], 0, s[84:85]
	v_readfirstlane_b32 s6, v138
	s_mov_b32 m0, s6
	s_nop 0
	global_load_lds_dwordx4 v[136:137], off
	v_mfma_f32_16x16x32_bf16 v[16:19], v[210:213], v[144:147], v[16:19]
	v_mfma_f32_16x16x32_bf16 v[0:3], v[210:213], v[148:151], v[0:3]
	s_setprio 0
	s_add_i32 s6, s1, 1
	s_cmp_lg_u32 s1, 2
	s_cselect_b32 s1, s6, 0
	s_add_u32 s4, s4, 0x80
	s_addc_u32 s5, s5, 0
	s_cmpk_lg_i32 s4, 0xf00
	s_cbranch_scc1 .LBB0_146
	s_waitcnt vmcnt(6)
	v_add_u32_e32 v32, 0, v134
	v_add_u32_e32 v152, 0, v135
	s_waitcnt lgkmcnt(0)
	s_barrier
; #define RAW_BARRIER() do { asm volatile("s_waitcnt lgkmcnt(0)" ::: "memory"); __builtin_amdgcn_s_barrier(); } while (0)
;     ...
;     for (int kt = 0; kt < nk - 1; ++kt) {
;         if (NI == 8) asm volatile("s_waitcnt vmcnt(6)" ::: "memory"); else if (NI == 4) asm volatile("s_waitcnt vmcnt(4)" ::: "memory"); else asm volatile("s_waitcnt vmcnt(3)" ::: "memory");
;         RAW_BARRIER();
;         const int s2 = st >= 1 ? st - 1 : 2;
;         const bool ld = kt + 2 < nk;
;         STEP_TILE(st, ld, kt + 2, s2);
;         st = st == 2 ? 0 : st + 1;
;     }
;     asm volatile("s_waitcnt vmcnt(0)" ::: "memory");
;     RAW_BARRIER();
;     STEP_TILE(st, false, 0, 0);
;     RAW_BARRIER();
	ds_read_b128 v[130:133], v32
	ds_read_b128 v[136:139], v32 offset:1024
	ds_read_b128 v[140:143], v32 offset:2048
	ds_read_b128 v[144:147], v32 offset:3072
	ds_read_b128 v[148:151], v152 offset:8192
	ds_read_b128 v[158:161], v152 offset:9216
	ds_read_b128 v[162:165], v152 offset:10240
	ds_read_b128 v[166:169], v152 offset:11264
	s_sext_i32_i16 s0, s0
	s_setprio 1
	s_waitcnt lgkmcnt(0)
	v_mfma_f32_16x16x32_bf16 v[126:129], v[148:151], v[130:133], v[126:129]
	v_mfma_f32_16x16x32_bf16 v[110:113], v[148:151], v[136:139], v[110:113]
	v_mfma_f32_16x16x32_bf16 v[82:85], v[148:151], v[140:143], v[82:85]
	v_mfma_f32_16x16x32_bf16 v[50:53], v[148:151], v[144:147], v[50:53]
	v_mfma_f32_16x16x32_bf16 v[122:125], v[158:161], v[130:133], v[122:125]
	ds_read_b128 v[148:151], v152 offset:12288
	ds_read_b128 v[170:173], v152 offset:13312
	ds_read_b128 v[174:177], v152 offset:14336
	ds_read_b128 v[178:181], v152 offset:15360
	v_mfma_f32_16x16x32_bf16 v[102:105], v[158:161], v[136:139], v[102:105]
	v_mfma_f32_16x16x32_bf16 v[70:73], v[158:161], v[140:143], v[70:73]
	v_mfma_f32_16x16x32_bf16 v[38:41], v[158:161], v[144:147], v[38:41]
	v_mfma_f32_16x16x32_bf16 v[94:97], v[162:165], v[136:139], v[94:97]
	v_mfma_f32_16x16x32_bf16 v[158:161], v[162:165], v[130:133], v[118:121]
	v_mfma_f32_16x16x32_bf16 v[62:65], v[162:165], v[140:143], v[62:65]
	v_mfma_f32_16x16x32_bf16 v[28:31], v[162:165], v[144:147], v[28:31]
	v_mfma_f32_16x16x32_bf16 v[210:213], v[166:169], v[136:139], v[86:89]
	v_mfma_f32_16x16x32_bf16 v[54:57], v[166:169], v[140:143], v[54:57]
	v_mfma_f32_16x16x32_bf16 v[162:165], v[166:169], v[130:133], v[114:117]
	v_mfma_f32_16x16x32_bf16 v[20:23], v[166:169], v[144:147], v[20:23]
	s_waitcnt lgkmcnt(0)
	v_mfma_f32_16x16x32_bf16 v[42:45], v[148:151], v[140:143], v[42:45]
	v_mfma_f32_16x16x32_bf16 v[12:15], v[148:151], v[144:147], v[12:15]
	v_mfma_f32_16x16x32_bf16 v[166:169], v[148:151], v[130:133], v[106:109]
	v_mfma_f32_16x16x32_bf16 v[214:217], v[148:151], v[136:139], v[74:77]
	v_mfma_f32_16x16x32_bf16 v[148:151], v[170:173], v[130:133], v[98:101]
	v_mfma_f32_16x16x32_bf16 v[8:11], v[170:173], v[144:147], v[8:11]
	v_mfma_f32_16x16x32_bf16 v[218:221], v[170:173], v[136:139], v[66:69]
	v_mfma_f32_16x16x32_bf16 v[222:225], v[170:173], v[140:143], v[34:37]
	v_mfma_f32_16x16x32_bf16 v[170:173], v[174:177], v[130:133], v[90:93]
	v_mfma_f32_16x16x32_bf16 v[24:27], v[174:177], v[140:143], v[24:27]
	v_mfma_f32_16x16x32_bf16 v[46:49], v[178:181], v[136:139], v[46:49]
	v_mfma_f32_16x16x32_bf16 v[226:229], v[174:177], v[136:139], v[58:61]
	v_mfma_f32_16x16x32_bf16 v[174:177], v[174:177], v[144:147], v[4:7]
	v_mfma_f32_16x16x32_bf16 v[130:133], v[178:181], v[130:133], v[78:81]
	v_mfma_f32_16x16x32_bf16 v[134:137], v[178:181], v[140:143], v[16:19]
	v_mfma_f32_16x16x32_bf16 v[138:141], v[178:181], v[144:147], v[0:3]
	s_setprio 0
	s_waitcnt vmcnt(0)
	s_waitcnt lgkmcnt(0)
	s_barrier
	ds_read_b128 v[142:145], v32 offset:24576
	ds_read_b128 v[178:181], v32 offset:25600
	ds_read_b128 v[230:233], v32 offset:26624
	ds_read_b128 v[234:237], v32 offset:27648
	ds_read_b128 v[0:3], v152 offset:32768
	ds_read_b128 v[4:7], v152 offset:33792
	ds_read_b128 v[16:19], v152 offset:34816
	ds_read_b128 v[34:37], v152 offset:35840
	s_setprio 1
	s_waitcnt lgkmcnt(0)
	v_mfma_f32_16x16x32_bf16 v[118:121], v[0:3], v[142:145], v[126:129]
	v_mfma_f32_16x16x32_bf16 v[98:101], v[0:3], v[178:181], v[110:113]
	v_mfma_f32_16x16x32_bf16 v[82:85], v[0:3], v[230:233], v[82:85]
	v_mfma_f32_16x16x32_bf16 v[66:69], v[0:3], v[234:237], v[50:53]
	v_mfma_f32_16x16x32_bf16 v[114:117], v[4:7], v[142:145], v[122:125]
	ds_read_b128 v[0:3], v152 offset:36864
	ds_read_b128 v[238:241], v152 offset:37888
	ds_read_b128 v[242:245], v152 offset:38912
	ds_read_b128 v[246:249], v152 offset:39936
	v_mfma_f32_16x16x32_bf16 v[106:109], v[4:7], v[178:181], v[102:105]
	v_mfma_f32_16x16x32_bf16 v[86:89], v[4:7], v[230:233], v[70:73]
	v_mfma_f32_16x16x32_bf16 v[70:73], v[4:7], v[234:237], v[38:41]
	v_mfma_f32_16x16x32_bf16 v[122:125], v[16:19], v[142:145], v[158:161]
	v_mfma_f32_16x16x32_bf16 v[102:105], v[16:19], v[178:181], v[94:97]
	v_mfma_f32_16x16x32_bf16 v[90:93], v[16:19], v[230:233], v[62:65]
	v_mfma_f32_16x16x32_bf16 v[74:77], v[16:19], v[234:237], v[28:31]
	v_mfma_f32_16x16x32_bf16 v[126:129], v[34:37], v[142:145], v[162:165]
	v_mfma_f32_16x16x32_bf16 v[110:113], v[34:37], v[178:181], v[210:213]
	v_mfma_f32_16x16x32_bf16 v[94:97], v[34:37], v[230:233], v[54:57]
	v_mfma_f32_16x16x32_bf16 v[78:81], v[34:37], v[234:237], v[20:23]
	s_waitcnt lgkmcnt(0)
	v_mfma_f32_16x16x32_bf16 v[50:53], v[0:3], v[142:145], v[166:169]
	v_mfma_f32_16x16x32_bf16 v[34:37], v[0:3], v[178:181], v[214:217]
	v_mfma_f32_16x16x32_bf16 v[16:19], v[0:3], v[230:233], v[42:45]
	v_mfma_f32_16x16x32_bf16 v[0:3], v[0:3], v[234:237], v[12:15]
	v_mfma_f32_16x16x32_bf16 v[58:61], v[238:241], v[142:145], v[148:151]
	v_mfma_f32_16x16x32_bf16 v[38:41], v[238:241], v[178:181], v[218:221]
	v_mfma_f32_16x16x32_bf16 v[20:23], v[238:241], v[230:233], v[222:225]
	v_mfma_f32_16x16x32_bf16 v[4:7], v[238:241], v[234:237], v[8:11]
	v_mfma_f32_16x16x32_bf16 v[54:57], v[242:245], v[142:145], v[170:173]
	v_mfma_f32_16x16x32_bf16 v[42:45], v[242:245], v[178:181], v[226:229]
	v_mfma_f32_16x16x32_bf16 v[24:27], v[242:245], v[230:233], v[24:27]
	v_mfma_f32_16x16x32_bf16 v[8:11], v[242:245], v[234:237], v[174:177]
	v_mfma_f32_16x16x32_bf16 v[62:65], v[246:249], v[142:145], v[130:133]
	v_mfma_f32_16x16x32_bf16 v[46:49], v[246:249], v[178:181], v[46:49]
	v_mfma_f32_16x16x32_bf16 v[28:31], v[246:249], v[230:233], v[134:137]
	v_mfma_f32_16x16x32_bf16 v[12:15], v[246:249], v[234:237], v[138:141]
	s_setprio 0
	v_mov_b32_e32 v32, v186
	s_waitcnt lgkmcnt(0)
	s_barrier
;     __device__ __forceinline__ bf16_t* W1t() const { return (bf16_t*)(ws + OFF_W1t); }
;     __device__ __forceinline__ bf16_t* H() const { return (bf16_t*)(ws + OFF_H); }
; DEV int tid_opaque() { int t = threadIdx.x; asm volatile("" : "+v"(t)); return t; }
; DEV void wst_put4(char* wsm, int row, int col, float a, float b, float c, float d) { uint2 w; w.x = pk_bf16(a, b); w.y = pk_bf16(c, d); *(uint2*)(wsm + row * WST_ROW + col * 2) = w; }
; template <int H>
; DEV void epi1_group(const Params& p, int l, bool samp, int rbase, int g64, int fq, int fr, char* wsm, const f32x4 (&acc)[4][8]) {
;     ...
;     } else if (g64 < 90) {
;         const int c0 = (g64 - 42) * 64 + cl;
;         const float* bg = p.b_gate + l * 3072 + c0;
; #pragma unroll
;         for (int ni = 0; ni < 4; ++ni) {
;             const f32x4 b4 = *(const f32x4*)(bg + ni * 16);
; #pragma unroll
;             for (int mi = 0; mi < 4; ++mi) {
;                 f32x4 v = acc[mi][H * 4 + ni] + b4;
; #pragma unroll
;                 for (int j = 0; j < 4; ++j) v[j] = __builtin_amdgcn_rcpf(1.f + __expf(-v[j]));
;                 wst_put4(wsm, mi * 16 + fr, sc + ni * 16, v[0], v[1], v[2], v[3]);
;             }
; DEV void gemm1_big(const Params& p, int l, int mt, int nt, char* smem) {
;     f32x4 acc[4][8]; zero_accn<8>(acc);
;     gemm_glds<8>(p.H() + (size_t)mt * 128 * 1024, 1024, p.W1t() + (size_t)l * N1P * 1024 + (size_t)nt * 256 * 1024, 1024, 1024, acc, smem);
;     const int t = tid_opaque(), lane = t & 63, wid = t >> 6, wm = wid >> 1, wn = wid & 1, fr = lane & 15, fq = lane >> 4;
;     const int rbase = mt * 128 + wm * 64 + fr, g0 = nt * 4 + wn * 2;
;     char* wsm = smem + wid * WST_BYTES;
;     epi1_group<0>(p, l, mt == MT - 1, rbase, g0, fq, fr, wsm, acc);
;     epi1_group<1>(p, l, mt == MT - 1, rbase, g0 + 1, fq, fr, wsm, acc);
	v_readlane_b32 s4, v252, 27
	v_ashrrev_i32_e32 v130, 6, v32
	v_and_b32_e32 v210, 15, v32
	v_bfe_u32 v155, v32, 4, 2
	v_ashrrev_i32_e32 v32, 1, v32
	v_and_b32_e32 v32, 0xffffffc0, v32
	v_lshl_add_u32 v150, s0, 7, v32
	s_lshl_b32 s0, s4, 2
	v_lshlrev_b32_e32 v32, 1, v130
	v_and_or_b32 v212, v32, 2, s0
	s_movk_i32 s0, 0x4400
	v_mul_lo_u32 v32, v130, s0
	s_add_i32 s0, s8, 0xfa00
	s_and_b32 s0, s0, 0xffff
	s_cmp_gt_u32 s0, 11
	v_readlane_b32 s5, v252, 28
	s_cselect_b64 s[6:7], -1, 0
	s_cmp_gt_u32 s4, 2
	s_cselect_b64 s[4:5], -1, 0
	v_or_b32_e32 v152, v150, v210
	v_add_u32_e32 v211, 0, v32
	v_lshlrev_b32_e32 v151, 2, v155
	s_mov_b64 s[0:1], -1
	s_and_b64 vcc, exec, s[4:5]
	s_cbranch_vccz .LBB0_797
	v_readlane_b32 s0, v252, 27
	v_readlane_b32 s1, v252, 28
	s_cmp_gt_u32 s0, 5
	s_mov_b64 s[0:1], -1
	s_cbranch_scc0 .LBB0_357
	v_cmp_lt_u32_e32 vcc, 29, v212
	s_and_saveexec_b64 s[0:1], vcc
	s_xor_b64 s[8:9], exec, s[0:1]
	s_cbranch_execz .LBB0_291
	v_cmp_lt_u32_e32 vcc, 33, v212
	s_and_saveexec_b64 s[0:1], vcc
	s_xor_b64 s[10:11], exec, s[0:1]
	s_cbranch_execz .LBB0_288
	v_cmp_lt_u32_e32 vcc, 37, v212
	s_and_saveexec_b64 s[0:1], vcc
	s_xor_b64 s[0:1], exec, s[0:1]
	s_cbranch_execz .LBB0_222
	v_cmp_lt_u32_e32 vcc, 41, v212
	s_and_saveexec_b64 s[12:13], vcc
	s_xor_b64 s[12:13], exec, s[12:13]
	s_cbranch_execz .LBB0_156
	s_movk_i32 s14, 0x5a
	v_cmp_gt_u32_e32 vcc, s14, v212
	s_and_saveexec_b64 s[14:15], vcc
	s_cbranch_execz .LBB0_155
	v_lshl_or_b32 v32, v212, 6, v151
	v_readlane_b32 s16, v250, 10
	v_add_u32_e32 v32, 0xfffff580, v32
	v_readlane_b32 s17, v250, 11
	s_nop 1
	v_lshl_add_u64 v[134:135], v[32:33], 2, s[16:17]
	flat_load_dwordx4 v[130:133], v[134:135]
	v_lshlrev_b32_e32 v32, 3, v155
	s_waitcnt vmcnt(0) lgkmcnt(0)
	v_pk_add_f32 v[136:137], v[120:121], v[132:133]
	s_nop 0
	v_mul_f32_e32 v136, 0xbfb8aa3b, v136
	v_exp_f32_e32 v136, v136
	v_pk_add_f32 v[138:139], v[118:119], v[130:131]
	v_add_f32_e32 v136, 1.0, v136
	v_mul_f32_e32 v138, 0xbfb8aa3b, v138
	v_mul_f32_e32 v139, 0xbfb8aa3b, v139
	v_exp_f32_e32 v138, v138
	v_exp_f32_e32 v139, v139
	v_rcp_f32_e32 v140, v136
	v_mul_f32_e32 v136, 0xbfb8aa3b, v137
	v_exp_f32_e32 v136, v136
	v_add_f32_e32 v138, 1.0, v138
	v_add_f32_e32 v139, 1.0, v139
	v_rcp_f32_e32 v138, v138
	v_rcp_f32_e32 v139, v139
	v_add_f32_e32 v136, 1.0, v136
	v_rcp_f32_e32 v137, v136
	v_cvt_pk_bf16_f32 v136, v138, v139
	v_mul_u32_u24_e32 v138, 0x110, v210
	v_cvt_pk_bf16_f32 v137, v140, v137
	v_add3_u32 v32, v211, v32, v138
	ds_write_b64 v32, v[136:137]
	v_pk_add_f32 v[136:137], v[100:101], v[132:133]
	v_pk_add_f32 v[138:139], v[98:99], v[130:131]
	v_mul_f32_e32 v136, 0xbfb8aa3b, v136
	v_exp_f32_e32 v136, v136
	v_mul_f32_e32 v138, 0xbfb8aa3b, v138
	v_mul_f32_e32 v139, 0xbfb8aa3b, v139
	v_exp_f32_e32 v138, v138
	v_add_f32_e32 v136, 1.0, v136
	v_rcp_f32_e32 v140, v136
	v_mul_f32_e32 v136, 0xbfb8aa3b, v137
	v_exp_f32_e32 v139, v139
	v_exp_f32_e32 v136, v136
	v_add_f32_e32 v138, 1.0, v138
	v_rcp_f32_e32 v138, v138
	v_add_f32_e32 v139, 1.0, v139
	v_add_f32_e32 v136, 1.0, v136
	v_rcp_f32_e32 v139, v139
	v_rcp_f32_e32 v137, v136
	v_cvt_pk_bf16_f32 v136, v138, v139
	v_cvt_pk_bf16_f32 v137, v140, v137
	ds_write_b64 v32, v[136:137] offset:4352
	v_pk_add_f32 v[136:137], v[84:85], v[132:133]
	v_pk_add_f32 v[138:139], v[82:83], v[130:131]
	v_mul_f32_e32 v136, 0xbfb8aa3b, v136
	v_exp_f32_e32 v136, v136
	v_pk_add_f32 v[132:133], v[68:69], v[132:133]
	v_pk_add_f32 v[130:131], v[66:67], v[130:131]
	v_mul_f32_e32 v138, 0xbfb8aa3b, v138
	v_add_f32_e32 v136, 1.0, v136
	v_mul_f32_e32 v139, 0xbfb8aa3b, v139
	v_rcp_f32_e32 v140, v136
	v_mul_f32_e32 v136, 0xbfb8aa3b, v137
	v_mul_f32_e32 v130, 0xbfb8aa3b, v130
	v_mul_f32_e32 v131, 0xbfb8aa3b, v131
	v_mul_f32_e32 v132, 0xbfb8aa3b, v132
	v_mul_f32_e32 v133, 0xbfb8aa3b, v133
	v_exp_f32_e32 v138, v138
	v_exp_f32_e32 v139, v139
	v_exp_f32_e32 v136, v136
	v_exp_f32_e32 v130, v130
	v_exp_f32_e32 v131, v131
	v_exp_f32_e32 v132, v132
	v_exp_f32_e32 v133, v133
	v_add_f32_e32 v138, 1.0, v138
	v_add_f32_e32 v139, 1.0, v139
	v_add_f32_e32 v136, 1.0, v136
	v_add_f32_e32 v130, 1.0, v130
	v_add_f32_e32 v131, 1.0, v131
	v_add_f32_e32 v132, 1.0, v132
	v_add_f32_e32 v133, 1.0, v133
	v_rcp_f32_e32 v138, v138
	v_rcp_f32_e32 v139, v139
	v_rcp_f32_e32 v137, v136
	v_rcp_f32_e32 v130, v130
	v_rcp_f32_e32 v131, v131
	v_rcp_f32_e32 v132, v132
	v_rcp_f32_e32 v133, v133
	v_cvt_pk_bf16_f32 v136, v138, v139
	v_cvt_pk_bf16_f32 v137, v140, v137
	v_cvt_pk_bf16_f32 v130, v130, v131
	v_cvt_pk_bf16_f32 v131, v132, v133
	ds_write_b64 v32, v[136:137] offset:8704
	ds_write_b64 v32, v[130:131] offset:13056
	flat_load_dwordx4 v[130:133], v[134:135] offset:64
	s_waitcnt vmcnt(0) lgkmcnt(0)
;     __device__ __forceinline__ bf16_t* H() const { return (bf16_t*)(ws + OFF_H); }
; DEV void wst_put4(char* wsm, int row, int col, float a, float b, float c, float d) { uint2 w; w.x = pk_bf16(a, b); w.y = pk_bf16(c, d); *(uint2*)(wsm + row * WST_ROW + col * 2) = w; }
; template <int H>
; DEV void epi1_group(const Params& p, int l, bool samp, int rbase, int g64, int fq, int fr, char* wsm, const f32x4 (&acc)[4][8]) {
;     ...
;     } else if (g64 < 90) {
;         const int c0 = (g64 - 42) * 64 + cl;
;         const float* bg = p.b_gate + l * 3072 + c0;
; #pragma unroll
;         for (int ni = 0; ni < 4; ++ni) {
;             const f32x4 b4 = *(const f32x4*)(bg + ni * 16);
; #pragma unroll
;             for (int mi = 0; mi < 4; ++mi) {
;                 f32x4 v = acc[mi][H * 4 + ni] + b4;
; #pragma unroll
;                 for (int j = 0; j < 4; ++j) v[j] = __builtin_amdgcn_rcpf(1.f + __expf(-v[j]));
;                 wst_put4(wsm, mi * 16 + fr, sc + ni * 16, v[0], v[1], v[2], v[3]);
;             }
	v_pk_add_f32 v[136:137], v[116:117], v[132:133]
	s_nop 0
	v_mul_f32_e32 v136, 0xbfb8aa3b, v136
	v_exp_f32_e32 v136, v136
	v_pk_add_f32 v[138:139], v[114:115], v[130:131]
	v_add_f32_e32 v136, 1.0, v136
	v_mul_f32_e32 v138, 0xbfb8aa3b, v138
	v_mul_f32_e32 v139, 0xbfb8aa3b, v139
	v_rcp_f32_e32 v140, v136
	v_mul_f32_e32 v136, 0xbfb8aa3b, v137
	v_exp_f32_e32 v138, v138
	v_exp_f32_e32 v139, v139
	v_exp_f32_e32 v136, v136
	v_add_f32_e32 v138, 1.0, v138
	v_add_f32_e32 v139, 1.0, v139
	v_add_f32_e32 v136, 1.0, v136
	v_rcp_f32_e32 v138, v138
	v_rcp_f32_e32 v139, v139
	v_rcp_f32_e32 v137, v136
	v_cvt_pk_bf16_f32 v136, v138, v139
	v_cvt_pk_bf16_f32 v137, v140, v137
	ds_write_b64 v32, v[136:137] offset:32
	v_pk_add_f32 v[136:137], v[108:109], v[132:133]
	v_pk_add_f32 v[138:139], v[106:107], v[130:131]
	v_mul_f32_e32 v136, 0xbfb8aa3b, v136
	v_exp_f32_e32 v136, v136
	v_mul_f32_e32 v138, 0xbfb8aa3b, v138
	v_mul_f32_e32 v139, 0xbfb8aa3b, v139
	v_exp_f32_e32 v138, v138
	v_add_f32_e32 v136, 1.0, v136
	v_rcp_f32_e32 v140, v136
	v_mul_f32_e32 v136, 0xbfb8aa3b, v137
	v_exp_f32_e32 v139, v139
	v_exp_f32_e32 v136, v136
	v_add_f32_e32 v138, 1.0, v138
	v_rcp_f32_e32 v138, v138
	v_add_f32_e32 v139, 1.0, v139
	v_add_f32_e32 v136, 1.0, v136
	v_rcp_f32_e32 v139, v139
	v_rcp_f32_e32 v137, v136
	v_cvt_pk_bf16_f32 v136, v138, v139
	v_cvt_pk_bf16_f32 v137, v140, v137
	ds_write_b64 v32, v[136:137] offset:4384
	v_pk_add_f32 v[136:137], v[88:89], v[132:133]
	v_pk_add_f32 v[138:139], v[86:87], v[130:131]
	v_mul_f32_e32 v136, 0xbfb8aa3b, v136
	v_exp_f32_e32 v136, v136
	v_pk_add_f32 v[132:133], v[72:73], v[132:133]
	v_pk_add_f32 v[130:131], v[70:71], v[130:131]
	v_mul_f32_e32 v138, 0xbfb8aa3b, v138
	v_add_f32_e32 v136, 1.0, v136
	v_mul_f32_e32 v139, 0xbfb8aa3b, v139
	v_rcp_f32_e32 v140, v136
	v_mul_f32_e32 v136, 0xbfb8aa3b, v137
	v_mul_f32_e32 v130, 0xbfb8aa3b, v130
	v_mul_f32_e32 v131, 0xbfb8aa3b, v131
	v_mul_f32_e32 v132, 0xbfb8aa3b, v132
	v_mul_f32_e32 v133, 0xbfb8aa3b, v133
	v_exp_f32_e32 v138, v138
	v_exp_f32_e32 v139, v139
	v_exp_f32_e32 v136, v136
	v_exp_f32_e32 v130, v130
	v_exp_f32_e32 v131, v131
	v_exp_f32_e32 v132, v132
	v_exp_f32_e32 v133, v133
	v_add_f32_e32 v138, 1.0, v138
	v_add_f32_e32 v139, 1.0, v139
	v_add_f32_e32 v136, 1.0, v136
	v_add_f32_e32 v130, 1.0, v130
	v_add_f32_e32 v131, 1.0, v131
	v_add_f32_e32 v132, 1.0, v132
	v_add_f32_e32 v133, 1.0, v133
	v_rcp_f32_e32 v138, v138
	v_rcp_f32_e32 v139, v139
	v_rcp_f32_e32 v137, v136
	v_rcp_f32_e32 v130, v130
	v_rcp_f32_e32 v131, v131
	v_rcp_f32_e32 v132, v132
	v_rcp_f32_e32 v133, v133
	v_cvt_pk_bf16_f32 v136, v138, v139
	v_cvt_pk_bf16_f32 v137, v140, v137
	v_cvt_pk_bf16_f32 v130, v130, v131
	v_cvt_pk_bf16_f32 v131, v132, v133
	ds_write_b64 v32, v[136:137] offset:8736
	ds_write_b64 v32, v[130:131] offset:13088
	flat_load_dwordx4 v[130:133], v[134:135] offset:128
	s_waitcnt vmcnt(0) lgkmcnt(0)
;     __device__ __forceinline__ bf16_t* H() const { return (bf16_t*)(ws + OFF_H); }
; DEV void wst_put4(char* wsm, int row, int col, float a, float b, float c, float d) { uint2 w; w.x = pk_bf16(a, b); w.y = pk_bf16(c, d); *(uint2*)(wsm + row * WST_ROW + col * 2) = w; }
; template <int H>
; DEV void epi1_group(const Params& p, int l, bool samp, int rbase, int g64, int fq, int fr, char* wsm, const f32x4 (&acc)[4][8]) {
;     ...
;     } else if (g64 < 90) {
;         const int c0 = (g64 - 42) * 64 + cl;
;         const float* bg = p.b_gate + l * 3072 + c0;
; #pragma unroll
;         for (int ni = 0; ni < 4; ++ni) {
;             const f32x4 b4 = *(const f32x4*)(bg + ni * 16);
; #pragma unroll
;             for (int mi = 0; mi < 4; ++mi) {
;                 f32x4 v = acc[mi][H * 4 + ni] + b4;
; #pragma unroll
;                 for (int j = 0; j < 4; ++j) v[j] = __builtin_amdgcn_rcpf(1.f + __expf(-v[j]));
;                 wst_put4(wsm, mi * 16 + fr, sc + ni * 16, v[0], v[1], v[2], v[3]);
;             }
	v_pk_add_f32 v[136:137], v[124:125], v[132:133]
	s_nop 0
	v_mul_f32_e32 v136, 0xbfb8aa3b, v136
	v_exp_f32_e32 v136, v136
	v_pk_add_f32 v[138:139], v[122:123], v[130:131]
	v_add_f32_e32 v136, 1.0, v136
	v_mul_f32_e32 v138, 0xbfb8aa3b, v138
	v_mul_f32_e32 v139, 0xbfb8aa3b, v139
	v_rcp_f32_e32 v140, v136
	v_mul_f32_e32 v136, 0xbfb8aa3b, v137
	v_exp_f32_e32 v138, v138
	v_exp_f32_e32 v139, v139
	v_exp_f32_e32 v136, v136
	v_add_f32_e32 v138, 1.0, v138
	v_add_f32_e32 v139, 1.0, v139
	v_add_f32_e32 v136, 1.0, v136
	v_rcp_f32_e32 v138, v138
	v_rcp_f32_e32 v139, v139
	v_rcp_f32_e32 v137, v136
	v_cvt_pk_bf16_f32 v136, v138, v139
	v_cvt_pk_bf16_f32 v137, v140, v137
	ds_write_b64 v32, v[136:137] offset:64
	v_pk_add_f32 v[136:137], v[104:105], v[132:133]
	v_pk_add_f32 v[138:139], v[102:103], v[130:131]
	v_mul_f32_e32 v136, 0xbfb8aa3b, v136
	v_exp_f32_e32 v136, v136
	v_mul_f32_e32 v138, 0xbfb8aa3b, v138
	v_mul_f32_e32 v139, 0xbfb8aa3b, v139
	v_exp_f32_e32 v138, v138
	v_add_f32_e32 v136, 1.0, v136
	v_rcp_f32_e32 v140, v136
	v_mul_f32_e32 v136, 0xbfb8aa3b, v137
	v_exp_f32_e32 v139, v139
	v_exp_f32_e32 v136, v136
	v_add_f32_e32 v138, 1.0, v138
	v_rcp_f32_e32 v138, v138
	v_add_f32_e32 v139, 1.0, v139
	v_add_f32_e32 v136, 1.0, v136
	v_rcp_f32_e32 v139, v139
	v_rcp_f32_e32 v137, v136
	v_cvt_pk_bf16_f32 v136, v138, v139
	v_cvt_pk_bf16_f32 v137, v140, v137
	ds_write_b64 v32, v[136:137] offset:4416
	v_pk_add_f32 v[136:137], v[92:93], v[132:133]
	v_pk_add_f32 v[138:139], v[90:91], v[130:131]
	v_mul_f32_e32 v136, 0xbfb8aa3b, v136
	v_exp_f32_e32 v136, v136
	v_pk_add_f32 v[132:133], v[76:77], v[132:133]
	v_pk_add_f32 v[130:131], v[74:75], v[130:131]
	v_mul_f32_e32 v138, 0xbfb8aa3b, v138
	v_add_f32_e32 v136, 1.0, v136
	v_mul_f32_e32 v139, 0xbfb8aa3b, v139
	v_rcp_f32_e32 v140, v136
	v_mul_f32_e32 v136, 0xbfb8aa3b, v137
	v_mul_f32_e32 v130, 0xbfb8aa3b, v130
	v_mul_f32_e32 v131, 0xbfb8aa3b, v131
	v_mul_f32_e32 v132, 0xbfb8aa3b, v132
	v_mul_f32_e32 v133, 0xbfb8aa3b, v133
	v_exp_f32_e32 v138, v138
	v_exp_f32_e32 v139, v139
	v_exp_f32_e32 v136, v136
	v_exp_f32_e32 v130, v130
	v_exp_f32_e32 v131, v131
	v_exp_f32_e32 v132, v132
	v_exp_f32_e32 v133, v133
	v_add_f32_e32 v138, 1.0, v138
	v_add_f32_e32 v139, 1.0, v139
	v_add_f32_e32 v136, 1.0, v136
	v_add_f32_e32 v130, 1.0, v130
	v_add_f32_e32 v131, 1.0, v131
	v_add_f32_e32 v132, 1.0, v132
	v_add_f32_e32 v133, 1.0, v133
	v_rcp_f32_e32 v138, v138
	v_rcp_f32_e32 v139, v139
	v_rcp_f32_e32 v137, v136
	v_rcp_f32_e32 v130, v130
	v_rcp_f32_e32 v131, v131
	v_rcp_f32_e32 v132, v132
	v_rcp_f32_e32 v133, v133
	v_cvt_pk_bf16_f32 v136, v138, v139
	v_cvt_pk_bf16_f32 v137, v140, v137
	v_cvt_pk_bf16_f32 v130, v130, v131
	v_cvt_pk_bf16_f32 v131, v132, v133
	ds_write_b64 v32, v[136:137] offset:8768
	ds_write_b64 v32, v[130:131] offset:13120
	flat_load_dwordx4 v[130:133], v[134:135] offset:192
	s_waitcnt vmcnt(0) lgkmcnt(0)
	v_pk_add_f32 v[134:135], v[128:129], v[132:133]
	s_nop 0
	v_mul_f32_e32 v134, 0xbfb8aa3b, v134
	v_exp_f32_e32 v134, v134
	v_pk_add_f32 v[136:137], v[126:127], v[130:131]
	v_add_f32_e32 v134, 1.0, v134
	v_mul_f32_e32 v136, 0xbfb8aa3b, v136
	v_mul_f32_e32 v137, 0xbfb8aa3b, v137
	v_rcp_f32_e32 v138, v134
	v_mul_f32_e32 v134, 0xbfb8aa3b, v135
	v_exp_f32_e32 v136, v136
	v_exp_f32_e32 v137, v137
	v_exp_f32_e32 v134, v134
	v_add_f32_e32 v136, 1.0, v136
	v_add_f32_e32 v137, 1.0, v137
	v_add_f32_e32 v134, 1.0, v134
	v_rcp_f32_e32 v136, v136
	v_rcp_f32_e32 v137, v137
	v_rcp_f32_e32 v135, v134
	v_cvt_pk_bf16_f32 v134, v136, v137
	v_cvt_pk_bf16_f32 v135, v138, v135
	ds_write_b64 v32, v[134:135] offset:96
	v_pk_add_f32 v[134:135], v[112:113], v[132:133]
	v_pk_add_f32 v[136:137], v[110:111], v[130:131]
	v_mul_f32_e32 v134, 0xbfb8aa3b, v134
	v_exp_f32_e32 v134, v134
	v_mul_f32_e32 v136, 0xbfb8aa3b, v136
	v_mul_f32_e32 v137, 0xbfb8aa3b, v137
	v_exp_f32_e32 v136, v136
	v_add_f32_e32 v134, 1.0, v134
	v_rcp_f32_e32 v138, v134
	v_mul_f32_e32 v134, 0xbfb8aa3b, v135
	v_exp_f32_e32 v137, v137
	v_exp_f32_e32 v134, v134
	v_add_f32_e32 v136, 1.0, v136
	v_rcp_f32_e32 v136, v136
	v_add_f32_e32 v137, 1.0, v137
	v_add_f32_e32 v134, 1.0, v134
	v_rcp_f32_e32 v137, v137
	v_rcp_f32_e32 v135, v134
	v_cvt_pk_bf16_f32 v134, v136, v137
	v_cvt_pk_bf16_f32 v135, v138, v135
	ds_write_b64 v32, v[134:135] offset:4448
	v_pk_add_f32 v[134:135], v[96:97], v[132:133]
	v_pk_add_f32 v[136:137], v[94:95], v[130:131]
	v_mul_f32_e32 v134, 0xbfb8aa3b, v134
	v_exp_f32_e32 v134, v134
	v_pk_add_f32 v[132:133], v[80:81], v[132:133]
	v_pk_add_f32 v[130:131], v[78:79], v[130:131]
	v_mul_f32_e32 v136, 0xbfb8aa3b, v136
	v_add_f32_e32 v134, 1.0, v134
	v_mul_f32_e32 v137, 0xbfb8aa3b, v137
	v_rcp_f32_e32 v138, v134
	v_mul_f32_e32 v134, 0xbfb8aa3b, v135
	v_mul_f32_e32 v130, 0xbfb8aa3b, v130
	v_mul_f32_e32 v131, 0xbfb8aa3b, v131
	v_mul_f32_e32 v132, 0xbfb8aa3b, v132
	v_mul_f32_e32 v133, 0xbfb8aa3b, v133
	v_exp_f32_e32 v136, v136
	v_exp_f32_e32 v137, v137
	v_exp_f32_e32 v134, v134
	v_exp_f32_e32 v130, v130
	v_exp_f32_e32 v131, v131
	v_exp_f32_e32 v132, v132
	v_exp_f32_e32 v133, v133
	v_add_f32_e32 v136, 1.0, v136
	v_add_f32_e32 v137, 1.0, v137
	v_add_f32_e32 v134, 1.0, v134
	v_add_f32_e32 v130, 1.0, v130
	v_add_f32_e32 v131, 1.0, v131
	v_add_f32_e32 v132, 1.0, v132
	v_add_f32_e32 v133, 1.0, v133
	v_rcp_f32_e32 v136, v136
	v_rcp_f32_e32 v137, v137
	v_rcp_f32_e32 v135, v134
	v_rcp_f32_e32 v130, v130
	v_rcp_f32_e32 v131, v131
	v_rcp_f32_e32 v132, v132
	v_rcp_f32_e32 v133, v133
	v_cvt_pk_bf16_f32 v134, v136, v137
	v_cvt_pk_bf16_f32 v135, v138, v135
	v_cvt_pk_bf16_f32 v130, v130, v131
	v_cvt_pk_bf16_f32 v131, v132, v133
	ds_write_b64 v32, v[134:135] offset:8800
	ds_write_b64 v32, v[130:131] offset:13152

; #define RAW_BARRIER() do { asm volatile("s_waitcnt lgkmcnt(0)" ::: "memory"); __builtin_amdgcn_s_barrier(); } while (0)
; #define GLDS_TILE(kt, st) do { _Pragma("unroll") for (int _i = 0; _i < NP; ++_i) GLDS_PIECE(_i, kt, st); } while (0)
;     ...
;     constexpr int NH = NI >= 4 ? NI / 2 : NI;
;     constexpr int NP = 2 + NB, IVL = (4 * NI) / NP;
;     RAW_BARRIER();
;     GLDS_TILE(0, 0);
;     GLDS_TILE(1, 1);
;     int st = 0;
;     for (int kt = 0; kt < nk - 1; ++kt) {
;         if (NI == 8) asm volatile("s_waitcnt vmcnt(6)" ::: "memory"); else if (NI == 4) asm volatile("s_waitcnt vmcnt(4)" ::: "memory"); else asm volatile("s_waitcnt vmcnt(3)" ::: "memory");
;         RAW_BARRIER();
;         const int s2 = st >= 1 ? st - 1 : 2;
;         const bool ld = kt + 2 < nk;
;         STEP_TILE(st, ld, kt + 2, s2);
;         st = st == 2 ? 0 : st + 1;
;     }
.LBB0_977:
	s_mul_i32 s6, s1, 0x6000
	s_add_i32 s7, s6, 0
	s_waitcnt vmcnt(6)
	v_add_u32_e32 v148, s7, v134
	v_add_u32_e32 v155, s7, v135
	s_waitcnt lgkmcnt(0)
	s_barrier
	ds_read_b128 v[158:161], v155 offset:8192
	ds_read_b128 v[136:139], v148
	ds_read_b128 v[140:143], v148 offset:1024
	ds_read_b128 v[144:147], v148 offset:2048
	ds_read_b128 v[148:151], v148 offset:3072
	ds_read_b128 v[162:165], v155 offset:9216
	ds_read_b128 v[166:169], v155 offset:10240
	ds_read_b128 v[170:173], v155 offset:11264
	s_addk_i32 s6, 0xa000
	s_cmp_gt_i32 s1, 0
	s_setprio 1
	s_waitcnt lgkmcnt(6)
	v_mfma_f32_16x16x32_bf16 v[126:129], v[158:161], v[136:139], v[126:129]
	s_cselect_b32 s6, s6, 0xc000
	v_add_u32_e32 v214, s6, v32
	v_lshl_add_u64 v[152:153], v[132:133], 0, s[4:5]
	s_waitcnt lgkmcnt(5)
	v_mfma_f32_16x16x32_bf16 v[110:113], v[158:161], v[140:143], v[110:113]
	v_lshl_add_u64 v[212:213], v[130:131], 0, s[4:5]
	v_lshl_add_u64 v[182:183], v[152:153], 0, s[10:11]
	v_add_u32_e32 v215, 0x2000, v214
	s_waitcnt lgkmcnt(4)
	v_mfma_f32_16x16x32_bf16 v[82:85], v[158:161], v[144:147], v[82:85]
	s_waitcnt lgkmcnt(3)
	v_mfma_f32_16x16x32_bf16 v[50:53], v[158:161], v[148:151], v[50:53]
	v_lshl_add_u64 v[158:159], v[212:213], 0, s[12:13]
	s_waitcnt lgkmcnt(2)
	v_mfma_f32_16x16x32_bf16 v[122:125], v[162:165], v[136:139], v[122:125]
	v_readfirstlane_b32 s6, v214
	s_mov_b32 m0, s6
	s_nop 0
	global_load_lds_dwordx4 v[158:159], off
	ds_read_b128 v[158:161], v155 offset:12288
	ds_read_b128 v[174:177], v155 offset:13312
	ds_read_b128 v[178:181], v155 offset:14336
	ds_read_b128 v[208:211], v155 offset:15360
	v_mfma_f32_16x16x32_bf16 v[102:105], v[162:165], v[140:143], v[102:105]
	v_mfma_f32_16x16x32_bf16 v[70:73], v[162:165], v[144:147], v[70:73]
	v_mfma_f32_16x16x32_bf16 v[38:41], v[162:165], v[148:151], v[38:41]
	s_waitcnt lgkmcnt(5)
	v_mfma_f32_16x16x32_bf16 v[118:121], v[166:169], v[136:139], v[118:121]
	v_mfma_f32_16x16x32_bf16 v[94:97], v[166:169], v[140:143], v[94:97]
	v_add_u32_e32 v155, 0x1000, v214
	v_lshl_add_u64 v[162:163], v[212:213], 0, s[14:15]
	v_readfirstlane_b32 s6, v155
	s_mov_b32 m0, s6
	s_nop 0
	global_load_lds_dwordx4 v[162:163], off
	v_mfma_f32_16x16x32_bf16 v[62:65], v[166:169], v[144:147], v[62:65]
	v_mfma_f32_16x16x32_bf16 v[28:31], v[166:169], v[148:151], v[28:31]
	s_waitcnt lgkmcnt(4)
	v_mfma_f32_16x16x32_bf16 v[114:117], v[170:173], v[136:139], v[114:117]
	v_mfma_f32_16x16x32_bf16 v[86:89], v[170:173], v[140:143], v[86:89]
	v_mfma_f32_16x16x32_bf16 v[54:57], v[170:173], v[144:147], v[54:57]
	v_readfirstlane_b32 s6, v215
	s_mov_b32 m0, s6
	s_nop 0
	global_load_lds_dwordx4 v[182:183], off
	v_mfma_f32_16x16x32_bf16 v[20:23], v[170:173], v[148:151], v[20:23]
	s_waitcnt lgkmcnt(0)
	v_mfma_f32_16x16x32_bf16 v[106:109], v[158:161], v[136:139], v[106:109]
	v_mfma_f32_16x16x32_bf16 v[74:77], v[158:161], v[140:143], v[74:77]
	v_mfma_f32_16x16x32_bf16 v[42:45], v[158:161], v[144:147], v[42:45]
	v_mfma_f32_16x16x32_bf16 v[12:15], v[158:161], v[148:151], v[12:15]
	v_add_u32_e32 v155, 0x3000, v214
	v_lshl_add_u64 v[158:159], v[152:153], 0, s[16:17]
	v_readfirstlane_b32 s6, v155
	s_mov_b32 m0, s6
	s_nop 0
	global_load_lds_dwordx4 v[158:159], off
	v_mfma_f32_16x16x32_bf16 v[98:101], v[174:177], v[136:139], v[98:101]
	v_mfma_f32_16x16x32_bf16 v[66:69], v[174:177], v[140:143], v[66:69]
	v_mfma_f32_16x16x32_bf16 v[34:37], v[174:177], v[144:147], v[34:37]
	v_mfma_f32_16x16x32_bf16 v[8:11], v[174:177], v[148:151], v[8:11]
	v_mfma_f32_16x16x32_bf16 v[90:93], v[178:181], v[136:139], v[90:93]
	v_add_u32_e32 v155, 0x4000, v214
	v_lshl_add_u64 v[158:159], v[152:153], 0, s[76:77]
	v_readfirstlane_b32 s6, v155
	s_mov_b32 m0, s6
	s_nop 0
	global_load_lds_dwordx4 v[158:159], off
	v_mfma_f32_16x16x32_bf16 v[58:61], v[178:181], v[140:143], v[58:61]
	v_mfma_f32_16x16x32_bf16 v[24:27], v[178:181], v[144:147], v[24:27]
	v_mfma_f32_16x16x32_bf16 v[4:7], v[178:181], v[148:151], v[4:7]
	v_mfma_f32_16x16x32_bf16 v[78:81], v[208:211], v[136:139], v[78:81]
	v_mfma_f32_16x16x32_bf16 v[46:49], v[208:211], v[140:143], v[46:49]
	v_add_u32_e32 v138, 0x5000, v214
	v_lshl_add_u64 v[136:137], v[152:153], 0, s[84:85]
	v_readfirstlane_b32 s6, v138
	s_mov_b32 m0, s6
	s_nop 0
	global_load_lds_dwordx4 v[136:137], off
	v_mfma_f32_16x16x32_bf16 v[16:19], v[208:211], v[144:147], v[16:19]
	v_mfma_f32_16x16x32_bf16 v[0:3], v[208:211], v[148:151], v[0:3]
	s_setprio 0
	s_add_i32 s6, s1, 1
	s_cmp_lg_u32 s1, 2
	s_cselect_b32 s1, s6, 0
	s_add_u32 s4, s4, 0x80
	s_addc_u32 s5, s5, 0
	s_cmpk_lg_i32 s4, 0xf00
	s_cbranch_scc1 .LBB0_977
	s_waitcnt vmcnt(6)
	v_add_u32_e32 v32, 0, v134
	v_add_u32_e32 v152, 0, v135
	s_waitcnt lgkmcnt(0)
	s_barrier
; #define RAW_BARRIER() do { asm volatile("s_waitcnt lgkmcnt(0)" ::: "memory"); __builtin_amdgcn_s_barrier(); } while (0)
;     ...
;     for (int kt = 0; kt < nk - 1; ++kt) {
;         if (NI == 8) asm volatile("s_waitcnt vmcnt(6)" ::: "memory"); else if (NI == 4) asm volatile("s_waitcnt vmcnt(4)" ::: "memory"); else asm volatile("s_waitcnt vmcnt(3)" ::: "memory");
;         RAW_BARRIER();
;         const int s2 = st >= 1 ? st - 1 : 2;
;         const bool ld = kt + 2 < nk;
;         STEP_TILE(st, ld, kt + 2, s2);
;         st = st == 2 ? 0 : st + 1;
;     }
;     asm volatile("s_waitcnt vmcnt(0)" ::: "memory");
;     RAW_BARRIER();
;     STEP_TILE(st, false, 0, 0);
;     RAW_BARRIER();
	ds_read_b128 v[130:133], v32
	ds_read_b128 v[136:139], v32 offset:1024
	ds_read_b128 v[140:143], v32 offset:2048
	ds_read_b128 v[144:147], v32 offset:3072
	ds_read_b128 v[148:151], v152 offset:8192
	ds_read_b128 v[158:161], v152 offset:9216
	ds_read_b128 v[162:165], v152 offset:10240
	ds_read_b128 v[166:169], v152 offset:11264
	s_sext_i32_i16 s0, s0
	s_setprio 1
	s_waitcnt lgkmcnt(0)
	v_mfma_f32_16x16x32_bf16 v[126:129], v[148:151], v[130:133], v[126:129]
	v_mfma_f32_16x16x32_bf16 v[110:113], v[148:151], v[136:139], v[110:113]
	v_mfma_f32_16x16x32_bf16 v[82:85], v[148:151], v[140:143], v[82:85]
	v_mfma_f32_16x16x32_bf16 v[50:53], v[148:151], v[144:147], v[50:53]
	v_mfma_f32_16x16x32_bf16 v[122:125], v[158:161], v[130:133], v[122:125]
	ds_read_b128 v[148:151], v152 offset:12288
	ds_read_b128 v[170:173], v152 offset:13312
	ds_read_b128 v[174:177], v152 offset:14336
	ds_read_b128 v[178:181], v152 offset:15360
	v_mfma_f32_16x16x32_bf16 v[102:105], v[158:161], v[136:139], v[102:105]
	v_mfma_f32_16x16x32_bf16 v[70:73], v[158:161], v[140:143], v[70:73]
	v_mfma_f32_16x16x32_bf16 v[38:41], v[158:161], v[144:147], v[38:41]
	v_mfma_f32_16x16x32_bf16 v[94:97], v[162:165], v[136:139], v[94:97]
	v_mfma_f32_16x16x32_bf16 v[158:161], v[162:165], v[130:133], v[118:121]
	v_mfma_f32_16x16x32_bf16 v[62:65], v[162:165], v[140:143], v[62:65]
	v_mfma_f32_16x16x32_bf16 v[28:31], v[162:165], v[144:147], v[28:31]
	v_mfma_f32_16x16x32_bf16 v[208:211], v[166:169], v[136:139], v[86:89]
	v_mfma_f32_16x16x32_bf16 v[54:57], v[166:169], v[140:143], v[54:57]
	v_mfma_f32_16x16x32_bf16 v[162:165], v[166:169], v[130:133], v[114:117]
	v_mfma_f32_16x16x32_bf16 v[20:23], v[166:169], v[144:147], v[20:23]
	s_waitcnt lgkmcnt(0)
	v_mfma_f32_16x16x32_bf16 v[42:45], v[148:151], v[140:143], v[42:45]
	v_mfma_f32_16x16x32_bf16 v[12:15], v[148:151], v[144:147], v[12:15]
	v_mfma_f32_16x16x32_bf16 v[166:169], v[148:151], v[130:133], v[106:109]
	v_mfma_f32_16x16x32_bf16 v[212:215], v[148:151], v[136:139], v[74:77]
	v_mfma_f32_16x16x32_bf16 v[148:151], v[170:173], v[130:133], v[98:101]
	v_mfma_f32_16x16x32_bf16 v[8:11], v[170:173], v[144:147], v[8:11]
	v_mfma_f32_16x16x32_bf16 v[216:219], v[170:173], v[136:139], v[66:69]
	v_mfma_f32_16x16x32_bf16 v[220:223], v[170:173], v[140:143], v[34:37]
	v_mfma_f32_16x16x32_bf16 v[170:173], v[174:177], v[130:133], v[90:93]
	v_mfma_f32_16x16x32_bf16 v[24:27], v[174:177], v[140:143], v[24:27]
	v_mfma_f32_16x16x32_bf16 v[46:49], v[178:181], v[136:139], v[46:49]
	v_mfma_f32_16x16x32_bf16 v[224:227], v[174:177], v[136:139], v[58:61]
	v_mfma_f32_16x16x32_bf16 v[174:177], v[174:177], v[144:147], v[4:7]
	v_mfma_f32_16x16x32_bf16 v[130:133], v[178:181], v[130:133], v[78:81]
	v_mfma_f32_16x16x32_bf16 v[134:137], v[178:181], v[140:143], v[16:19]
	v_mfma_f32_16x16x32_bf16 v[138:141], v[178:181], v[144:147], v[0:3]
	s_setprio 0
	s_waitcnt vmcnt(0)
	s_waitcnt lgkmcnt(0)
	s_barrier
	ds_read_b128 v[142:145], v32 offset:24576
	ds_read_b128 v[178:181], v32 offset:25600
	ds_read_b128 v[228:231], v32 offset:26624
	ds_read_b128 v[232:235], v32 offset:27648
	ds_read_b128 v[0:3], v152 offset:32768
	ds_read_b128 v[4:7], v152 offset:33792
	ds_read_b128 v[16:19], v152 offset:34816
	ds_read_b128 v[34:37], v152 offset:35840
	s_setprio 1
	s_waitcnt lgkmcnt(0)
	v_mfma_f32_16x16x32_bf16 v[118:121], v[0:3], v[142:145], v[126:129]
	v_mfma_f32_16x16x32_bf16 v[98:101], v[0:3], v[178:181], v[110:113]
	v_mfma_f32_16x16x32_bf16 v[82:85], v[0:3], v[228:231], v[82:85]
	v_mfma_f32_16x16x32_bf16 v[66:69], v[0:3], v[232:235], v[50:53]
	v_mfma_f32_16x16x32_bf16 v[114:117], v[4:7], v[142:145], v[122:125]
	ds_read_b128 v[0:3], v152 offset:36864
	ds_read_b128 v[236:239], v152 offset:37888
	ds_read_b128 v[240:243], v152 offset:38912
	ds_read_b128 v[244:247], v152 offset:39936
	v_mfma_f32_16x16x32_bf16 v[106:109], v[4:7], v[178:181], v[102:105]
	v_mfma_f32_16x16x32_bf16 v[86:89], v[4:7], v[228:231], v[70:73]
	v_mfma_f32_16x16x32_bf16 v[70:73], v[4:7], v[232:235], v[38:41]
	v_mfma_f32_16x16x32_bf16 v[122:125], v[16:19], v[142:145], v[158:161]
	v_mfma_f32_16x16x32_bf16 v[102:105], v[16:19], v[178:181], v[94:97]
	v_mfma_f32_16x16x32_bf16 v[90:93], v[16:19], v[228:231], v[62:65]
	v_mfma_f32_16x16x32_bf16 v[74:77], v[16:19], v[232:235], v[28:31]
	v_mfma_f32_16x16x32_bf16 v[126:129], v[34:37], v[142:145], v[162:165]
	v_mfma_f32_16x16x32_bf16 v[110:113], v[34:37], v[178:181], v[208:211]
	v_mfma_f32_16x16x32_bf16 v[94:97], v[34:37], v[228:231], v[54:57]
	v_mfma_f32_16x16x32_bf16 v[78:81], v[34:37], v[232:235], v[20:23]
	s_waitcnt lgkmcnt(0)
	v_mfma_f32_16x16x32_bf16 v[50:53], v[0:3], v[142:145], v[166:169]
	v_mfma_f32_16x16x32_bf16 v[34:37], v[0:3], v[178:181], v[212:215]
	v_mfma_f32_16x16x32_bf16 v[16:19], v[0:3], v[228:231], v[42:45]
	v_mfma_f32_16x16x32_bf16 v[0:3], v[0:3], v[232:235], v[12:15]
	v_mfma_f32_16x16x32_bf16 v[58:61], v[236:239], v[142:145], v[148:151]
	v_mfma_f32_16x16x32_bf16 v[38:41], v[236:239], v[178:181], v[216:219]
	v_mfma_f32_16x16x32_bf16 v[20:23], v[236:239], v[228:231], v[220:223]
	v_mfma_f32_16x16x32_bf16 v[4:7], v[236:239], v[232:235], v[8:11]
	v_mfma_f32_16x16x32_bf16 v[54:57], v[240:243], v[142:145], v[170:173]
	v_mfma_f32_16x16x32_bf16 v[42:45], v[240:243], v[178:181], v[224:227]
	v_mfma_f32_16x16x32_bf16 v[24:27], v[240:243], v[228:231], v[24:27]
	v_mfma_f32_16x16x32_bf16 v[8:11], v[240:243], v[232:235], v[174:177]
	v_mfma_f32_16x16x32_bf16 v[62:65], v[244:247], v[142:145], v[130:133]
	v_mfma_f32_16x16x32_bf16 v[46:49], v[244:247], v[178:181], v[46:49]
	v_mfma_f32_16x16x32_bf16 v[28:31], v[244:247], v[228:231], v[134:137]
	v_mfma_f32_16x16x32_bf16 v[12:15], v[244:247], v[232:235], v[138:141]
	s_setprio 0
	v_mov_b32_e32 v32, v186
	s_waitcnt lgkmcnt(0)
	s_barrier
;     __device__ __forceinline__ bf16_t* W1t() const { return (bf16_t*)(ws + OFF_W1t); }
;     __device__ __forceinline__ bf16_t* H() const { return (bf16_t*)(ws + OFF_H); }
; DEV int tid_opaque() { int t = threadIdx.x; asm volatile("" : "+v"(t)); return t; }
; DEV void wst_put4(char* wsm, int row, int col, float a, float b, float c, float d) { uint2 w; w.x = pk_bf16(a, b); w.y = pk_bf16(c, d); *(uint2*)(wsm + row * WST_ROW + col * 2) = w; }
; template <int H>
; DEV void epi1_group(const Params& p, int l, bool samp, int rbase, int g64, int fq, int fr, char* wsm, const f32x4 (&acc)[4][8]) {
;     ...
;     } else if (g64 < 90) {
;         const int c0 = (g64 - 42) * 64 + cl;
;         const float* bg = p.b_gate + l * 3072 + c0;
; #pragma unroll
;         for (int ni = 0; ni < 4; ++ni) {
;             const f32x4 b4 = *(const f32x4*)(bg + ni * 16);
; #pragma unroll
;             for (int mi = 0; mi < 4; ++mi) {
;                 f32x4 v = acc[mi][H * 4 + ni] + b4;
; #pragma unroll
;                 for (int j = 0; j < 4; ++j) v[j] = __builtin_amdgcn_rcpf(1.f + __expf(-v[j]));
;                 wst_put4(wsm, mi * 16 + fr, sc + ni * 16, v[0], v[1], v[2], v[3]);
;             }
; DEV void gemm1_big(const Params& p, int l, int mt, int nt, char* smem) {
;     f32x4 acc[4][8]; zero_accn<8>(acc);
;     gemm_glds<8>(p.H() + (size_t)mt * 128 * 1024, 1024, p.W1t() + (size_t)l * N1P * 1024 + (size_t)nt * 256 * 1024, 1024, 1024, acc, smem);
;     const int t = tid_opaque(), lane = t & 63, wid = t >> 6, wm = wid >> 1, wn = wid & 1, fr = lane & 15, fq = lane >> 4;
;     const int rbase = mt * 128 + wm * 64 + fr, g0 = nt * 4 + wn * 2;
;     char* wsm = smem + wid * WST_BYTES;
;     epi1_group<0>(p, l, mt == MT - 1, rbase, g0, fq, fr, wsm, acc);
;     epi1_group<1>(p, l, mt == MT - 1, rbase, g0 + 1, fq, fr, wsm, acc);
	v_readlane_b32 s4, v252, 27
	v_ashrrev_i32_e32 v130, 6, v32
	v_and_b32_e32 v208, 15, v32
	v_bfe_u32 v155, v32, 4, 2
	v_ashrrev_i32_e32 v32, 1, v32
	v_and_b32_e32 v32, 0xffffffc0, v32
	v_lshl_add_u32 v150, s0, 7, v32
	s_lshl_b32 s0, s4, 2
	v_lshlrev_b32_e32 v32, 1, v130
	v_and_or_b32 v210, v32, 2, s0
	s_movk_i32 s0, 0x4400
	v_mul_lo_u32 v32, v130, s0
	s_add_i32 s0, s8, 0xfa00
	s_and_b32 s0, s0, 0xffff
	s_cmp_gt_u32 s0, 11
	v_readlane_b32 s5, v252, 28
	s_cselect_b64 s[6:7], -1, 0
	s_cmp_gt_u32 s4, 2
	s_cselect_b64 s[4:5], -1, 0
	v_or_b32_e32 v152, v150, v208
	v_add_u32_e32 v209, 0, v32
	v_lshlrev_b32_e32 v151, 2, v155
	s_mov_b64 s[0:1], -1
	s_and_b64 vcc, exec, s[4:5]
	s_cbranch_vccz .LBB0_1628
	v_readlane_b32 s0, v252, 27
	v_readlane_b32 s1, v252, 28
	s_cmp_gt_u32 s0, 5
	s_mov_b64 s[0:1], -1
	s_cbranch_scc0 .LBB0_1188
	v_cmp_lt_u32_e32 vcc, 29, v210
	s_and_saveexec_b64 s[0:1], vcc
	s_xor_b64 s[8:9], exec, s[0:1]
	s_cbranch_execz .LBB0_1122
	v_cmp_lt_u32_e32 vcc, 33, v210
	s_and_saveexec_b64 s[0:1], vcc
	s_xor_b64 s[10:11], exec, s[0:1]
	s_cbranch_execz .LBB0_1119
	v_cmp_lt_u32_e32 vcc, 37, v210
	s_and_saveexec_b64 s[0:1], vcc
	s_xor_b64 s[0:1], exec, s[0:1]
	s_cbranch_execz .LBB0_1053
	v_cmp_lt_u32_e32 vcc, 41, v210
	s_and_saveexec_b64 s[12:13], vcc
	s_xor_b64 s[12:13], exec, s[12:13]
	s_cbranch_execz .LBB0_987
	s_movk_i32 s14, 0x5a
	v_cmp_gt_u32_e32 vcc, s14, v210
	s_and_saveexec_b64 s[14:15], vcc
	s_cbranch_execz .LBB0_986
	v_lshl_or_b32 v32, v210, 6, v151
	v_readlane_b32 s2, v250, 42
	v_add_u32_e32 v32, 0xfffff580, v32
	v_readlane_b32 s3, v250, 43
	s_nop 1
	v_lshl_add_u64 v[134:135], v[32:33], 2, s[2:3]
	flat_load_dwordx4 v[130:133], v[134:135]
	v_lshlrev_b32_e32 v32, 3, v155
	s_waitcnt vmcnt(0) lgkmcnt(0)
	v_pk_add_f32 v[136:137], v[120:121], v[132:133]
	s_nop 0
	v_mul_f32_e32 v136, 0xbfb8aa3b, v136
	v_exp_f32_e32 v136, v136
	v_pk_add_f32 v[138:139], v[118:119], v[130:131]
	v_add_f32_e32 v136, 1.0, v136
	v_mul_f32_e32 v138, 0xbfb8aa3b, v138
	v_mul_f32_e32 v139, 0xbfb8aa3b, v139
	v_exp_f32_e32 v138, v138
	v_exp_f32_e32 v139, v139
	v_rcp_f32_e32 v140, v136
	v_mul_f32_e32 v136, 0xbfb8aa3b, v137
	v_exp_f32_e32 v136, v136
	v_add_f32_e32 v138, 1.0, v138
	v_add_f32_e32 v139, 1.0, v139
	v_rcp_f32_e32 v138, v138
	v_rcp_f32_e32 v139, v139
	v_add_f32_e32 v136, 1.0, v136
	v_rcp_f32_e32 v137, v136
	v_cvt_pk_bf16_f32 v136, v138, v139
	v_mul_u32_u24_e32 v138, 0x110, v208
	v_cvt_pk_bf16_f32 v137, v140, v137
	v_add3_u32 v32, v209, v32, v138
	ds_write_b64 v32, v[136:137]
	v_pk_add_f32 v[136:137], v[100:101], v[132:133]
	v_pk_add_f32 v[138:139], v[98:99], v[130:131]
	v_mul_f32_e32 v136, 0xbfb8aa3b, v136
	v_exp_f32_e32 v136, v136
	v_mul_f32_e32 v138, 0xbfb8aa3b, v138
	v_mul_f32_e32 v139, 0xbfb8aa3b, v139
	v_exp_f32_e32 v138, v138
	v_add_f32_e32 v136, 1.0, v136
	v_rcp_f32_e32 v140, v136
	v_mul_f32_e32 v136, 0xbfb8aa3b, v137
	v_exp_f32_e32 v139, v139
	v_exp_f32_e32 v136, v136
	v_add_f32_e32 v138, 1.0, v138
	v_rcp_f32_e32 v138, v138
	v_add_f32_e32 v139, 1.0, v139
	v_add_f32_e32 v136, 1.0, v136
	v_rcp_f32_e32 v139, v139
	v_rcp_f32_e32 v137, v136
	v_cvt_pk_bf16_f32 v136, v138, v139
	v_cvt_pk_bf16_f32 v137, v140, v137
	ds_write_b64 v32, v[136:137] offset:4352
	v_pk_add_f32 v[136:137], v[84:85], v[132:133]
	v_pk_add_f32 v[138:139], v[82:83], v[130:131]
	v_mul_f32_e32 v136, 0xbfb8aa3b, v136
	v_exp_f32_e32 v136, v136
	v_pk_add_f32 v[132:133], v[68:69], v[132:133]
	v_pk_add_f32 v[130:131], v[66:67], v[130:131]
	v_mul_f32_e32 v138, 0xbfb8aa3b, v138
	v_add_f32_e32 v136, 1.0, v136
	v_mul_f32_e32 v139, 0xbfb8aa3b, v139
	v_rcp_f32_e32 v140, v136
	v_mul_f32_e32 v136, 0xbfb8aa3b, v137
	v_mul_f32_e32 v130, 0xbfb8aa3b, v130
	v_mul_f32_e32 v131, 0xbfb8aa3b, v131
	v_mul_f32_e32 v132, 0xbfb8aa3b, v132
	v_mul_f32_e32 v133, 0xbfb8aa3b, v133
	v_exp_f32_e32 v138, v138
	v_exp_f32_e32 v139, v139
	v_exp_f32_e32 v136, v136
	v_exp_f32_e32 v130, v130
	v_exp_f32_e32 v131, v131
	v_exp_f32_e32 v132, v132
	v_exp_f32_e32 v133, v133
	v_add_f32_e32 v138, 1.0, v138
	v_add_f32_e32 v139, 1.0, v139
	v_add_f32_e32 v136, 1.0, v136
	v_add_f32_e32 v130, 1.0, v130
	v_add_f32_e32 v131, 1.0, v131
	v_add_f32_e32 v132, 1.0, v132
	v_add_f32_e32 v133, 1.0, v133
	v_rcp_f32_e32 v138, v138
	v_rcp_f32_e32 v139, v139
	v_rcp_f32_e32 v137, v136
	v_rcp_f32_e32 v130, v130
	v_rcp_f32_e32 v131, v131
	v_rcp_f32_e32 v132, v132
	v_rcp_f32_e32 v133, v133
	v_cvt_pk_bf16_f32 v136, v138, v139
	v_cvt_pk_bf16_f32 v137, v140, v137
	v_cvt_pk_bf16_f32 v130, v130, v131
	v_cvt_pk_bf16_f32 v131, v132, v133
	ds_write_b64 v32, v[136:137] offset:8704
	ds_write_b64 v32, v[130:131] offset:13056
	flat_load_dwordx4 v[130:133], v[134:135] offset:64
	s_waitcnt vmcnt(0) lgkmcnt(0)
;     __device__ __forceinline__ bf16_t* H() const { return (bf16_t*)(ws + OFF_H); }
; DEV void wst_put4(char* wsm, int row, int col, float a, float b, float c, float d) { uint2 w; w.x = pk_bf16(a, b); w.y = pk_bf16(c, d); *(uint2*)(wsm + row * WST_ROW + col * 2) = w; }
; template <int H>
; DEV void epi1_group(const Params& p, int l, bool samp, int rbase, int g64, int fq, int fr, char* wsm, const f32x4 (&acc)[4][8]) {
;     ...
;     } else if (g64 < 90) {
;         const int c0 = (g64 - 42) * 64 + cl;
;         const float* bg = p.b_gate + l * 3072 + c0;
; #pragma unroll
;         for (int ni = 0; ni < 4; ++ni) {
;             const f32x4 b4 = *(const f32x4*)(bg + ni * 16);
; #pragma unroll
;             for (int mi = 0; mi < 4; ++mi) {
;                 f32x4 v = acc[mi][H * 4 + ni] + b4;
; #pragma unroll
;                 for (int j = 0; j < 4; ++j) v[j] = __builtin_amdgcn_rcpf(1.f + __expf(-v[j]));
;                 wst_put4(wsm, mi * 16 + fr, sc + ni * 16, v[0], v[1], v[2], v[3]);
;             }
	v_pk_add_f32 v[136:137], v[116:117], v[132:133]
	s_nop 0
	v_mul_f32_e32 v136, 0xbfb8aa3b, v136
	v_exp_f32_e32 v136, v136
	v_pk_add_f32 v[138:139], v[114:115], v[130:131]
	v_add_f32_e32 v136, 1.0, v136
	v_mul_f32_e32 v138, 0xbfb8aa3b, v138
	v_mul_f32_e32 v139, 0xbfb8aa3b, v139
	v_rcp_f32_e32 v140, v136
	v_mul_f32_e32 v136, 0xbfb8aa3b, v137
	v_exp_f32_e32 v138, v138
	v_exp_f32_e32 v139, v139
	v_exp_f32_e32 v136, v136
	v_add_f32_e32 v138, 1.0, v138
	v_add_f32_e32 v139, 1.0, v139
	v_add_f32_e32 v136, 1.0, v136
	v_rcp_f32_e32 v138, v138
	v_rcp_f32_e32 v139, v139
	v_rcp_f32_e32 v137, v136
	v_cvt_pk_bf16_f32 v136, v138, v139
	v_cvt_pk_bf16_f32 v137, v140, v137
	ds_write_b64 v32, v[136:137] offset:32
	v_pk_add_f32 v[136:137], v[108:109], v[132:133]
	v_pk_add_f32 v[138:139], v[106:107], v[130:131]
	v_mul_f32_e32 v136, 0xbfb8aa3b, v136
	v_exp_f32_e32 v136, v136
	v_mul_f32_e32 v138, 0xbfb8aa3b, v138
	v_mul_f32_e32 v139, 0xbfb8aa3b, v139
	v_exp_f32_e32 v138, v138
	v_add_f32_e32 v136, 1.0, v136
	v_rcp_f32_e32 v140, v136
	v_mul_f32_e32 v136, 0xbfb8aa3b, v137
	v_exp_f32_e32 v139, v139
	v_exp_f32_e32 v136, v136
	v_add_f32_e32 v138, 1.0, v138
	v_rcp_f32_e32 v138, v138
	v_add_f32_e32 v139, 1.0, v139
	v_add_f32_e32 v136, 1.0, v136
	v_rcp_f32_e32 v139, v139
	v_rcp_f32_e32 v137, v136
	v_cvt_pk_bf16_f32 v136, v138, v139
	v_cvt_pk_bf16_f32 v137, v140, v137
	ds_write_b64 v32, v[136:137] offset:4384
	v_pk_add_f32 v[136:137], v[88:89], v[132:133]
	v_pk_add_f32 v[138:139], v[86:87], v[130:131]
	v_mul_f32_e32 v136, 0xbfb8aa3b, v136
	v_exp_f32_e32 v136, v136
	v_pk_add_f32 v[132:133], v[72:73], v[132:133]
	v_pk_add_f32 v[130:131], v[70:71], v[130:131]
	v_mul_f32_e32 v138, 0xbfb8aa3b, v138
	v_add_f32_e32 v136, 1.0, v136
	v_mul_f32_e32 v139, 0xbfb8aa3b, v139
	v_rcp_f32_e32 v140, v136
	v_mul_f32_e32 v136, 0xbfb8aa3b, v137
	v_mul_f32_e32 v130, 0xbfb8aa3b, v130
	v_mul_f32_e32 v131, 0xbfb8aa3b, v131
	v_mul_f32_e32 v132, 0xbfb8aa3b, v132
	v_mul_f32_e32 v133, 0xbfb8aa3b, v133
	v_exp_f32_e32 v138, v138
	v_exp_f32_e32 v139, v139
	v_exp_f32_e32 v136, v136
	v_exp_f32_e32 v130, v130
	v_exp_f32_e32 v131, v131
	v_exp_f32_e32 v132, v132
	v_exp_f32_e32 v133, v133
	v_add_f32_e32 v138, 1.0, v138
	v_add_f32_e32 v139, 1.0, v139
	v_add_f32_e32 v136, 1.0, v136
	v_add_f32_e32 v130, 1.0, v130
	v_add_f32_e32 v131, 1.0, v131
	v_add_f32_e32 v132, 1.0, v132
	v_add_f32_e32 v133, 1.0, v133
	v_rcp_f32_e32 v138, v138
	v_rcp_f32_e32 v139, v139
	v_rcp_f32_e32 v137, v136
	v_rcp_f32_e32 v130, v130
	v_rcp_f32_e32 v131, v131
	v_rcp_f32_e32 v132, v132
	v_rcp_f32_e32 v133, v133
	v_cvt_pk_bf16_f32 v136, v138, v139
	v_cvt_pk_bf16_f32 v137, v140, v137
	v_cvt_pk_bf16_f32 v130, v130, v131
	v_cvt_pk_bf16_f32 v131, v132, v133
	ds_write_b64 v32, v[136:137] offset:8736
	ds_write_b64 v32, v[130:131] offset:13088
	flat_load_dwordx4 v[130:133], v[134:135] offset:128
	s_waitcnt vmcnt(0) lgkmcnt(0)
;     __device__ __forceinline__ bf16_t* H() const { return (bf16_t*)(ws + OFF_H); }
; DEV void wst_put4(char* wsm, int row, int col, float a, float b, float c, float d) { uint2 w; w.x = pk_bf16(a, b); w.y = pk_bf16(c, d); *(uint2*)(wsm + row * WST_ROW + col * 2) = w; }
; template <int H>
; DEV void epi1_group(const Params& p, int l, bool samp, int rbase, int g64, int fq, int fr, char* wsm, const f32x4 (&acc)[4][8]) {
;     ...
;     } else if (g64 < 90) {
;         const int c0 = (g64 - 42) * 64 + cl;
;         const float* bg = p.b_gate + l * 3072 + c0;
; #pragma unroll
;         for (int ni = 0; ni < 4; ++ni) {
;             const f32x4 b4 = *(const f32x4*)(bg + ni * 16);
; #pragma unroll
;             for (int mi = 0; mi < 4; ++mi) {
;                 f32x4 v = acc[mi][H * 4 + ni] + b4;
; #pragma unroll
;                 for (int j = 0; j < 4; ++j) v[j] = __builtin_amdgcn_rcpf(1.f + __expf(-v[j]));
;                 wst_put4(wsm, mi * 16 + fr, sc + ni * 16, v[0], v[1], v[2], v[3]);
;             }
	v_pk_add_f32 v[136:137], v[124:125], v[132:133]
	s_nop 0
	v_mul_f32_e32 v136, 0xbfb8aa3b, v136
	v_exp_f32_e32 v136, v136
	v_pk_add_f32 v[138:139], v[122:123], v[130:131]
	v_add_f32_e32 v136, 1.0, v136
	v_mul_f32_e32 v138, 0xbfb8aa3b, v138
	v_mul_f32_e32 v139, 0xbfb8aa3b, v139
	v_rcp_f32_e32 v140, v136
	v_mul_f32_e32 v136, 0xbfb8aa3b, v137
	v_exp_f32_e32 v138, v138
	v_exp_f32_e32 v139, v139
	v_exp_f32_e32 v136, v136
	v_add_f32_e32 v138, 1.0, v138
	v_add_f32_e32 v139, 1.0, v139
	v_add_f32_e32 v136, 1.0, v136
	v_rcp_f32_e32 v138, v138
	v_rcp_f32_e32 v139, v139
	v_rcp_f32_e32 v137, v136
	v_cvt_pk_bf16_f32 v136, v138, v139
	v_cvt_pk_bf16_f32 v137, v140, v137
	ds_write_b64 v32, v[136:137] offset:64
	v_pk_add_f32 v[136:137], v[104:105], v[132:133]
	v_pk_add_f32 v[138:139], v[102:103], v[130:131]
	v_mul_f32_e32 v136, 0xbfb8aa3b, v136
	v_exp_f32_e32 v136, v136
	v_mul_f32_e32 v138, 0xbfb8aa3b, v138
	v_mul_f32_e32 v139, 0xbfb8aa3b, v139
	v_exp_f32_e32 v138, v138
	v_add_f32_e32 v136, 1.0, v136
	v_rcp_f32_e32 v140, v136
	v_mul_f32_e32 v136, 0xbfb8aa3b, v137
	v_exp_f32_e32 v139, v139
	v_exp_f32_e32 v136, v136
	v_add_f32_e32 v138, 1.0, v138
	v_rcp_f32_e32 v138, v138
	v_add_f32_e32 v139, 1.0, v139
	v_add_f32_e32 v136, 1.0, v136
	v_rcp_f32_e32 v139, v139
	v_rcp_f32_e32 v137, v136
	v_cvt_pk_bf16_f32 v136, v138, v139
	v_cvt_pk_bf16_f32 v137, v140, v137
	ds_write_b64 v32, v[136:137] offset:4416
	v_pk_add_f32 v[136:137], v[92:93], v[132:133]
	v_pk_add_f32 v[138:139], v[90:91], v[130:131]
	v_mul_f32_e32 v136, 0xbfb8aa3b, v136
	v_exp_f32_e32 v136, v136
	v_pk_add_f32 v[132:133], v[76:77], v[132:133]
	v_pk_add_f32 v[130:131], v[74:75], v[130:131]
	v_mul_f32_e32 v138, 0xbfb8aa3b, v138
	v_add_f32_e32 v136, 1.0, v136
	v_mul_f32_e32 v139, 0xbfb8aa3b, v139
	v_rcp_f32_e32 v140, v136
	v_mul_f32_e32 v136, 0xbfb8aa3b, v137
	v_mul_f32_e32 v130, 0xbfb8aa3b, v130
	v_mul_f32_e32 v131, 0xbfb8aa3b, v131
	v_mul_f32_e32 v132, 0xbfb8aa3b, v132
	v_mul_f32_e32 v133, 0xbfb8aa3b, v133
	v_exp_f32_e32 v138, v138
	v_exp_f32_e32 v139, v139
	v_exp_f32_e32 v136, v136
	v_exp_f32_e32 v130, v130
	v_exp_f32_e32 v131, v131
	v_exp_f32_e32 v132, v132
	v_exp_f32_e32 v133, v133
	v_add_f32_e32 v138, 1.0, v138
	v_add_f32_e32 v139, 1.0, v139
	v_add_f32_e32 v136, 1.0, v136
	v_add_f32_e32 v130, 1.0, v130
	v_add_f32_e32 v131, 1.0, v131
	v_add_f32_e32 v132, 1.0, v132
	v_add_f32_e32 v133, 1.0, v133
	v_rcp_f32_e32 v138, v138
	v_rcp_f32_e32 v139, v139
	v_rcp_f32_e32 v137, v136
	v_rcp_f32_e32 v130, v130
	v_rcp_f32_e32 v131, v131
	v_rcp_f32_e32 v132, v132
	v_rcp_f32_e32 v133, v133
	v_cvt_pk_bf16_f32 v136, v138, v139
	v_cvt_pk_bf16_f32 v137, v140, v137
	v_cvt_pk_bf16_f32 v130, v130, v131
	v_cvt_pk_bf16_f32 v131, v132, v133
	ds_write_b64 v32, v[136:137] offset:8768
	ds_write_b64 v32, v[130:131] offset:13120
	flat_load_dwordx4 v[130:133], v[134:135] offset:192
	s_waitcnt vmcnt(0) lgkmcnt(0)
	v_pk_add_f32 v[134:135], v[128:129], v[132:133]
	s_nop 0
	v_mul_f32_e32 v134, 0xbfb8aa3b, v134
	v_exp_f32_e32 v134, v134
	v_pk_add_f32 v[136:137], v[126:127], v[130:131]
	v_add_f32_e32 v134, 1.0, v134
	v_mul_f32_e32 v136, 0xbfb8aa3b, v136
	v_mul_f32_e32 v137, 0xbfb8aa3b, v137
	v_rcp_f32_e32 v138, v134
	v_mul_f32_e32 v134, 0xbfb8aa3b, v135
	v_exp_f32_e32 v136, v136
	v_exp_f32_e32 v137, v137
	v_exp_f32_e32 v134, v134
	v_add_f32_e32 v136, 1.0, v136
	v_add_f32_e32 v137, 1.0, v137
	v_add_f32_e32 v134, 1.0, v134
	v_rcp_f32_e32 v136, v136
	v_rcp_f32_e32 v137, v137
	v_rcp_f32_e32 v135, v134
	v_cvt_pk_bf16_f32 v134, v136, v137
	v_cvt_pk_bf16_f32 v135, v138, v135
	ds_write_b64 v32, v[134:135] offset:96
	v_pk_add_f32 v[134:135], v[112:113], v[132:133]
	v_pk_add_f32 v[136:137], v[110:111], v[130:131]
	v_mul_f32_e32 v134, 0xbfb8aa3b, v134
	v_exp_f32_e32 v134, v134
	v_mul_f32_e32 v136, 0xbfb8aa3b, v136
	v_mul_f32_e32 v137, 0xbfb8aa3b, v137
	v_exp_f32_e32 v136, v136
	v_add_f32_e32 v134, 1.0, v134
	v_rcp_f32_e32 v138, v134
	v_mul_f32_e32 v134, 0xbfb8aa3b, v135
	v_exp_f32_e32 v137, v137
	v_exp_f32_e32 v134, v134
	v_add_f32_e32 v136, 1.0, v136
	v_rcp_f32_e32 v136, v136
	v_add_f32_e32 v137, 1.0, v137
	v_add_f32_e32 v134, 1.0, v134
	v_rcp_f32_e32 v137, v137
	v_rcp_f32_e32 v135, v134
	v_cvt_pk_bf16_f32 v134, v136, v137
	v_cvt_pk_bf16_f32 v135, v138, v135
	ds_write_b64 v32, v[134:135] offset:4448
	v_pk_add_f32 v[134:135], v[96:97], v[132:133]
	v_pk_add_f32 v[136:137], v[94:95], v[130:131]
	v_mul_f32_e32 v134, 0xbfb8aa3b, v134
	v_exp_f32_e32 v134, v134
	v_pk_add_f32 v[132:133], v[80:81], v[132:133]
	v_pk_add_f32 v[130:131], v[78:79], v[130:131]
	v_mul_f32_e32 v136, 0xbfb8aa3b, v136
	v_add_f32_e32 v134, 1.0, v134
	v_mul_f32_e32 v137, 0xbfb8aa3b, v137
	v_rcp_f32_e32 v138, v134
	v_mul_f32_e32 v134, 0xbfb8aa3b, v135
	v_mul_f32_e32 v130, 0xbfb8aa3b, v130
	v_mul_f32_e32 v131, 0xbfb8aa3b, v131
	v_mul_f32_e32 v132, 0xbfb8aa3b, v132
	v_mul_f32_e32 v133, 0xbfb8aa3b, v133
	v_exp_f32_e32 v136, v136
	v_exp_f32_e32 v137, v137
	v_exp_f32_e32 v134, v134
	v_exp_f32_e32 v130, v130
	v_exp_f32_e32 v131, v131
	v_exp_f32_e32 v132, v132
	v_exp_f32_e32 v133, v133
	v_add_f32_e32 v136, 1.0, v136
	v_add_f32_e32 v137, 1.0, v137
	v_add_f32_e32 v134, 1.0, v134
	v_add_f32_e32 v130, 1.0, v130
	v_add_f32_e32 v131, 1.0, v131
	v_add_f32_e32 v132, 1.0, v132
	v_add_f32_e32 v133, 1.0, v133
	v_rcp_f32_e32 v136, v136
	v_rcp_f32_e32 v137, v137
	v_rcp_f32_e32 v135, v134
	v_rcp_f32_e32 v130, v130
	v_rcp_f32_e32 v131, v131
	v_rcp_f32_e32 v132, v132
	v_rcp_f32_e32 v133, v133
	v_cvt_pk_bf16_f32 v134, v136, v137
	v_cvt_pk_bf16_f32 v135, v138, v135
	v_cvt_pk_bf16_f32 v130, v130, v131
	v_cvt_pk_bf16_f32 v131, v132, v133
	ds_write_b64 v32, v[134:135] offset:8800
	ds_write_b64 v32, v[130:131] offset:13152

; #define RAW_BARRIER() do { asm volatile("s_waitcnt lgkmcnt(0)" ::: "memory"); __builtin_amdgcn_s_barrier(); } while (0)
; #define GLDS_TILE(kt, st) do { _Pragma("unroll") for (int _i = 0; _i < NP; ++_i) GLDS_PIECE(_i, kt, st); } while (0)
;     ...
;     constexpr int NH = NI >= 4 ? NI / 2 : NI;
;     constexpr int NP = 2 + NB, IVL = (4 * NI) / NP;
;     RAW_BARRIER();
;     GLDS_TILE(0, 0);
;     GLDS_TILE(1, 1);
;     int st = 0;
;     for (int kt = 0; kt < nk - 1; ++kt) {
;         if (NI == 8) asm volatile("s_waitcnt vmcnt(6)" ::: "memory"); else if (NI == 4) asm volatile("s_waitcnt vmcnt(4)" ::: "memory"); else asm volatile("s_waitcnt vmcnt(3)" ::: "memory");
;         RAW_BARRIER();
;         const int s2 = st >= 1 ? st - 1 : 2;
;         const bool ld = kt + 2 < nk;
;         STEP_TILE(st, ld, kt + 2, s2);
;         st = st == 2 ? 0 : st + 1;
;     }
.LBB0_1940:
	s_mul_i32 s29, s1, 0x6000
	s_add_i32 s30, s29, 0
	s_waitcnt vmcnt(6)
	v_add_u32_e32 v148, s30, v134
	v_add_u32_e32 v155, s30, v135
	s_waitcnt lgkmcnt(0)
	s_barrier
	ds_read_b128 v[158:161], v155 offset:8192
	ds_read_b128 v[136:139], v148
	ds_read_b128 v[140:143], v148 offset:1024
	ds_read_b128 v[144:147], v148 offset:2048
	ds_read_b128 v[148:151], v148 offset:3072
	ds_read_b128 v[162:165], v155 offset:9216
	ds_read_b128 v[166:169], v155 offset:10240
	ds_read_b128 v[170:173], v155 offset:11264
	s_addk_i32 s29, 0xa000
	s_cmp_gt_i32 s1, 0
	s_setprio 1
	s_waitcnt lgkmcnt(6)
	v_mfma_f32_16x16x32_bf16 v[126:129], v[158:161], v[136:139], v[126:129]
	s_cselect_b32 s29, s29, 0xc000
	v_add_u32_e32 v157, s29, v32
	v_lshl_add_u64 v[152:153], v[132:133], 0, s[22:23]
	s_waitcnt lgkmcnt(5)
	v_mfma_f32_16x16x32_bf16 v[110:113], v[158:161], v[140:143], v[110:113]
	v_lshl_add_u64 v[208:209], v[130:131], 0, s[22:23]
	v_lshl_add_u64 v[206:207], v[152:153], 0, s[34:35]
	v_add_u32_e32 v205, 0x2000, v157
	s_waitcnt lgkmcnt(4)
	v_mfma_f32_16x16x32_bf16 v[82:85], v[158:161], v[144:147], v[82:85]
	s_waitcnt lgkmcnt(3)
	v_mfma_f32_16x16x32_bf16 v[50:53], v[158:161], v[148:151], v[50:53]
	v_lshl_add_u64 v[158:159], v[208:209], 0, s[38:39]
	s_waitcnt lgkmcnt(2)
	v_mfma_f32_16x16x32_bf16 v[122:125], v[162:165], v[136:139], v[122:125]
	v_readfirstlane_b32 s29, v157
	s_mov_b32 m0, s29
	s_nop 0
	global_load_lds_dwordx4 v[158:159], off
	ds_read_b128 v[158:161], v155 offset:12288
	ds_read_b128 v[174:177], v155 offset:13312
	ds_read_b128 v[178:181], v155 offset:14336
	ds_read_b128 v[182:185], v155 offset:15360
	v_mfma_f32_16x16x32_bf16 v[102:105], v[162:165], v[140:143], v[102:105]
	v_mfma_f32_16x16x32_bf16 v[70:73], v[162:165], v[144:147], v[70:73]
	v_mfma_f32_16x16x32_bf16 v[38:41], v[162:165], v[148:151], v[38:41]
	s_waitcnt lgkmcnt(5)
	v_mfma_f32_16x16x32_bf16 v[118:121], v[166:169], v[136:139], v[118:121]
	v_mfma_f32_16x16x32_bf16 v[94:97], v[166:169], v[140:143], v[94:97]
	v_add_u32_e32 v155, 0x1000, v157
	v_lshl_add_u64 v[162:163], v[208:209], 0, s[40:41]
	v_readfirstlane_b32 s29, v155
	s_mov_b32 m0, s29
	s_nop 0
	global_load_lds_dwordx4 v[162:163], off
	v_mfma_f32_16x16x32_bf16 v[62:65], v[166:169], v[144:147], v[62:65]
	v_mfma_f32_16x16x32_bf16 v[28:31], v[166:169], v[148:151], v[28:31]
	s_waitcnt lgkmcnt(4)
	v_mfma_f32_16x16x32_bf16 v[114:117], v[170:173], v[136:139], v[114:117]
	v_mfma_f32_16x16x32_bf16 v[86:89], v[170:173], v[140:143], v[86:89]
	v_mfma_f32_16x16x32_bf16 v[54:57], v[170:173], v[144:147], v[54:57]
	v_readfirstlane_b32 s29, v205
	s_mov_b32 m0, s29
	s_nop 0
	global_load_lds_dwordx4 v[206:207], off
	v_mfma_f32_16x16x32_bf16 v[20:23], v[170:173], v[148:151], v[20:23]
	s_waitcnt lgkmcnt(0)
	v_mfma_f32_16x16x32_bf16 v[106:109], v[158:161], v[136:139], v[106:109]
	v_mfma_f32_16x16x32_bf16 v[74:77], v[158:161], v[140:143], v[74:77]
	v_mfma_f32_16x16x32_bf16 v[42:45], v[158:161], v[144:147], v[42:45]
	v_mfma_f32_16x16x32_bf16 v[12:15], v[158:161], v[148:151], v[12:15]
	v_add_u32_e32 v155, 0x3000, v157
	v_lshl_add_u64 v[158:159], v[152:153], 0, s[42:43]
	v_readfirstlane_b32 s29, v155
	s_mov_b32 m0, s29
	s_nop 0
	global_load_lds_dwordx4 v[158:159], off
	v_mfma_f32_16x16x32_bf16 v[98:101], v[174:177], v[136:139], v[98:101]
	v_mfma_f32_16x16x32_bf16 v[66:69], v[174:177], v[140:143], v[66:69]
	v_mfma_f32_16x16x32_bf16 v[34:37], v[174:177], v[144:147], v[34:37]
	v_mfma_f32_16x16x32_bf16 v[8:11], v[174:177], v[148:151], v[8:11]
	v_mfma_f32_16x16x32_bf16 v[90:93], v[178:181], v[136:139], v[90:93]
	v_add_u32_e32 v155, 0x4000, v157
	v_lshl_add_u64 v[158:159], v[152:153], 0, s[76:77]
	v_readfirstlane_b32 s29, v155
	s_mov_b32 m0, s29
	s_nop 0
	global_load_lds_dwordx4 v[158:159], off
	v_mfma_f32_16x16x32_bf16 v[58:61], v[178:181], v[140:143], v[58:61]
	v_mfma_f32_16x16x32_bf16 v[24:27], v[178:181], v[144:147], v[24:27]
	v_mfma_f32_16x16x32_bf16 v[4:7], v[178:181], v[148:151], v[4:7]
	v_mfma_f32_16x16x32_bf16 v[78:81], v[182:185], v[136:139], v[78:81]
	v_mfma_f32_16x16x32_bf16 v[46:49], v[182:185], v[140:143], v[46:49]
	v_add_u32_e32 v138, 0x5000, v157
	v_lshl_add_u64 v[136:137], v[152:153], 0, s[84:85]
	v_readfirstlane_b32 s29, v138
	s_mov_b32 m0, s29
	s_nop 0
	global_load_lds_dwordx4 v[136:137], off
	v_mfma_f32_16x16x32_bf16 v[16:19], v[182:185], v[144:147], v[16:19]
	v_mfma_f32_16x16x32_bf16 v[0:3], v[182:185], v[148:151], v[0:3]
	s_setprio 0
	s_add_i32 s29, s1, 1
	s_cmp_lg_u32 s1, 2
	s_cselect_b32 s1, s29, 0
	s_add_u32 s22, s22, 0x80
	s_addc_u32 s23, s23, 0
	s_cmpk_lg_i32 s22, 0xf00
	s_cbranch_scc1 .LBB0_1940
	s_waitcnt vmcnt(6)
	v_add_u32_e32 v32, 0, v134
	v_add_u32_e32 v152, 0, v135
	s_waitcnt lgkmcnt(0)
	s_barrier
; #define RAW_BARRIER() do { asm volatile("s_waitcnt lgkmcnt(0)" ::: "memory"); __builtin_amdgcn_s_barrier(); } while (0)
;     ...
;     for (int kt = 0; kt < nk - 1; ++kt) {
;         if (NI == 8) asm volatile("s_waitcnt vmcnt(6)" ::: "memory"); else if (NI == 4) asm volatile("s_waitcnt vmcnt(4)" ::: "memory"); else asm volatile("s_waitcnt vmcnt(3)" ::: "memory");
;         RAW_BARRIER();
;         const int s2 = st >= 1 ? st - 1 : 2;
;         const bool ld = kt + 2 < nk;
;         STEP_TILE(st, ld, kt + 2, s2);
;         st = st == 2 ? 0 : st + 1;
;     }
;     asm volatile("s_waitcnt vmcnt(0)" ::: "memory");
;     RAW_BARRIER();
;     STEP_TILE(st, false, 0, 0);
;     RAW_BARRIER();
	ds_read_b128 v[130:133], v32
	ds_read_b128 v[136:139], v32 offset:1024
	ds_read_b128 v[140:143], v32 offset:2048
	ds_read_b128 v[144:147], v32 offset:3072
	ds_read_b128 v[148:151], v152 offset:8192
	ds_read_b128 v[158:161], v152 offset:9216
	ds_read_b128 v[162:165], v152 offset:10240
	ds_read_b128 v[166:169], v152 offset:11264
	s_setprio 1
	s_waitcnt lgkmcnt(0)
	v_mfma_f32_16x16x32_bf16 v[126:129], v[148:151], v[130:133], v[126:129]
	v_mfma_f32_16x16x32_bf16 v[110:113], v[148:151], v[136:139], v[110:113]
	v_mfma_f32_16x16x32_bf16 v[82:85], v[148:151], v[140:143], v[82:85]
	v_mfma_f32_16x16x32_bf16 v[50:53], v[148:151], v[144:147], v[50:53]
	v_mfma_f32_16x16x32_bf16 v[122:125], v[158:161], v[130:133], v[122:125]
	ds_read_b128 v[148:151], v152 offset:12288
	ds_read_b128 v[170:173], v152 offset:13312
	ds_read_b128 v[174:177], v152 offset:14336
	ds_read_b128 v[178:181], v152 offset:15360
	v_mfma_f32_16x16x32_bf16 v[102:105], v[158:161], v[136:139], v[102:105]
	v_mfma_f32_16x16x32_bf16 v[70:73], v[158:161], v[140:143], v[70:73]
	v_mfma_f32_16x16x32_bf16 v[38:41], v[158:161], v[144:147], v[38:41]
	v_mfma_f32_16x16x32_bf16 v[118:121], v[162:165], v[130:133], v[118:121]
	v_mfma_f32_16x16x32_bf16 v[158:161], v[162:165], v[136:139], v[94:97]
	v_mfma_f32_16x16x32_bf16 v[62:65], v[162:165], v[140:143], v[62:65]
	v_mfma_f32_16x16x32_bf16 v[28:31], v[162:165], v[144:147], v[28:31]
	v_mfma_f32_16x16x32_bf16 v[114:117], v[166:169], v[130:133], v[114:117]
	v_mfma_f32_16x16x32_bf16 v[54:57], v[166:169], v[140:143], v[54:57]
	v_mfma_f32_16x16x32_bf16 v[162:165], v[166:169], v[136:139], v[86:89]
	v_mfma_f32_16x16x32_bf16 v[20:23], v[166:169], v[144:147], v[20:23]
	s_waitcnt lgkmcnt(0)
	v_mfma_f32_16x16x32_bf16 v[42:45], v[148:151], v[140:143], v[42:45]
	v_mfma_f32_16x16x32_bf16 v[12:15], v[148:151], v[144:147], v[12:15]
	v_mfma_f32_16x16x32_bf16 v[166:169], v[148:151], v[130:133], v[106:109]
	v_mfma_f32_16x16x32_bf16 v[182:185], v[148:151], v[136:139], v[74:77]
	v_mfma_f32_16x16x32_bf16 v[148:151], v[170:173], v[130:133], v[98:101]
	v_mfma_f32_16x16x32_bf16 v[206:209], v[170:173], v[136:139], v[66:69]
	v_mfma_f32_16x16x32_bf16 v[34:37], v[170:173], v[140:143], v[34:37]
	v_mfma_f32_16x16x32_bf16 v[8:11], v[170:173], v[144:147], v[8:11]
	v_mfma_f32_16x16x32_bf16 v[170:173], v[174:177], v[130:133], v[90:93]
	v_mfma_f32_16x16x32_bf16 v[4:7], v[174:177], v[144:147], v[4:7]
	v_mfma_f32_16x16x32_bf16 v[210:213], v[174:177], v[136:139], v[58:61]
	v_mfma_f32_16x16x32_bf16 v[214:217], v[174:177], v[140:143], v[24:27]
	v_mfma_f32_16x16x32_bf16 v[130:133], v[178:181], v[130:133], v[78:81]
	v_mfma_f32_16x16x32_bf16 v[134:137], v[178:181], v[136:139], v[46:49]
	v_mfma_f32_16x16x32_bf16 v[16:19], v[178:181], v[140:143], v[16:19]
	v_mfma_f32_16x16x32_bf16 v[0:3], v[178:181], v[144:147], v[0:3]
	s_setprio 0
	s_waitcnt vmcnt(0)
	s_waitcnt lgkmcnt(0)
	s_barrier
	ds_read_b128 v[138:141], v32 offset:24576
	ds_read_b128 v[142:145], v32 offset:25600
	ds_read_b128 v[174:177], v32 offset:26624
	ds_read_b128 v[178:181], v32 offset:27648
	ds_read_b128 v[24:27], v152 offset:32768
	ds_read_b128 v[46:49], v152 offset:33792
	ds_read_b128 v[58:61], v152 offset:34816
	ds_read_b128 v[66:69], v152 offset:35840
	s_setprio 1
	s_waitcnt lgkmcnt(0)
	v_mfma_f32_16x16x32_bf16 v[126:129], v[24:27], v[138:141], v[126:129]
	v_mfma_f32_16x16x32_bf16 v[110:113], v[24:27], v[142:145], v[110:113]
	v_mfma_f32_16x16x32_bf16 v[94:97], v[24:27], v[174:177], v[82:85]
	v_mfma_f32_16x16x32_bf16 v[78:81], v[24:27], v[178:181], v[50:53]
	v_mfma_f32_16x16x32_bf16 v[122:125], v[46:49], v[138:141], v[122:125]
	ds_read_b128 v[24:27], v152 offset:36864
	s_nop 0
	ds_read_b128 v[50:53], v152 offset:37888
	ds_read_b128 v[218:221], v152 offset:38912
	ds_read_b128 v[222:225], v152 offset:39936
	v_mfma_f32_16x16x32_bf16 v[106:109], v[46:49], v[142:145], v[102:105]
	v_mfma_f32_16x16x32_bf16 v[90:93], v[46:49], v[174:177], v[70:73]
	v_mfma_f32_16x16x32_bf16 v[74:77], v[46:49], v[178:181], v[38:41]
	v_mfma_f32_16x16x32_bf16 v[118:121], v[58:61], v[138:141], v[118:121]
	v_mfma_f32_16x16x32_bf16 v[102:105], v[58:61], v[142:145], v[158:161]
	v_mfma_f32_16x16x32_bf16 v[86:89], v[58:61], v[174:177], v[62:65]
	v_mfma_f32_16x16x32_bf16 v[70:73], v[58:61], v[178:181], v[28:31]
	v_mfma_f32_16x16x32_bf16 v[114:117], v[66:69], v[138:141], v[114:117]
	v_mfma_f32_16x16x32_bf16 v[98:101], v[66:69], v[142:145], v[162:165]
	v_mfma_f32_16x16x32_bf16 v[82:85], v[66:69], v[174:177], v[54:57]
	v_mfma_f32_16x16x32_bf16 v[66:69], v[66:69], v[178:181], v[20:23]
	s_waitcnt lgkmcnt(0)
	v_mfma_f32_16x16x32_bf16 v[62:65], v[24:27], v[138:141], v[166:169]
	v_mfma_f32_16x16x32_bf16 v[46:49], v[24:27], v[142:145], v[182:185]
	v_mfma_f32_16x16x32_bf16 v[28:31], v[24:27], v[174:177], v[42:45]
	v_mfma_f32_16x16x32_bf16 v[12:15], v[24:27], v[178:181], v[12:15]
	v_mfma_f32_16x16x32_bf16 v[58:61], v[50:53], v[138:141], v[148:151]
	v_mfma_f32_16x16x32_bf16 v[42:45], v[50:53], v[142:145], v[206:209]
	v_mfma_f32_16x16x32_bf16 v[24:27], v[50:53], v[174:177], v[34:37]
	v_mfma_f32_16x16x32_bf16 v[8:11], v[50:53], v[178:181], v[8:11]
	v_mfma_f32_16x16x32_bf16 v[54:57], v[218:221], v[138:141], v[170:173]
	v_mfma_f32_16x16x32_bf16 v[38:41], v[218:221], v[142:145], v[210:213]
	v_mfma_f32_16x16x32_bf16 v[20:23], v[218:221], v[174:177], v[214:217]
	v_mfma_f32_16x16x32_bf16 v[4:7], v[218:221], v[178:181], v[4:7]
	v_mfma_f32_16x16x32_bf16 v[50:53], v[222:225], v[138:141], v[130:133]
	v_mfma_f32_16x16x32_bf16 v[34:37], v[222:225], v[142:145], v[134:137]
	v_mfma_f32_16x16x32_bf16 v[16:19], v[222:225], v[174:177], v[16:19]
	v_mfma_f32_16x16x32_bf16 v[0:3], v[222:225], v[178:181], v[0:3]
	s_setprio 0
	v_mov_b32_e32 v32, v186
	s_waitcnt lgkmcnt(0)
	s_barrier
;     __device__ __forceinline__ bf16_t* W1t() const { return (bf16_t*)(ws + OFF_W1t); }
;     __device__ __forceinline__ bf16_t* H() const { return (bf16_t*)(ws + OFF_H); }
;     __device__ __forceinline__ bf16_t* U() const { return (bf16_t*)(ws + OFF_U); }
;     __device__ __forceinline__ bf16_t* Vs() const { return (bf16_t*)(ws + OFF_Vs); }
; DEV int tid_opaque() { int t = threadIdx.x; asm volatile("" : "+v"(t)); return t; }
; template <int H>
; DEV void epi1_group(const Params& p, int l, bool samp, int rbase, int g64, int fq, int fr, char* wsm, const f32x4 (&acc)[4][8]) {
;     const int cl = fq * 4;
;     const int sc = H * 64 + cl;
;     if (g64 < 12) {
;         bf16_t* dst = g64 < 6 ? p.U() : p.Vs(); const int c0 = (g64 % 6) * 64 + cl;
; DEV void gemm1_big(const Params& p, int l, int mt, int nt, char* smem) {
;     f32x4 acc[4][8]; zero_accn<8>(acc);
;     gemm_glds<8>(p.H() + (size_t)mt * 128 * 1024, 1024, p.W1t() + (size_t)l * N1P * 1024 + (size_t)nt * 256 * 1024, 1024, 1024, acc, smem);
;     const int t = tid_opaque(), lane = t & 63, wid = t >> 6, wm = wid >> 1, wn = wid & 1, fr = lane & 15, fq = lane >> 4;
;     const int rbase = mt * 128 + wm * 64 + fr, g0 = nt * 4 + wn * 2;
;     char* wsm = smem + wid * WST_BYTES;
;     epi1_group<0>(p, l, mt == MT - 1, rbase, g0, fq, fr, wsm, acc);
;     epi1_group<1>(p, l, mt == MT - 1, rbase, g0 + 1, fq, fr, wsm, acc);
	s_lshl_b32 s34, s0, 2
	v_ashrrev_i32_e32 v130, 6, v32
	v_and_b32_e32 v205, 15, v32
	v_bfe_u32 v155, v32, 4, 2
	v_ashrrev_i32_e32 v32, 1, v32
	v_and_b32_e32 v32, 0xffffffc0, v32
	v_lshl_add_u32 v146, s28, 7, v32
	v_lshlrev_b32_e32 v32, 1, v130
	s_movk_i32 s0, 0x4400
	v_and_or_b32 v206, v32, 2, s34
	v_mul_lo_u32 v32, v130, s0
	s_cmpk_lg_i32 s28, 0x80
	v_or_b32_e32 v148, v146, v205
	v_add_u32_e32 v157, 0, v32
	s_cselect_b64 s[42:43], -1, 0
	v_lshlrev_b32_e32 v147, 2, v155
	v_cmp_lt_i32_e64 s[38:39], 11, v206
	s_and_saveexec_b64 s[0:1], s[38:39]
	s_xor_b64 s[64:65], exec, s[0:1]
	s_cbranch_execz .LBB0_2265
	s_cmp_gt_u32 s34, 23
	s_mov_b64 s[0:1], -1
	s_cbranch_scc0 .LBB0_2151
	v_cmp_lt_u32_e32 vcc, 29, v206
	s_and_saveexec_b64 s[0:1], vcc
	s_xor_b64 s[66:67], exec, s[0:1]
	s_cbranch_execz .LBB0_2085
	v_cmp_lt_u32_e32 vcc, 33, v206
	s_and_saveexec_b64 s[0:1], vcc
	s_xor_b64 s[68:69], exec, s[0:1]
	s_cbranch_execz .LBB0_2082
	v_cmp_lt_u32_e32 vcc, 37, v206
	s_and_saveexec_b64 s[0:1], vcc
	s_xor_b64 s[0:1], exec, s[0:1]
	s_cbranch_execz .LBB0_2016
	v_cmp_lt_u32_e32 vcc, 41, v206
	s_and_saveexec_b64 s[22:23], vcc
	s_xor_b64 s[40:41], exec, s[22:23]
	s_cbranch_execz .LBB0_1950
	s_movk_i32 s22, 0x5a
	v_cmp_gt_u32_e32 vcc, s22, v206
	s_and_saveexec_b64 s[70:71], vcc
	s_cbranch_execz .LBB0_1949
	v_lshl_or_b32 v32, v206, 6, v147
	v_add_u32_e32 v32, 0xfffff580, v32
	v_lshl_add_u64 v[134:135], v[32:33], 2, s[6:7]
	flat_load_dwordx4 v[130:133], v[134:135]
	v_lshlrev_b32_e32 v32, 3, v155
	s_waitcnt vmcnt(0) lgkmcnt(0)
	v_pk_add_f32 v[136:137], v[128:129], v[132:133]
	s_nop 0
	v_mul_f32_e32 v136, 0xbfb8aa3b, v136
	v_exp_f32_e32 v136, v136
	v_pk_add_f32 v[138:139], v[126:127], v[130:131]
	v_add_f32_e32 v136, 1.0, v136
	v_mul_f32_e32 v138, 0xbfb8aa3b, v138
	v_mul_f32_e32 v139, 0xbfb8aa3b, v139
	v_exp_f32_e32 v138, v138
	v_exp_f32_e32 v139, v139
	v_rcp_f32_e32 v140, v136
	v_mul_f32_e32 v136, 0xbfb8aa3b, v137
	v_exp_f32_e32 v136, v136
	v_add_f32_e32 v138, 1.0, v138
	v_add_f32_e32 v139, 1.0, v139
	v_rcp_f32_e32 v138, v138
	v_rcp_f32_e32 v139, v139
	v_add_f32_e32 v136, 1.0, v136
	v_rcp_f32_e32 v137, v136
	v_cvt_pk_bf16_f32 v136, v138, v139
	v_mul_u32_u24_e32 v138, 0x110, v205
	v_cvt_pk_bf16_f32 v137, v140, v137
	v_add3_u32 v32, v157, v32, v138
	ds_write_b64 v32, v[136:137]
	v_pk_add_f32 v[136:137], v[112:113], v[132:133]
	v_pk_add_f32 v[138:139], v[110:111], v[130:131]
	v_mul_f32_e32 v136, 0xbfb8aa3b, v136
	v_exp_f32_e32 v136, v136
	v_mul_f32_e32 v138, 0xbfb8aa3b, v138
	v_mul_f32_e32 v139, 0xbfb8aa3b, v139
	v_exp_f32_e32 v138, v138
	v_add_f32_e32 v136, 1.0, v136
	v_rcp_f32_e32 v140, v136
	v_mul_f32_e32 v136, 0xbfb8aa3b, v137
	v_exp_f32_e32 v139, v139
	v_exp_f32_e32 v136, v136
	v_add_f32_e32 v138, 1.0, v138
	v_rcp_f32_e32 v138, v138
	v_add_f32_e32 v139, 1.0, v139
	v_add_f32_e32 v136, 1.0, v136
	v_rcp_f32_e32 v139, v139
	v_rcp_f32_e32 v137, v136
	v_cvt_pk_bf16_f32 v136, v138, v139
	v_cvt_pk_bf16_f32 v137, v140, v137
	ds_write_b64 v32, v[136:137] offset:4352
	v_pk_add_f32 v[136:137], v[96:97], v[132:133]
	v_pk_add_f32 v[138:139], v[94:95], v[130:131]
	v_mul_f32_e32 v136, 0xbfb8aa3b, v136
	v_exp_f32_e32 v136, v136
	v_pk_add_f32 v[132:133], v[80:81], v[132:133]
	v_pk_add_f32 v[130:131], v[78:79], v[130:131]
	v_mul_f32_e32 v138, 0xbfb8aa3b, v138
	v_add_f32_e32 v136, 1.0, v136
	v_mul_f32_e32 v139, 0xbfb8aa3b, v139
	v_rcp_f32_e32 v140, v136
	v_mul_f32_e32 v136, 0xbfb8aa3b, v137
	v_mul_f32_e32 v130, 0xbfb8aa3b, v130
	v_mul_f32_e32 v131, 0xbfb8aa3b, v131
	v_mul_f32_e32 v132, 0xbfb8aa3b, v132
	v_mul_f32_e32 v133, 0xbfb8aa3b, v133
	v_exp_f32_e32 v138, v138
	v_exp_f32_e32 v139, v139
	v_exp_f32_e32 v136, v136
	v_exp_f32_e32 v130, v130
	v_exp_f32_e32 v131, v131
	v_exp_f32_e32 v132, v132
	v_exp_f32_e32 v133, v133
	v_add_f32_e32 v138, 1.0, v138
	v_add_f32_e32 v139, 1.0, v139
	v_add_f32_e32 v136, 1.0, v136
	v_add_f32_e32 v130, 1.0, v130
	v_add_f32_e32 v131, 1.0, v131
	v_add_f32_e32 v132, 1.0, v132
	v_add_f32_e32 v133, 1.0, v133
	v_rcp_f32_e32 v138, v138
	v_rcp_f32_e32 v139, v139
	v_rcp_f32_e32 v137, v136
	v_rcp_f32_e32 v130, v130
	v_rcp_f32_e32 v131, v131
	v_rcp_f32_e32 v132, v132
	v_rcp_f32_e32 v133, v133
	v_cvt_pk_bf16_f32 v136, v138, v139
	v_cvt_pk_bf16_f32 v137, v140, v137
	v_cvt_pk_bf16_f32 v130, v130, v131
	v_cvt_pk_bf16_f32 v131, v132, v133
	ds_write_b64 v32, v[136:137] offset:8704
	ds_write_b64 v32, v[130:131] offset:13056
	flat_load_dwordx4 v[130:133], v[134:135] offset:64
	s_waitcnt vmcnt(0) lgkmcnt(0)
;     __device__ __forceinline__ bf16_t* H() const { return (bf16_t*)(ws + OFF_H); }
; DEV void wst_put4(char* wsm, int row, int col, float a, float b, float c, float d) { uint2 w; w.x = pk_bf16(a, b); w.y = pk_bf16(c, d); *(uint2*)(wsm + row * WST_ROW + col * 2) = w; }
; template <int H>
; DEV void epi1_group(const Params& p, int l, bool samp, int rbase, int g64, int fq, int fr, char* wsm, const f32x4 (&acc)[4][8]) {
;     ...
;     } else if (g64 < 90) {
;         const int c0 = (g64 - 42) * 64 + cl;
;         const float* bg = p.b_gate + l * 3072 + c0;
; #pragma unroll
;         for (int ni = 0; ni < 4; ++ni) {
;             const f32x4 b4 = *(const f32x4*)(bg + ni * 16);
; #pragma unroll
;             for (int mi = 0; mi < 4; ++mi) {
;                 f32x4 v = acc[mi][H * 4 + ni] + b4;
; #pragma unroll
;                 for (int j = 0; j < 4; ++j) v[j] = __builtin_amdgcn_rcpf(1.f + __expf(-v[j]));
;                 wst_put4(wsm, mi * 16 + fr, sc + ni * 16, v[0], v[1], v[2], v[3]);
;             }
	v_pk_add_f32 v[136:137], v[124:125], v[132:133]
	s_nop 0
	v_mul_f32_e32 v136, 0xbfb8aa3b, v136
	v_exp_f32_e32 v136, v136
	v_pk_add_f32 v[138:139], v[122:123], v[130:131]
	v_add_f32_e32 v136, 1.0, v136
	v_mul_f32_e32 v138, 0xbfb8aa3b, v138
	v_mul_f32_e32 v139, 0xbfb8aa3b, v139
	v_rcp_f32_e32 v140, v136
	v_mul_f32_e32 v136, 0xbfb8aa3b, v137
	v_exp_f32_e32 v138, v138
	v_exp_f32_e32 v139, v139
	v_exp_f32_e32 v136, v136
	v_add_f32_e32 v138, 1.0, v138
	v_add_f32_e32 v139, 1.0, v139
	v_add_f32_e32 v136, 1.0, v136
	v_rcp_f32_e32 v138, v138
	v_rcp_f32_e32 v139, v139
	v_rcp_f32_e32 v137, v136
	v_cvt_pk_bf16_f32 v136, v138, v139
	v_cvt_pk_bf16_f32 v137, v140, v137
	ds_write_b64 v32, v[136:137] offset:32
	v_pk_add_f32 v[136:137], v[108:109], v[132:133]
	v_pk_add_f32 v[138:139], v[106:107], v[130:131]
	v_mul_f32_e32 v136, 0xbfb8aa3b, v136
	v_exp_f32_e32 v136, v136
	v_mul_f32_e32 v138, 0xbfb8aa3b, v138
	v_mul_f32_e32 v139, 0xbfb8aa3b, v139
	v_exp_f32_e32 v138, v138
	v_add_f32_e32 v136, 1.0, v136
	v_rcp_f32_e32 v140, v136
	v_mul_f32_e32 v136, 0xbfb8aa3b, v137
	v_exp_f32_e32 v139, v139
	v_exp_f32_e32 v136, v136
	v_add_f32_e32 v138, 1.0, v138
	v_rcp_f32_e32 v138, v138
	v_add_f32_e32 v139, 1.0, v139
	v_add_f32_e32 v136, 1.0, v136
	v_rcp_f32_e32 v139, v139
	v_rcp_f32_e32 v137, v136
	v_cvt_pk_bf16_f32 v136, v138, v139
	v_cvt_pk_bf16_f32 v137, v140, v137
	ds_write_b64 v32, v[136:137] offset:4384
	v_pk_add_f32 v[136:137], v[92:93], v[132:133]
	v_pk_add_f32 v[138:139], v[90:91], v[130:131]
	v_mul_f32_e32 v136, 0xbfb8aa3b, v136
	v_exp_f32_e32 v136, v136
	v_pk_add_f32 v[132:133], v[76:77], v[132:133]
	v_pk_add_f32 v[130:131], v[74:75], v[130:131]
	v_mul_f32_e32 v138, 0xbfb8aa3b, v138
	v_add_f32_e32 v136, 1.0, v136
	v_mul_f32_e32 v139, 0xbfb8aa3b, v139
	v_rcp_f32_e32 v140, v136
	v_mul_f32_e32 v136, 0xbfb8aa3b, v137
	v_mul_f32_e32 v130, 0xbfb8aa3b, v130
	v_mul_f32_e32 v131, 0xbfb8aa3b, v131
	v_mul_f32_e32 v132, 0xbfb8aa3b, v132
	v_mul_f32_e32 v133, 0xbfb8aa3b, v133
	v_exp_f32_e32 v138, v138
	v_exp_f32_e32 v139, v139
	v_exp_f32_e32 v136, v136
	v_exp_f32_e32 v130, v130
	v_exp_f32_e32 v131, v131
	v_exp_f32_e32 v132, v132
	v_exp_f32_e32 v133, v133
	v_add_f32_e32 v138, 1.0, v138
	v_add_f32_e32 v139, 1.0, v139
	v_add_f32_e32 v136, 1.0, v136
	v_add_f32_e32 v130, 1.0, v130
	v_add_f32_e32 v131, 1.0, v131
	v_add_f32_e32 v132, 1.0, v132
	v_add_f32_e32 v133, 1.0, v133
	v_rcp_f32_e32 v138, v138
	v_rcp_f32_e32 v139, v139
	v_rcp_f32_e32 v137, v136
	v_rcp_f32_e32 v130, v130
	v_rcp_f32_e32 v131, v131
	v_rcp_f32_e32 v132, v132
	v_rcp_f32_e32 v133, v133
	v_cvt_pk_bf16_f32 v136, v138, v139
	v_cvt_pk_bf16_f32 v137, v140, v137
	v_cvt_pk_bf16_f32 v130, v130, v131
	v_cvt_pk_bf16_f32 v131, v132, v133
	ds_write_b64 v32, v[136:137] offset:8736
	ds_write_b64 v32, v[130:131] offset:13088
	flat_load_dwordx4 v[130:133], v[134:135] offset:128
	s_waitcnt vmcnt(0) lgkmcnt(0)
;     __device__ __forceinline__ bf16_t* H() const { return (bf16_t*)(ws + OFF_H); }
; DEV void wst_put4(char* wsm, int row, int col, float a, float b, float c, float d) { uint2 w; w.x = pk_bf16(a, b); w.y = pk_bf16(c, d); *(uint2*)(wsm + row * WST_ROW + col * 2) = w; }
; template <int H>
; DEV void epi1_group(const Params& p, int l, bool samp, int rbase, int g64, int fq, int fr, char* wsm, const f32x4 (&acc)[4][8]) {
;     ...
;     } else if (g64 < 90) {
;         const int c0 = (g64 - 42) * 64 + cl;
;         const float* bg = p.b_gate + l * 3072 + c0;
; #pragma unroll
;         for (int ni = 0; ni < 4; ++ni) {
;             const f32x4 b4 = *(const f32x4*)(bg + ni * 16);
; #pragma unroll
;             for (int mi = 0; mi < 4; ++mi) {
;                 f32x4 v = acc[mi][H * 4 + ni] + b4;
; #pragma unroll
;                 for (int j = 0; j < 4; ++j) v[j] = __builtin_amdgcn_rcpf(1.f + __expf(-v[j]));
;                 wst_put4(wsm, mi * 16 + fr, sc + ni * 16, v[0], v[1], v[2], v[3]);
;             }
	v_pk_add_f32 v[136:137], v[120:121], v[132:133]
	s_nop 0
	v_mul_f32_e32 v136, 0xbfb8aa3b, v136
	v_exp_f32_e32 v136, v136
	v_pk_add_f32 v[138:139], v[118:119], v[130:131]
	v_add_f32_e32 v136, 1.0, v136
	v_mul_f32_e32 v138, 0xbfb8aa3b, v138
	v_mul_f32_e32 v139, 0xbfb8aa3b, v139
	v_rcp_f32_e32 v140, v136
	v_mul_f32_e32 v136, 0xbfb8aa3b, v137
	v_exp_f32_e32 v138, v138
	v_exp_f32_e32 v139, v139
	v_exp_f32_e32 v136, v136
	v_add_f32_e32 v138, 1.0, v138
	v_add_f32_e32 v139, 1.0, v139
	v_add_f32_e32 v136, 1.0, v136
	v_rcp_f32_e32 v138, v138
	v_rcp_f32_e32 v139, v139
	v_rcp_f32_e32 v137, v136
	v_cvt_pk_bf16_f32 v136, v138, v139
	v_cvt_pk_bf16_f32 v137, v140, v137
	ds_write_b64 v32, v[136:137] offset:64
	v_pk_add_f32 v[136:137], v[104:105], v[132:133]
	v_pk_add_f32 v[138:139], v[102:103], v[130:131]
	v_mul_f32_e32 v136, 0xbfb8aa3b, v136
	v_exp_f32_e32 v136, v136
	v_mul_f32_e32 v138, 0xbfb8aa3b, v138
	v_mul_f32_e32 v139, 0xbfb8aa3b, v139
	v_exp_f32_e32 v138, v138
	v_add_f32_e32 v136, 1.0, v136
	v_rcp_f32_e32 v140, v136
	v_mul_f32_e32 v136, 0xbfb8aa3b, v137
	v_exp_f32_e32 v139, v139
	v_exp_f32_e32 v136, v136
	v_add_f32_e32 v138, 1.0, v138
	v_rcp_f32_e32 v138, v138
	v_add_f32_e32 v139, 1.0, v139
	v_add_f32_e32 v136, 1.0, v136
	v_rcp_f32_e32 v139, v139
	v_rcp_f32_e32 v137, v136
	v_cvt_pk_bf16_f32 v136, v138, v139
	v_cvt_pk_bf16_f32 v137, v140, v137
	ds_write_b64 v32, v[136:137] offset:4416
	v_pk_add_f32 v[136:137], v[88:89], v[132:133]
	v_pk_add_f32 v[138:139], v[86:87], v[130:131]
	v_mul_f32_e32 v136, 0xbfb8aa3b, v136
	v_exp_f32_e32 v136, v136
	v_pk_add_f32 v[132:133], v[72:73], v[132:133]
	v_pk_add_f32 v[130:131], v[70:71], v[130:131]
	v_mul_f32_e32 v138, 0xbfb8aa3b, v138
	v_add_f32_e32 v136, 1.0, v136
	v_mul_f32_e32 v139, 0xbfb8aa3b, v139
	v_rcp_f32_e32 v140, v136
	v_mul_f32_e32 v136, 0xbfb8aa3b, v137
	v_mul_f32_e32 v130, 0xbfb8aa3b, v130
	v_mul_f32_e32 v131, 0xbfb8aa3b, v131
	v_mul_f32_e32 v132, 0xbfb8aa3b, v132
	v_mul_f32_e32 v133, 0xbfb8aa3b, v133
	v_exp_f32_e32 v138, v138
	v_exp_f32_e32 v139, v139
	v_exp_f32_e32 v136, v136
	v_exp_f32_e32 v130, v130
	v_exp_f32_e32 v131, v131
	v_exp_f32_e32 v132, v132
	v_exp_f32_e32 v133, v133
	v_add_f32_e32 v138, 1.0, v138
	v_add_f32_e32 v139, 1.0, v139
	v_add_f32_e32 v136, 1.0, v136
	v_add_f32_e32 v130, 1.0, v130
	v_add_f32_e32 v131, 1.0, v131
	v_add_f32_e32 v132, 1.0, v132
	v_add_f32_e32 v133, 1.0, v133
	v_rcp_f32_e32 v138, v138
	v_rcp_f32_e32 v139, v139
	v_rcp_f32_e32 v137, v136
	v_rcp_f32_e32 v130, v130
	v_rcp_f32_e32 v131, v131
	v_rcp_f32_e32 v132, v132
	v_rcp_f32_e32 v133, v133
	v_cvt_pk_bf16_f32 v136, v138, v139
	v_cvt_pk_bf16_f32 v137, v140, v137
	v_cvt_pk_bf16_f32 v130, v130, v131
	v_cvt_pk_bf16_f32 v131, v132, v133
	ds_write_b64 v32, v[136:137] offset:8768
	ds_write_b64 v32, v[130:131] offset:13120
	flat_load_dwordx4 v[130:133], v[134:135] offset:192
	s_waitcnt vmcnt(0) lgkmcnt(0)
	v_pk_add_f32 v[134:135], v[116:117], v[132:133]
	s_nop 0
	v_mul_f32_e32 v134, 0xbfb8aa3b, v134
	v_exp_f32_e32 v134, v134
	v_pk_add_f32 v[136:137], v[114:115], v[130:131]
	v_add_f32_e32 v134, 1.0, v134
	v_mul_f32_e32 v136, 0xbfb8aa3b, v136
	v_mul_f32_e32 v137, 0xbfb8aa3b, v137
	v_rcp_f32_e32 v138, v134
	v_mul_f32_e32 v134, 0xbfb8aa3b, v135
	v_exp_f32_e32 v136, v136
	v_exp_f32_e32 v137, v137
	v_exp_f32_e32 v134, v134
	v_add_f32_e32 v136, 1.0, v136
	v_add_f32_e32 v137, 1.0, v137
	v_add_f32_e32 v134, 1.0, v134
	v_rcp_f32_e32 v136, v136
	v_rcp_f32_e32 v137, v137
	v_rcp_f32_e32 v135, v134
	v_cvt_pk_bf16_f32 v134, v136, v137
	v_cvt_pk_bf16_f32 v135, v138, v135
	ds_write_b64 v32, v[134:135] offset:96
	v_pk_add_f32 v[134:135], v[100:101], v[132:133]
	v_pk_add_f32 v[136:137], v[98:99], v[130:131]
	v_mul_f32_e32 v134, 0xbfb8aa3b, v134
	v_exp_f32_e32 v134, v134
	v_mul_f32_e32 v136, 0xbfb8aa3b, v136
	v_mul_f32_e32 v137, 0xbfb8aa3b, v137
	v_exp_f32_e32 v136, v136
	v_add_f32_e32 v134, 1.0, v134
	v_rcp_f32_e32 v138, v134
	v_mul_f32_e32 v134, 0xbfb8aa3b, v135
	v_exp_f32_e32 v137, v137
	v_exp_f32_e32 v134, v134
	v_add_f32_e32 v136, 1.0, v136
	v_rcp_f32_e32 v136, v136
	v_add_f32_e32 v137, 1.0, v137
	v_add_f32_e32 v134, 1.0, v134
	v_rcp_f32_e32 v137, v137
	v_rcp_f32_e32 v135, v134
	v_cvt_pk_bf16_f32 v134, v136, v137
	v_cvt_pk_bf16_f32 v135, v138, v135
	ds_write_b64 v32, v[134:135] offset:4448
	v_pk_add_f32 v[134:135], v[84:85], v[132:133]
	v_pk_add_f32 v[136:137], v[82:83], v[130:131]
	v_mul_f32_e32 v134, 0xbfb8aa3b, v134
	v_exp_f32_e32 v134, v134
	v_pk_add_f32 v[132:133], v[68:69], v[132:133]
	v_pk_add_f32 v[130:131], v[66:67], v[130:131]
	v_mul_f32_e32 v136, 0xbfb8aa3b, v136
	v_add_f32_e32 v134, 1.0, v134
	v_mul_f32_e32 v137, 0xbfb8aa3b, v137
	v_rcp_f32_e32 v138, v134
	v_mul_f32_e32 v134, 0xbfb8aa3b, v135
	v_mul_f32_e32 v130, 0xbfb8aa3b, v130
	v_mul_f32_e32 v131, 0xbfb8aa3b, v131
	v_mul_f32_e32 v132, 0xbfb8aa3b, v132
	v_mul_f32_e32 v133, 0xbfb8aa3b, v133
	v_exp_f32_e32 v136, v136
	v_exp_f32_e32 v137, v137
	v_exp_f32_e32 v134, v134
	v_exp_f32_e32 v130, v130
	v_exp_f32_e32 v131, v131
	v_exp_f32_e32 v132, v132
	v_exp_f32_e32 v133, v133
	v_add_f32_e32 v136, 1.0, v136
	v_add_f32_e32 v137, 1.0, v137
	v_add_f32_e32 v134, 1.0, v134
	v_add_f32_e32 v130, 1.0, v130
	v_add_f32_e32 v131, 1.0, v131
	v_add_f32_e32 v132, 1.0, v132
	v_add_f32_e32 v133, 1.0, v133
	v_rcp_f32_e32 v136, v136
	v_rcp_f32_e32 v137, v137
	v_rcp_f32_e32 v135, v134
	v_rcp_f32_e32 v130, v130
	v_rcp_f32_e32 v131, v131
	v_rcp_f32_e32 v132, v132
	v_rcp_f32_e32 v133, v133
	v_cvt_pk_bf16_f32 v134, v136, v137
	v_cvt_pk_bf16_f32 v135, v138, v135
	v_cvt_pk_bf16_f32 v130, v130, v131
	v_cvt_pk_bf16_f32 v131, v132, v133
	ds_write_b64 v32, v[134:135] offset:8800
	ds_write_b64 v32, v[130:131] offset:13152
